# acc zeroing with packed moves in GU tile loops, duplicate lgkmcnt(0) before MFMA blocks removed, never-taken denormal guards around rsq removed in swiglu epilogue
# speedup vs baseline: 1.0288x; 1.0083x over previous
.LBB0_279:
	s_add_u32 s12, s10, 0xfffc0080
	s_addc_u32 s13, s11, -1
	s_add_i32 s19, 0, 0x10000
	v_add_u32_e32 v140, s19, v188
	ds_read_b128 v[120:123], v140
	ds_read_b128 v[124:127], v140 offset:1024
	ds_read_b128 v[136:139], v140 offset:2048
	ds_read_b128 v[140:143], v140 offset:3072
	s_cmp_eq_u32 s18, 12
	s_cselect_b32 s15, s0, s13
	s_cselect_b32 s14, s1, s12
	s_cselect_b32 s13, s7, s17
	s_cselect_b32 s12, s9, s16
	s_add_i32 m0, s68, 0xc000
	ds_read_b128 v[144:147], v189
	ds_read_b128 v[148:151], v189 offset:1024
	ds_read_b128 v[152:155], v189 offset:2048
	ds_read_b128 v[156:159], v189 offset:3072
	ds_read_b128 v[168:171], v189 offset:4096
	ds_read_b128 v[172:175], v189 offset:5120
	ds_read_b128 v[176:179], v189 offset:6144
	ds_read_b128 v[180:183], v189 offset:7168
	global_load_lds_dwordx4 v166, s[10:11]
	s_add_i32 m0, s68, 0xe000
	s_nop 0
	global_load_lds_dwordx4 v164, s[10:11]
	s_waitcnt lgkmcnt(8)
	s_barrier
	s_waitcnt lgkmcnt(0)
	s_setprio 1
	v_mfma_f32_16x16x32_bf16 v[132:135], v[120:123], v[144:147], v[132:135]
	v_mfma_f32_16x16x32_bf16 v[128:131], v[136:139], v[144:147], v[128:131]
	v_mfma_f32_16x16x32_bf16 v[108:111], v[120:123], v[152:155], v[108:111]
	v_mfma_f32_16x16x32_bf16 v[104:107], v[136:139], v[152:155], v[104:107]
	v_mfma_f32_16x16x32_bf16 v[92:95], v[120:123], v[168:171], v[92:95]
	v_mfma_f32_16x16x32_bf16 v[88:91], v[136:139], v[168:171], v[88:91]
	v_mfma_f32_16x16x32_bf16 v[76:79], v[120:123], v[176:179], v[76:79]
	v_mfma_f32_16x16x32_bf16 v[72:75], v[136:139], v[176:179], v[72:75]
	v_mfma_f32_16x16x32_bf16 v[132:135], v[124:127], v[148:151], v[132:135]
	v_mfma_f32_16x16x32_bf16 v[128:131], v[140:143], v[148:151], v[128:131]
	v_mfma_f32_16x16x32_bf16 v[108:111], v[124:127], v[156:159], v[108:111]
	v_mfma_f32_16x16x32_bf16 v[104:107], v[140:143], v[156:159], v[104:107]
	v_mfma_f32_16x16x32_bf16 v[92:95], v[124:127], v[172:175], v[92:95]
	v_mfma_f32_16x16x32_bf16 v[88:91], v[140:143], v[172:175], v[88:91]
	v_mfma_f32_16x16x32_bf16 v[76:79], v[124:127], v[180:183], v[76:79]
	v_mfma_f32_16x16x32_bf16 v[72:75], v[140:143], v[180:183], v[72:75]
	s_setprio 0
	s_barrier
	s_add_i32 s33, 0, 0x14000
	v_add_u32_e32 v190, s33, v188
	s_add_i32 s19, s19, s67
	ds_read_b128 v[184:187], v190
	ds_read_b128 v[198:201], v190 offset:1024
	ds_read_b128 v[206:209], v190 offset:2048
	ds_read_b128 v[210:213], v190 offset:3072
	s_mov_b32 m0, s19
	s_nop 0
	global_load_lds_dwordx4 v160, s[12:13]
	s_add_i32 m0, s19, 0x2000
	s_nop 0
	global_load_lds_dwordx4 v162, s[12:13]
	s_barrier
	s_waitcnt lgkmcnt(0)
	s_setprio 1
	v_mfma_f32_16x16x32_bf16 v[116:119], v[184:187], v[144:147], v[116:119]
	v_mfma_f32_16x16x32_bf16 v[112:115], v[206:209], v[144:147], v[112:115]
	v_mfma_f32_16x16x32_bf16 v[100:103], v[184:187], v[152:155], v[100:103]
	v_mfma_f32_16x16x32_bf16 v[96:99], v[206:209], v[152:155], v[96:99]
	v_mfma_f32_16x16x32_bf16 v[84:87], v[184:187], v[168:171], v[84:87]
	v_mfma_f32_16x16x32_bf16 v[80:83], v[206:209], v[168:171], v[80:83]
	v_mfma_f32_16x16x32_bf16 v[68:71], v[184:187], v[176:179], v[68:71]
	v_mfma_f32_16x16x32_bf16 v[64:67], v[206:209], v[176:179], v[64:67]
	v_mfma_f32_16x16x32_bf16 v[116:119], v[198:201], v[148:151], v[116:119]
	v_mfma_f32_16x16x32_bf16 v[112:115], v[210:213], v[148:151], v[112:115]
	v_mfma_f32_16x16x32_bf16 v[100:103], v[198:201], v[156:159], v[100:103]
	v_mfma_f32_16x16x32_bf16 v[96:99], v[210:213], v[156:159], v[96:99]
	v_mfma_f32_16x16x32_bf16 v[84:87], v[198:201], v[172:175], v[84:87]
	v_mfma_f32_16x16x32_bf16 v[80:83], v[210:213], v[172:175], v[80:83]
	v_mfma_f32_16x16x32_bf16 v[68:71], v[198:201], v[180:183], v[68:71]
	v_mfma_f32_16x16x32_bf16 v[64:67], v[210:213], v[180:183], v[64:67]
	s_setprio 0
	s_mov_b32 m0, s68
	s_add_u32 vcc_lo, s14, 0x80
	s_addc_u32 vcc_hi, s15, 0
	s_barrier
	ds_read_b128 v[144:147], v189 offset:16384
	ds_read_b128 v[148:151], v189 offset:17408
	ds_read_b128 v[152:155], v189 offset:18432
	ds_read_b128 v[156:159], v189 offset:19456
	ds_read_b128 v[168:171], v189 offset:20480
	ds_read_b128 v[172:175], v189 offset:21504
	ds_read_b128 v[176:179], v189 offset:22528
	ds_read_b128 v[180:183], v189 offset:23552
	global_load_lds_dwordx4 v160, s[14:15]
	s_mov_b32 m0, s69
	s_nop 0
	global_load_lds_dwordx4 v162, s[14:15]
	s_barrier
	s_waitcnt lgkmcnt(0)
	s_setprio 1
	v_mfma_f32_16x16x32_bf16 v[60:63], v[120:123], v[144:147], v[60:63]
	v_mfma_f32_16x16x32_bf16 v[56:59], v[136:139], v[144:147], v[56:59]
	v_mfma_f32_16x16x32_bf16 v[44:47], v[120:123], v[152:155], v[44:47]
	v_mfma_f32_16x16x32_bf16 v[40:43], v[136:139], v[152:155], v[40:43]
	v_mfma_f32_16x16x32_bf16 v[28:31], v[120:123], v[168:171], v[28:31]
	v_mfma_f32_16x16x32_bf16 v[24:27], v[136:139], v[168:171], v[24:27]
	v_mfma_f32_16x16x32_bf16 v[12:15], v[120:123], v[176:179], v[12:15]
	v_mfma_f32_16x16x32_bf16 v[8:11], v[136:139], v[176:179], v[8:11]
	v_mfma_f32_16x16x32_bf16 v[60:63], v[124:127], v[148:151], v[60:63]
	v_mfma_f32_16x16x32_bf16 v[56:59], v[140:143], v[148:151], v[56:59]
	v_mfma_f32_16x16x32_bf16 v[44:47], v[124:127], v[156:159], v[44:47]
	v_mfma_f32_16x16x32_bf16 v[40:43], v[140:143], v[156:159], v[40:43]
	v_mfma_f32_16x16x32_bf16 v[28:31], v[124:127], v[172:175], v[28:31]
	v_mfma_f32_16x16x32_bf16 v[24:27], v[140:143], v[172:175], v[24:27]
	v_mfma_f32_16x16x32_bf16 v[12:15], v[124:127], v[180:183], v[12:15]
	v_mfma_f32_16x16x32_bf16 v[8:11], v[140:143], v[180:183], v[8:11]
	s_setprio 0
	s_barrier
	s_add_u32 s44, s12, 0x40000
	s_addc_u32 s45, s13, 0
	s_add_i32 s19, s33, s67
	s_mov_b32 m0, s19
	s_nop 0
	global_load_lds_dwordx4 v160, s[44:45]
	s_add_i32 m0, s19, 0x2000
	s_nop 0
	global_load_lds_dwordx4 v162, s[44:45]
	s_waitcnt vmcnt(6)
	s_barrier
	s_setprio 1
	v_mfma_f32_16x16x32_bf16 v[52:55], v[184:187], v[144:147], v[52:55]
	v_mfma_f32_16x16x32_bf16 v[48:51], v[206:209], v[144:147], v[48:51]
	v_mfma_f32_16x16x32_bf16 v[36:39], v[184:187], v[152:155], v[36:39]
	v_mfma_f32_16x16x32_bf16 v[32:35], v[206:209], v[152:155], v[32:35]
	v_mfma_f32_16x16x32_bf16 v[20:23], v[184:187], v[168:171], v[20:23]
	v_mfma_f32_16x16x32_bf16 v[16:19], v[206:209], v[168:171], v[16:19]
	v_mfma_f32_16x16x32_bf16 v[4:7], v[184:187], v[176:179], v[4:7]
	v_mfma_f32_16x16x32_bf16 v[0:3], v[206:209], v[176:179], v[0:3]
	v_mfma_f32_16x16x32_bf16 v[52:55], v[198:201], v[148:151], v[52:55]
	v_mfma_f32_16x16x32_bf16 v[48:51], v[210:213], v[148:151], v[48:51]
	v_mfma_f32_16x16x32_bf16 v[36:39], v[198:201], v[156:159], v[36:39]
	v_mfma_f32_16x16x32_bf16 v[32:35], v[210:213], v[156:159], v[32:35]
	v_mfma_f32_16x16x32_bf16 v[20:23], v[198:201], v[172:175], v[20:23]
	v_mfma_f32_16x16x32_bf16 v[16:19], v[210:213], v[172:175], v[16:19]
	v_mfma_f32_16x16x32_bf16 v[4:7], v[198:201], v[180:183], v[4:7]
	v_mfma_f32_16x16x32_bf16 v[0:3], v[210:213], v[180:183], v[0:3]
	s_setprio 0
	s_add_i32 s19, 0, 0x18000
	v_add_u32_e32 v140, s19, v188
	s_barrier
	ds_read_b128 v[120:123], v140
	ds_read_b128 v[124:127], v140 offset:1024
	ds_read_b128 v[136:139], v140 offset:2048
	ds_read_b128 v[140:143], v140 offset:3072
	s_add_u32 s14, s14, 0x40000
	s_addc_u32 s15, s15, 0
	s_mov_b32 m0, s72
	ds_read_b128 v[144:147], v189 offset:32768
	ds_read_b128 v[148:151], v189 offset:33792
	ds_read_b128 v[152:155], v189 offset:34816
	ds_read_b128 v[156:159], v189 offset:35840
	ds_read_b128 v[168:171], v189 offset:36864
	ds_read_b128 v[172:175], v189 offset:37888
	ds_read_b128 v[176:179], v189 offset:38912
	ds_read_b128 v[180:183], v189 offset:39936
	global_load_lds_dwordx4 v160, s[14:15]
	s_mov_b32 m0, s73
	s_nop 0
	global_load_lds_dwordx4 v162, s[14:15]
	s_waitcnt lgkmcnt(8)
	s_barrier
	s_waitcnt lgkmcnt(0)
	s_setprio 1
	v_mfma_f32_16x16x32_bf16 v[132:135], v[120:123], v[144:147], v[132:135]
	v_mfma_f32_16x16x32_bf16 v[128:131], v[136:139], v[144:147], v[128:131]
	v_mfma_f32_16x16x32_bf16 v[108:111], v[120:123], v[152:155], v[108:111]
	v_mfma_f32_16x16x32_bf16 v[104:107], v[136:139], v[152:155], v[104:107]
	v_mfma_f32_16x16x32_bf16 v[92:95], v[120:123], v[168:171], v[92:95]
	v_mfma_f32_16x16x32_bf16 v[88:91], v[136:139], v[168:171], v[88:91]
	v_mfma_f32_16x16x32_bf16 v[76:79], v[120:123], v[176:179], v[76:79]
	v_mfma_f32_16x16x32_bf16 v[72:75], v[136:139], v[176:179], v[72:75]
	v_mfma_f32_16x16x32_bf16 v[132:135], v[124:127], v[148:151], v[132:135]
	v_mfma_f32_16x16x32_bf16 v[128:131], v[140:143], v[148:151], v[128:131]
	v_mfma_f32_16x16x32_bf16 v[108:111], v[124:127], v[156:159], v[108:111]
	v_mfma_f32_16x16x32_bf16 v[104:107], v[140:143], v[156:159], v[104:107]
	v_mfma_f32_16x16x32_bf16 v[92:95], v[124:127], v[172:175], v[92:95]
	v_mfma_f32_16x16x32_bf16 v[88:91], v[140:143], v[172:175], v[88:91]
	v_mfma_f32_16x16x32_bf16 v[76:79], v[124:127], v[180:183], v[76:79]
	v_mfma_f32_16x16x32_bf16 v[72:75], v[140:143], v[180:183], v[72:75]
	s_setprio 0
	s_barrier
	s_add_i32 s14, 0, 0x1c000
	s_add_i32 s15, s19, s67
	v_add_u32_e32 v192, s14, v188
	s_add_u32 s100, s12, 0x80
	s_addc_u32 s101, s13, 0
	s_mov_b32 m0, s15
	ds_read_b128 v[184:187], v192
	ds_read_b128 v[198:201], v192 offset:1024
	ds_read_b128 v[206:209], v192 offset:2048
	ds_read_b128 v[210:213], v192 offset:3072
	global_load_lds_dwordx4 v160, s[100:101]
	s_add_i32 m0, s15, 0x2000
	s_nop 0
	global_load_lds_dwordx4 v162, s[100:101]
	s_barrier
	s_waitcnt lgkmcnt(0)
	s_setprio 1
	v_mfma_f32_16x16x32_bf16 v[116:119], v[184:187], v[144:147], v[116:119]
	v_mfma_f32_16x16x32_bf16 v[112:115], v[206:209], v[144:147], v[112:115]
	v_mfma_f32_16x16x32_bf16 v[100:103], v[184:187], v[152:155], v[100:103]
	v_mfma_f32_16x16x32_bf16 v[96:99], v[206:209], v[152:155], v[96:99]
	v_mfma_f32_16x16x32_bf16 v[84:87], v[184:187], v[168:171], v[84:87]
	v_mfma_f32_16x16x32_bf16 v[80:83], v[206:209], v[168:171], v[80:83]
	v_mfma_f32_16x16x32_bf16 v[68:71], v[184:187], v[176:179], v[68:71]
	v_mfma_f32_16x16x32_bf16 v[64:67], v[206:209], v[176:179], v[64:67]
	v_mfma_f32_16x16x32_bf16 v[116:119], v[198:201], v[148:151], v[116:119]
	v_mfma_f32_16x16x32_bf16 v[112:115], v[210:213], v[148:151], v[112:115]
	v_mfma_f32_16x16x32_bf16 v[100:103], v[198:201], v[156:159], v[100:103]
	v_mfma_f32_16x16x32_bf16 v[96:99], v[210:213], v[156:159], v[96:99]
	v_mfma_f32_16x16x32_bf16 v[84:87], v[198:201], v[172:175], v[84:87]
	v_mfma_f32_16x16x32_bf16 v[80:83], v[210:213], v[172:175], v[80:83]
	v_mfma_f32_16x16x32_bf16 v[68:71], v[198:201], v[180:183], v[68:71]
	v_mfma_f32_16x16x32_bf16 v[64:67], v[210:213], v[180:183], v[64:67]
	s_setprio 0
	s_mov_b32 m0, s74
	s_barrier
	ds_read_b128 v[144:147], v189 offset:49152
	ds_read_b128 v[148:151], v189 offset:50176
	ds_read_b128 v[152:155], v189 offset:51200
	ds_read_b128 v[156:159], v189 offset:52224
	ds_read_b128 v[168:171], v189 offset:53248
	ds_read_b128 v[172:175], v189 offset:54272
	ds_read_b128 v[176:179], v189 offset:55296
	ds_read_b128 v[180:183], v189 offset:56320
	global_load_lds_dwordx4 v160, vcc
	s_mov_b32 m0, s75
	s_nop 0
	global_load_lds_dwordx4 v162, vcc
	s_barrier
	s_waitcnt lgkmcnt(0)
	s_setprio 1
	v_mfma_f32_16x16x32_bf16 v[60:63], v[120:123], v[144:147], v[60:63]
	v_mfma_f32_16x16x32_bf16 v[56:59], v[136:139], v[144:147], v[56:59]
	v_mfma_f32_16x16x32_bf16 v[44:47], v[120:123], v[152:155], v[44:47]
	v_mfma_f32_16x16x32_bf16 v[40:43], v[136:139], v[152:155], v[40:43]
	v_mfma_f32_16x16x32_bf16 v[28:31], v[120:123], v[168:171], v[28:31]
	v_mfma_f32_16x16x32_bf16 v[24:27], v[136:139], v[168:171], v[24:27]
	v_mfma_f32_16x16x32_bf16 v[12:15], v[120:123], v[176:179], v[12:15]
	v_mfma_f32_16x16x32_bf16 v[8:11], v[136:139], v[176:179], v[8:11]
	v_mfma_f32_16x16x32_bf16 v[60:63], v[124:127], v[148:151], v[60:63]
	v_mfma_f32_16x16x32_bf16 v[56:59], v[140:143], v[148:151], v[56:59]
	v_mfma_f32_16x16x32_bf16 v[44:47], v[124:127], v[156:159], v[44:47]
	v_mfma_f32_16x16x32_bf16 v[40:43], v[140:143], v[156:159], v[40:43]
	v_mfma_f32_16x16x32_bf16 v[28:31], v[124:127], v[172:175], v[28:31]
	v_mfma_f32_16x16x32_bf16 v[24:27], v[140:143], v[172:175], v[24:27]
	v_mfma_f32_16x16x32_bf16 v[12:15], v[124:127], v[180:183], v[12:15]
	v_mfma_f32_16x16x32_bf16 v[8:11], v[140:143], v[180:183], v[8:11]
	s_setprio 0
	s_barrier
	s_add_u32 s12, s12, 0x40080
	s_addc_u32 s13, s13, 0
	s_add_i32 s14, s14, s67
	s_mov_b32 m0, s14
	s_nop 0
	global_load_lds_dwordx4 v160, s[12:13]
	s_add_i32 m0, s14, 0x2000
	s_nop 0
	global_load_lds_dwordx4 v162, s[12:13]
	s_waitcnt vmcnt(6)
	s_barrier
	s_setprio 1
	v_mfma_f32_16x16x32_bf16 v[52:55], v[184:187], v[144:147], v[52:55]
	v_mfma_f32_16x16x32_bf16 v[48:51], v[206:209], v[144:147], v[48:51]
	v_mfma_f32_16x16x32_bf16 v[36:39], v[184:187], v[152:155], v[36:39]
	v_mfma_f32_16x16x32_bf16 v[32:35], v[206:209], v[152:155], v[32:35]
	v_mfma_f32_16x16x32_bf16 v[20:23], v[184:187], v[168:171], v[20:23]
	v_mfma_f32_16x16x32_bf16 v[16:19], v[206:209], v[168:171], v[16:19]
	v_mfma_f32_16x16x32_bf16 v[4:7], v[184:187], v[176:179], v[4:7]
	v_mfma_f32_16x16x32_bf16 v[0:3], v[206:209], v[176:179], v[0:3]
	v_mfma_f32_16x16x32_bf16 v[52:55], v[198:201], v[148:151], v[52:55]
	v_mfma_f32_16x16x32_bf16 v[48:51], v[210:213], v[148:151], v[48:51]
	v_mfma_f32_16x16x32_bf16 v[36:39], v[198:201], v[156:159], v[36:39]
	v_mfma_f32_16x16x32_bf16 v[32:35], v[210:213], v[156:159], v[32:35]
	v_mfma_f32_16x16x32_bf16 v[20:23], v[198:201], v[172:175], v[20:23]
	v_mfma_f32_16x16x32_bf16 v[16:19], v[210:213], v[172:175], v[16:19]
	v_mfma_f32_16x16x32_bf16 v[4:7], v[198:201], v[180:183], v[4:7]
	v_mfma_f32_16x16x32_bf16 v[0:3], v[210:213], v[180:183], v[0:3]
	s_setprio 0
	s_add_i32 s18, s18, 2
	s_add_u32 s16, s16, 0x100
	s_addc_u32 s17, s17, 0
	s_add_u32 s10, s10, 0x100
	s_addc_u32 s11, s11, 0
	s_cmp_gt_u32 s18, 13
	s_barrier
	s_cbranch_scc0 .LBB0_279
	v_mov_b32_e32 v120, v252
	s_lshl_b32 s0, s8, 8
	v_readfirstlane_b32 s1, v120
	s_ashr_i32 s7, s1, 2
	s_andn2_b32 s7, s7, 63
	v_and_b32_e32 v121, 15, v120
	s_add_i32 s0, s7, s0
	v_or_b32_e32 v172, s0, v121
	v_ashrrev_i32_e32 v173, 31, v172
	v_lshl_add_u64 v[174:175], v[172:173], 2, s[34:35]
	global_load_dword v171, v[174:175], off
	s_lshr_b32 s1, s1, 1
	s_and_b32 s1, s1, 0x60
	s_lshl_b32 s6, s6, 8
	s_or_b32 s1, s1, s6
	v_lshrrev_b32_e32 v120, 2, v120
	s_cmpk_eq_i32 s1, 0x100
	v_and_b32_e32 v170, 12, v120
	s_movk_i32 s6, 0x4000
	v_mov_b32_e32 v120, 0x1fcf
	s_cselect_b64 s[8:9], -1, 0
	v_lshlrev_b32_e32 v168, 1, v170
	v_cmp_gt_i32_e64 s[10:11], s6, v172
	v_bitop3_b32 v169, s0, v120, v121 bitop3:0xc8
	v_mov_b32_e32 v144, 0
	s_and_b64 vcc, exec, s[8:9]
	v_mov_b32_e32 v152, 0
	v_mov_b32_e32 v153, 0
	v_mov_b32_e32 v154, 0
	v_mov_b32_e32 v155, 0
	v_mov_b32_e32 v156, 0
	v_mov_b32_e32 v157, 0
	v_mov_b32_e32 v158, 0
	v_mov_b32_e32 v159, 0
	s_cbranch_vccz .LBB0_282
	v_or_b32_e32 v120, 16, v169
	v_add_u32_e32 v121, 0x7ffc000, v172
	v_cndmask_b32_e64 v120, v121, v120, s[10:11]
	v_lshl_or_b32 v192, v120, 5, v168
	v_lshl_add_u64 v[120:121], v[192:193], 2, s[30:31]
	global_load_dwordx4 v[152:155], v[120:121], off
	global_load_dwordx4 v[156:159], v[120:121], off offset:16

.LBB0_401:
	v_mov_b64_e32 v[0:1], 0x580
	s_ashr_i32 s9, s8, 31
	v_cmp_lt_i64_e32 vcc, s[12:13], v[0:1]
	s_lshl_b64 s[12:13], s[8:9], 19
	v_readlane_b32 s14, v254, 33
	v_readlane_b32 s15, v254, 34
	s_add_u32 s12, s14, s12
	s_addc_u32 s13, s15, s13
	s_and_b64 s[14:15], vcc, exec
	s_cselect_b32 s1, s13, s21
	s_cselect_b32 s9, s12, s20
	s_ashr_i32 s11, s10, 31
	s_lshl_b64 s[14:15], s[10:11], 19
	s_add_u32 s14, s26, s14
	s_addc_u32 s15, s27, s15
	s_and_b64 s[22:23], vcc, exec
	s_cselect_b32 s11, s15, s19
	s_cselect_b32 s33, s14, s18
	s_add_u32 s38, s18, 0x100
	s_addc_u32 s39, s19, 0
	s_add_u32 s18, s20, 0x40080
	v_mov_b32_e32 v0, 0
	s_addc_u32 s19, s21, 0
	s_mov_b32 s40, -2
	v_mov_b32_e32 v1, 0
	v_pk_mov_b32 v[2:3], v[0:1], v[0:1]
	v_pk_mov_b32 v[4:5], v[0:1], v[0:1]
	v_pk_mov_b32 v[6:7], v[0:1], v[0:1]
	v_pk_mov_b32 v[8:9], v[0:1], v[0:1]
	v_pk_mov_b32 v[10:11], v[0:1], v[0:1]
	v_pk_mov_b32 v[12:13], v[0:1], v[0:1]
	v_pk_mov_b32 v[14:15], v[0:1], v[0:1]
	v_pk_mov_b32 v[16:17], v[0:1], v[0:1]
	v_pk_mov_b32 v[18:19], v[0:1], v[0:1]
	v_pk_mov_b32 v[20:21], v[0:1], v[0:1]
	v_pk_mov_b32 v[22:23], v[0:1], v[0:1]
	v_pk_mov_b32 v[24:25], v[0:1], v[0:1]
	v_pk_mov_b32 v[26:27], v[0:1], v[0:1]
	v_pk_mov_b32 v[28:29], v[0:1], v[0:1]
	v_pk_mov_b32 v[30:31], v[0:1], v[0:1]
	v_pk_mov_b32 v[32:33], v[0:1], v[0:1]
	v_pk_mov_b32 v[34:35], v[0:1], v[0:1]
	v_pk_mov_b32 v[36:37], v[0:1], v[0:1]
	v_pk_mov_b32 v[38:39], v[0:1], v[0:1]
	v_pk_mov_b32 v[40:41], v[0:1], v[0:1]
	v_pk_mov_b32 v[42:43], v[0:1], v[0:1]
	v_pk_mov_b32 v[44:45], v[0:1], v[0:1]
	v_pk_mov_b32 v[46:47], v[0:1], v[0:1]
	v_pk_mov_b32 v[48:49], v[0:1], v[0:1]
	v_pk_mov_b32 v[50:51], v[0:1], v[0:1]
	v_pk_mov_b32 v[52:53], v[0:1], v[0:1]
	v_pk_mov_b32 v[54:55], v[0:1], v[0:1]
	v_pk_mov_b32 v[56:57], v[0:1], v[0:1]
	v_pk_mov_b32 v[58:59], v[0:1], v[0:1]
	v_pk_mov_b32 v[60:61], v[0:1], v[0:1]
	v_pk_mov_b32 v[62:63], v[0:1], v[0:1]
	v_pk_mov_b32 v[64:65], v[0:1], v[0:1]
	v_pk_mov_b32 v[66:67], v[0:1], v[0:1]
	v_pk_mov_b32 v[68:69], v[0:1], v[0:1]
	v_pk_mov_b32 v[70:71], v[0:1], v[0:1]
	v_pk_mov_b32 v[72:73], v[0:1], v[0:1]
	v_pk_mov_b32 v[74:75], v[0:1], v[0:1]
	v_pk_mov_b32 v[76:77], v[0:1], v[0:1]
	v_pk_mov_b32 v[78:79], v[0:1], v[0:1]
	v_pk_mov_b32 v[80:81], v[0:1], v[0:1]
	v_pk_mov_b32 v[82:83], v[0:1], v[0:1]
	v_pk_mov_b32 v[84:85], v[0:1], v[0:1]
	v_pk_mov_b32 v[86:87], v[0:1], v[0:1]
	v_pk_mov_b32 v[88:89], v[0:1], v[0:1]
	v_pk_mov_b32 v[90:91], v[0:1], v[0:1]
	v_pk_mov_b32 v[92:93], v[0:1], v[0:1]
	v_pk_mov_b32 v[94:95], v[0:1], v[0:1]
	v_pk_mov_b32 v[96:97], v[0:1], v[0:1]
	v_pk_mov_b32 v[98:99], v[0:1], v[0:1]
	v_pk_mov_b32 v[100:101], v[0:1], v[0:1]
	v_pk_mov_b32 v[102:103], v[0:1], v[0:1]
	v_pk_mov_b32 v[104:105], v[0:1], v[0:1]
	v_pk_mov_b32 v[106:107], v[0:1], v[0:1]
	v_pk_mov_b32 v[108:109], v[0:1], v[0:1]
	v_pk_mov_b32 v[110:111], v[0:1], v[0:1]
	v_pk_mov_b32 v[112:113], v[0:1], v[0:1]
	v_pk_mov_b32 v[114:115], v[0:1], v[0:1]
	v_pk_mov_b32 v[116:117], v[0:1], v[0:1]
	v_pk_mov_b32 v[118:119], v[0:1], v[0:1]
	v_pk_mov_b32 v[120:121], v[0:1], v[0:1]
	v_pk_mov_b32 v[122:123], v[0:1], v[0:1]
	v_pk_mov_b32 v[124:125], v[0:1], v[0:1]
	v_pk_mov_b32 v[126:127], v[0:1], v[0:1]
	s_waitcnt vmcnt(0)
	v_add_u32_e32 v218, 0x10000, v145
	v_add_u32_e32 v219, 0x14000, v145
	v_add_u32_e32 v220, 0x18000, v145
	v_add_u32_e32 v221, 0x1c000, v145
.LBB0_402:
	s_add_u32 s20, s18, 0xfffc0080
	s_addc_u32 s21, s19, -1
	s_add_i32 s41, 0, 0x10000
	ds_read_b128 v[138:141], v218
	ds_read_b128 v[148:151], v218 offset:1024
	ds_read_b128 v[152:155], v218 offset:2048
	ds_read_b128 v[156:159], v218 offset:3072
	s_cmp_eq_u32 s40, 12
	s_cselect_b32 s23, s1, s21
	s_cselect_b32 s22, s9, s20
	s_cselect_b32 s21, s11, s39
	s_cselect_b32 s20, s33, s38
	s_add_i32 m0, s17, 0xc000
	ds_read_b128 v[160:163], v146
	ds_read_b128 v[164:167], v146 offset:1024
	ds_read_b128 v[168:171], v146 offset:2048
	ds_read_b128 v[172:175], v146 offset:3072
	ds_read_b128 v[176:179], v146 offset:4096
	ds_read_b128 v[180:183], v146 offset:5120
	ds_read_b128 v[184:187], v146 offset:6144
	ds_read_b128 v[188:191], v146 offset:7168
	global_load_lds_dwordx4 v136, s[18:19]
	s_add_i32 m0, s17, 0xe000
	s_nop 0
	global_load_lds_dwordx4 v134, s[18:19]
	s_waitcnt lgkmcnt(8)
	s_barrier
	s_waitcnt lgkmcnt(0)
	s_setprio 1
	v_mfma_f32_16x16x32_bf16 v[124:127], v[138:141], v[160:163], v[124:127]
	v_mfma_f32_16x16x32_bf16 v[116:119], v[152:155], v[160:163], v[116:119]
	v_mfma_f32_16x16x32_bf16 v[108:111], v[138:141], v[168:171], v[108:111]
	v_mfma_f32_16x16x32_bf16 v[100:103], v[152:155], v[168:171], v[100:103]
	v_mfma_f32_16x16x32_bf16 v[92:95], v[138:141], v[176:179], v[92:95]
	v_mfma_f32_16x16x32_bf16 v[84:87], v[152:155], v[176:179], v[84:87]
	v_mfma_f32_16x16x32_bf16 v[76:79], v[138:141], v[184:187], v[76:79]
	v_mfma_f32_16x16x32_bf16 v[68:71], v[152:155], v[184:187], v[68:71]
	v_mfma_f32_16x16x32_bf16 v[124:127], v[148:151], v[164:167], v[124:127]
	v_mfma_f32_16x16x32_bf16 v[116:119], v[156:159], v[164:167], v[116:119]
	v_mfma_f32_16x16x32_bf16 v[108:111], v[148:151], v[172:175], v[108:111]
	v_mfma_f32_16x16x32_bf16 v[100:103], v[156:159], v[172:175], v[100:103]
	v_mfma_f32_16x16x32_bf16 v[92:95], v[148:151], v[180:183], v[92:95]
	v_mfma_f32_16x16x32_bf16 v[84:87], v[156:159], v[180:183], v[84:87]
	v_mfma_f32_16x16x32_bf16 v[76:79], v[148:151], v[188:191], v[76:79]
	v_mfma_f32_16x16x32_bf16 v[68:71], v[156:159], v[188:191], v[68:71]
	s_setprio 0
	s_barrier
	s_add_i32 s44, 0, 0x14000
	s_add_i32 s41, s41, s28
	ds_read_b128 v[198:201], v219
	ds_read_b128 v[206:209], v219 offset:1024
	ds_read_b128 v[210:213], v219 offset:2048
	ds_read_b128 v[214:217], v219 offset:3072
	s_mov_b32 m0, s41
	s_nop 0
	global_load_lds_dwordx4 v192, s[20:21]
	s_add_i32 m0, s41, 0x2000
	s_nop 0
	global_load_lds_dwordx4 v128, s[20:21]
	s_barrier
	s_waitcnt lgkmcnt(0)
	s_setprio 1
	v_mfma_f32_16x16x32_bf16 v[120:123], v[198:201], v[160:163], v[120:123]
	v_mfma_f32_16x16x32_bf16 v[112:115], v[210:213], v[160:163], v[112:115]
	v_mfma_f32_16x16x32_bf16 v[104:107], v[198:201], v[168:171], v[104:107]
	v_mfma_f32_16x16x32_bf16 v[96:99], v[210:213], v[168:171], v[96:99]
	v_mfma_f32_16x16x32_bf16 v[88:91], v[198:201], v[176:179], v[88:91]
	v_mfma_f32_16x16x32_bf16 v[80:83], v[210:213], v[176:179], v[80:83]
	v_mfma_f32_16x16x32_bf16 v[72:75], v[198:201], v[184:187], v[72:75]
	v_mfma_f32_16x16x32_bf16 v[64:67], v[210:213], v[184:187], v[64:67]
	v_mfma_f32_16x16x32_bf16 v[120:123], v[206:209], v[164:167], v[120:123]
	v_mfma_f32_16x16x32_bf16 v[112:115], v[214:217], v[164:167], v[112:115]
	v_mfma_f32_16x16x32_bf16 v[104:107], v[206:209], v[172:175], v[104:107]
	v_mfma_f32_16x16x32_bf16 v[96:99], v[214:217], v[172:175], v[96:99]
	v_mfma_f32_16x16x32_bf16 v[88:91], v[206:209], v[180:183], v[88:91]
	v_mfma_f32_16x16x32_bf16 v[80:83], v[214:217], v[180:183], v[80:83]
	v_mfma_f32_16x16x32_bf16 v[72:75], v[206:209], v[188:191], v[72:75]
	v_mfma_f32_16x16x32_bf16 v[64:67], v[214:217], v[188:191], v[64:67]
	s_setprio 0
	s_mov_b32 m0, s17
	s_add_u32 vcc_lo, s22, 0x80
	s_addc_u32 vcc_hi, s23, 0
	s_barrier
	ds_read_b128 v[160:163], v146 offset:16384
	ds_read_b128 v[164:167], v146 offset:17408
	ds_read_b128 v[168:171], v146 offset:18432
	ds_read_b128 v[172:175], v146 offset:19456
	ds_read_b128 v[176:179], v146 offset:20480
	ds_read_b128 v[180:183], v146 offset:21504
	ds_read_b128 v[184:187], v146 offset:22528
	ds_read_b128 v[188:191], v146 offset:23552
	global_load_lds_dwordx4 v132, s[22:23]
	s_mov_b32 m0, s29
	s_nop 0
	global_load_lds_dwordx4 v130, s[22:23]
	s_barrier
	s_waitcnt lgkmcnt(0)
	s_setprio 1
	v_mfma_f32_16x16x32_bf16 v[60:63], v[138:141], v[160:163], v[60:63]
	v_mfma_f32_16x16x32_bf16 v[52:55], v[152:155], v[160:163], v[52:55]
	v_mfma_f32_16x16x32_bf16 v[44:47], v[138:141], v[168:171], v[44:47]
	v_mfma_f32_16x16x32_bf16 v[36:39], v[152:155], v[168:171], v[36:39]
	v_mfma_f32_16x16x32_bf16 v[28:31], v[138:141], v[176:179], v[28:31]
	v_mfma_f32_16x16x32_bf16 v[20:23], v[152:155], v[176:179], v[20:23]
	v_mfma_f32_16x16x32_bf16 v[12:15], v[138:141], v[184:187], v[12:15]
	v_mfma_f32_16x16x32_bf16 v[4:7], v[152:155], v[184:187], v[4:7]
	v_mfma_f32_16x16x32_bf16 v[60:63], v[148:151], v[164:167], v[60:63]
	v_mfma_f32_16x16x32_bf16 v[52:55], v[156:159], v[164:167], v[52:55]
	v_mfma_f32_16x16x32_bf16 v[44:47], v[148:151], v[172:175], v[44:47]
	v_mfma_f32_16x16x32_bf16 v[36:39], v[156:159], v[172:175], v[36:39]
	v_mfma_f32_16x16x32_bf16 v[28:31], v[148:151], v[180:183], v[28:31]
	v_mfma_f32_16x16x32_bf16 v[20:23], v[156:159], v[180:183], v[20:23]
	v_mfma_f32_16x16x32_bf16 v[12:15], v[148:151], v[188:191], v[12:15]
	v_mfma_f32_16x16x32_bf16 v[4:7], v[156:159], v[188:191], v[4:7]
	s_setprio 0
	s_barrier
	s_add_u32 s42, s20, 0x40000
	s_addc_u32 s43, s21, 0
	s_add_i32 s41, s44, s28
	s_mov_b32 m0, s41
	s_nop 0
	global_load_lds_dwordx4 v192, s[42:43]
	s_add_i32 m0, s41, 0x2000
	s_nop 0
	global_load_lds_dwordx4 v128, s[42:43]
	s_waitcnt vmcnt(6)
	s_barrier
	s_setprio 1
	v_mfma_f32_16x16x32_bf16 v[56:59], v[198:201], v[160:163], v[56:59]
	v_mfma_f32_16x16x32_bf16 v[48:51], v[210:213], v[160:163], v[48:51]
	v_mfma_f32_16x16x32_bf16 v[40:43], v[198:201], v[168:171], v[40:43]
	v_mfma_f32_16x16x32_bf16 v[32:35], v[210:213], v[168:171], v[32:35]
	v_mfma_f32_16x16x32_bf16 v[24:27], v[198:201], v[176:179], v[24:27]
	v_mfma_f32_16x16x32_bf16 v[16:19], v[210:213], v[176:179], v[16:19]
	v_mfma_f32_16x16x32_bf16 v[8:11], v[198:201], v[184:187], v[8:11]
	v_mfma_f32_16x16x32_bf16 v[0:3], v[210:213], v[184:187], v[0:3]
	v_mfma_f32_16x16x32_bf16 v[56:59], v[206:209], v[164:167], v[56:59]
	v_mfma_f32_16x16x32_bf16 v[48:51], v[214:217], v[164:167], v[48:51]
	v_mfma_f32_16x16x32_bf16 v[40:43], v[206:209], v[172:175], v[40:43]
	v_mfma_f32_16x16x32_bf16 v[32:35], v[214:217], v[172:175], v[32:35]
	v_mfma_f32_16x16x32_bf16 v[24:27], v[206:209], v[180:183], v[24:27]
	v_mfma_f32_16x16x32_bf16 v[16:19], v[214:217], v[180:183], v[16:19]
	v_mfma_f32_16x16x32_bf16 v[8:11], v[206:209], v[188:191], v[8:11]
	v_mfma_f32_16x16x32_bf16 v[0:3], v[214:217], v[188:191], v[0:3]
	s_setprio 0
	s_add_i32 s41, 0, 0x18000
	s_barrier
	ds_read_b128 v[138:141], v220
	ds_read_b128 v[148:151], v220 offset:1024
	ds_read_b128 v[152:155], v220 offset:2048
	ds_read_b128 v[156:159], v220 offset:3072
	s_add_u32 s22, s22, 0x40000
	s_addc_u32 s23, s23, 0
	s_mov_b32 m0, s30
	ds_read_b128 v[160:163], v146 offset:32768
	ds_read_b128 v[164:167], v146 offset:33792
	ds_read_b128 v[168:171], v146 offset:34816
	ds_read_b128 v[172:175], v146 offset:35840
	ds_read_b128 v[176:179], v146 offset:36864
	ds_read_b128 v[180:183], v146 offset:37888
	ds_read_b128 v[184:187], v146 offset:38912
	ds_read_b128 v[188:191], v146 offset:39936
	global_load_lds_dwordx4 v132, s[22:23]
	s_mov_b32 m0, s31
	s_nop 0
	global_load_lds_dwordx4 v130, s[22:23]
	s_waitcnt lgkmcnt(8)
	s_barrier
	s_waitcnt lgkmcnt(0)
	s_setprio 1
	v_mfma_f32_16x16x32_bf16 v[124:127], v[138:141], v[160:163], v[124:127]
	v_mfma_f32_16x16x32_bf16 v[116:119], v[152:155], v[160:163], v[116:119]
	v_mfma_f32_16x16x32_bf16 v[108:111], v[138:141], v[168:171], v[108:111]
	v_mfma_f32_16x16x32_bf16 v[100:103], v[152:155], v[168:171], v[100:103]
	v_mfma_f32_16x16x32_bf16 v[92:95], v[138:141], v[176:179], v[92:95]
	v_mfma_f32_16x16x32_bf16 v[84:87], v[152:155], v[176:179], v[84:87]
	v_mfma_f32_16x16x32_bf16 v[76:79], v[138:141], v[184:187], v[76:79]
	v_mfma_f32_16x16x32_bf16 v[68:71], v[152:155], v[184:187], v[68:71]
	v_mfma_f32_16x16x32_bf16 v[124:127], v[148:151], v[164:167], v[124:127]
	v_mfma_f32_16x16x32_bf16 v[116:119], v[156:159], v[164:167], v[116:119]
	v_mfma_f32_16x16x32_bf16 v[108:111], v[148:151], v[172:175], v[108:111]
	v_mfma_f32_16x16x32_bf16 v[100:103], v[156:159], v[172:175], v[100:103]
	v_mfma_f32_16x16x32_bf16 v[92:95], v[148:151], v[180:183], v[92:95]
	v_mfma_f32_16x16x32_bf16 v[84:87], v[156:159], v[180:183], v[84:87]
	v_mfma_f32_16x16x32_bf16 v[76:79], v[148:151], v[188:191], v[76:79]
	v_mfma_f32_16x16x32_bf16 v[68:71], v[156:159], v[188:191], v[68:71]
	s_setprio 0
	s_barrier
	s_add_i32 s22, 0, 0x1c000
	s_add_i32 s23, s41, s28
	s_add_u32 s100, s20, 0x80
	s_addc_u32 s101, s21, 0
	s_mov_b32 m0, s23
	ds_read_b128 v[198:201], v221
	ds_read_b128 v[206:209], v221 offset:1024
	ds_read_b128 v[210:213], v221 offset:2048
	ds_read_b128 v[214:217], v221 offset:3072
	global_load_lds_dwordx4 v192, s[100:101]
	s_add_i32 m0, s23, 0x2000
	s_nop 0
	global_load_lds_dwordx4 v128, s[100:101]
	s_barrier
	s_waitcnt lgkmcnt(0)
	s_setprio 1
	v_mfma_f32_16x16x32_bf16 v[120:123], v[198:201], v[160:163], v[120:123]
	v_mfma_f32_16x16x32_bf16 v[112:115], v[210:213], v[160:163], v[112:115]
	v_mfma_f32_16x16x32_bf16 v[104:107], v[198:201], v[168:171], v[104:107]
	v_mfma_f32_16x16x32_bf16 v[96:99], v[210:213], v[168:171], v[96:99]
	v_mfma_f32_16x16x32_bf16 v[88:91], v[198:201], v[176:179], v[88:91]
	v_mfma_f32_16x16x32_bf16 v[80:83], v[210:213], v[176:179], v[80:83]
	v_mfma_f32_16x16x32_bf16 v[72:75], v[198:201], v[184:187], v[72:75]
	v_mfma_f32_16x16x32_bf16 v[64:67], v[210:213], v[184:187], v[64:67]
	v_mfma_f32_16x16x32_bf16 v[120:123], v[206:209], v[164:167], v[120:123]
	v_mfma_f32_16x16x32_bf16 v[112:115], v[214:217], v[164:167], v[112:115]
	v_mfma_f32_16x16x32_bf16 v[104:107], v[206:209], v[172:175], v[104:107]
	v_mfma_f32_16x16x32_bf16 v[96:99], v[214:217], v[172:175], v[96:99]
	v_mfma_f32_16x16x32_bf16 v[88:91], v[206:209], v[180:183], v[88:91]
	v_mfma_f32_16x16x32_bf16 v[80:83], v[214:217], v[180:183], v[80:83]
	v_mfma_f32_16x16x32_bf16 v[72:75], v[206:209], v[188:191], v[72:75]
	v_mfma_f32_16x16x32_bf16 v[64:67], v[214:217], v[188:191], v[64:67]
	s_setprio 0
	s_mov_b32 m0, s34
	s_barrier
	ds_read_b128 v[160:163], v146 offset:49152
	ds_read_b128 v[164:167], v146 offset:50176
	ds_read_b128 v[168:171], v146 offset:51200
	ds_read_b128 v[172:175], v146 offset:52224
	ds_read_b128 v[176:179], v146 offset:53248
	ds_read_b128 v[180:183], v146 offset:54272
	ds_read_b128 v[184:187], v146 offset:55296
	ds_read_b128 v[188:191], v146 offset:56320
	global_load_lds_dwordx4 v132, vcc
	s_mov_b32 m0, s35
	s_nop 0
	global_load_lds_dwordx4 v130, vcc
	s_barrier
	s_waitcnt lgkmcnt(0)
	s_setprio 1
	v_mfma_f32_16x16x32_bf16 v[60:63], v[138:141], v[160:163], v[60:63]
	v_mfma_f32_16x16x32_bf16 v[52:55], v[152:155], v[160:163], v[52:55]
	v_mfma_f32_16x16x32_bf16 v[44:47], v[138:141], v[168:171], v[44:47]
	v_mfma_f32_16x16x32_bf16 v[36:39], v[152:155], v[168:171], v[36:39]
	v_mfma_f32_16x16x32_bf16 v[28:31], v[138:141], v[176:179], v[28:31]
	v_mfma_f32_16x16x32_bf16 v[20:23], v[152:155], v[176:179], v[20:23]
	v_mfma_f32_16x16x32_bf16 v[12:15], v[138:141], v[184:187], v[12:15]
	v_mfma_f32_16x16x32_bf16 v[4:7], v[152:155], v[184:187], v[4:7]
	v_mfma_f32_16x16x32_bf16 v[60:63], v[148:151], v[164:167], v[60:63]
	v_mfma_f32_16x16x32_bf16 v[52:55], v[156:159], v[164:167], v[52:55]
	v_mfma_f32_16x16x32_bf16 v[44:47], v[148:151], v[172:175], v[44:47]
	v_mfma_f32_16x16x32_bf16 v[36:39], v[156:159], v[172:175], v[36:39]
	v_mfma_f32_16x16x32_bf16 v[28:31], v[148:151], v[180:183], v[28:31]
	v_mfma_f32_16x16x32_bf16 v[20:23], v[156:159], v[180:183], v[20:23]
	v_mfma_f32_16x16x32_bf16 v[12:15], v[148:151], v[188:191], v[12:15]
	v_mfma_f32_16x16x32_bf16 v[4:7], v[156:159], v[188:191], v[4:7]
	s_setprio 0
	s_barrier
	s_add_u32 s20, s20, 0x40080
	s_addc_u32 s21, s21, 0
	s_add_i32 s22, s22, s28
	s_mov_b32 m0, s22
	s_nop 0
	global_load_lds_dwordx4 v192, s[20:21]
	s_add_i32 m0, s22, 0x2000
	s_nop 0
	global_load_lds_dwordx4 v128, s[20:21]
	s_waitcnt vmcnt(6)
	s_barrier
	s_setprio 1
	v_mfma_f32_16x16x32_bf16 v[56:59], v[198:201], v[160:163], v[56:59]
	v_mfma_f32_16x16x32_bf16 v[48:51], v[210:213], v[160:163], v[48:51]
	v_mfma_f32_16x16x32_bf16 v[40:43], v[198:201], v[168:171], v[40:43]
	v_mfma_f32_16x16x32_bf16 v[32:35], v[210:213], v[168:171], v[32:35]
	v_mfma_f32_16x16x32_bf16 v[24:27], v[198:201], v[176:179], v[24:27]
	v_mfma_f32_16x16x32_bf16 v[16:19], v[210:213], v[176:179], v[16:19]
	v_mfma_f32_16x16x32_bf16 v[8:11], v[198:201], v[184:187], v[8:11]
	v_mfma_f32_16x16x32_bf16 v[0:3], v[210:213], v[184:187], v[0:3]
	v_mfma_f32_16x16x32_bf16 v[56:59], v[206:209], v[164:167], v[56:59]
	v_mfma_f32_16x16x32_bf16 v[48:51], v[214:217], v[164:167], v[48:51]
	v_mfma_f32_16x16x32_bf16 v[40:43], v[206:209], v[172:175], v[40:43]
	v_mfma_f32_16x16x32_bf16 v[32:35], v[214:217], v[172:175], v[32:35]
	v_mfma_f32_16x16x32_bf16 v[24:27], v[206:209], v[180:183], v[24:27]
	v_mfma_f32_16x16x32_bf16 v[16:19], v[214:217], v[180:183], v[16:19]
	v_mfma_f32_16x16x32_bf16 v[8:11], v[206:209], v[188:191], v[8:11]
	v_mfma_f32_16x16x32_bf16 v[0:3], v[214:217], v[188:191], v[0:3]
	s_setprio 0
	s_add_i32 s40, s40, 2
	s_add_u32 s38, s38, 0x100
	s_addc_u32 s39, s39, 0
	s_add_u32 s18, s18, 0x100
	s_addc_u32 s19, s19, 0
	s_cmp_gt_u32 s40, 13
	s_barrier
	s_cbranch_scc0 .LBB0_402
	v_mov_b32_e32 v139, v252
	s_lshl_b32 s9, s16, 8
	v_readfirstlane_b32 s1, v139
	s_ashr_i32 s11, s1, 2
	s_andn2_b32 s11, s11, 63
	s_lshr_b32 s1, s1, 1
	s_add_i32 s11, s11, s9
	s_lshl_b32 s0, s0, 7
	s_and_b32 s1, s1, 0x60
	v_and_or_b32 v138, v139, 15, s11
	s_or_b32 s0, s1, s0
	v_lshrrev_b32_e32 v139, 1, v139
	v_and_or_b32 v142, v139, 24, s0
	v_ashrrev_i32_e32 v139, 31, v138
	v_lshl_add_u64 v[140:141], v[138:139], 2, s[6:7]
	v_pk_mul_f32 v[120:121], v[124:125], v[120:121]
	v_pk_mul_f32 v[122:123], v[126:127], v[122:123]
	v_pk_mul_f32 v[112:113], v[116:117], v[112:113]
	v_pk_mul_f32 v[114:115], v[118:119], v[114:115]
	v_ashrrev_i32_e32 v143, 31, v142
	s_movk_i32 s9, 0x1600
	v_pk_mul_f32 v[104:105], v[108:109], v[104:105]
	v_pk_mul_f32 v[106:107], v[110:111], v[106:107]
	v_pk_mul_f32 v[96:97], v[100:101], v[96:97]
	v_or_b32_e32 v150, 16, v138
	v_pk_mul_f32 v[98:99], v[102:103], v[98:99]
	v_pk_mul_f32 v[88:89], v[92:93], v[88:89]
	v_pk_mul_f32 v[90:91], v[94:95], v[90:91]
	v_pk_mul_f32 v[80:81], v[84:85], v[80:81]
	v_or_b32_e32 v148, 32, v138
	v_pk_mul_f32 v[82:83], v[86:87], v[82:83]
	v_pk_mul_f32 v[72:73], v[76:77], v[72:73]
	v_pk_mul_f32 v[74:75], v[78:79], v[74:75]
	v_pk_mul_f32 v[64:65], v[68:69], v[64:65]
	v_or_b32_e32 v139, 48, v138
	v_pk_mul_f32 v[66:67], v[70:71], v[66:67]
	v_pk_mul_f32 v[56:57], v[60:61], v[56:57]
	v_pk_mul_f32 v[58:59], v[62:63], v[58:59]
	v_pk_mul_f32 v[48:49], v[52:53], v[48:49]
	v_pk_mul_f32 v[50:51], v[54:55], v[50:51]
	v_pk_mul_f32 v[40:41], v[44:45], v[40:41]
	v_pk_mul_f32 v[42:43], v[46:47], v[42:43]
	v_pk_mul_f32 v[32:33], v[36:37], v[32:33]
	v_pk_mul_f32 v[34:35], v[38:39], v[34:35]
	v_pk_mul_f32 v[24:25], v[28:29], v[24:25]
	v_pk_mul_f32 v[26:27], v[30:31], v[26:27]
	v_pk_mul_f32 v[16:17], v[20:21], v[16:17]
	v_pk_mul_f32 v[18:19], v[22:23], v[18:19]
	v_pk_mul_f32 v[8:9], v[12:13], v[8:9]
	v_pk_mul_f32 v[10:11], v[14:15], v[10:11]
	v_pk_mul_f32 v[0:1], v[4:5], v[0:1]
	v_pk_mul_f32 v[2:3], v[6:7], v[2:3]
	s_mov_b32 s16, s8
	s_mov_b64 s[18:19], s[14:15]
	s_mov_b64 s[20:21], s[12:13]
	v_fmamk_f32 v144, v231, 0x3a800000, v194
	s_nop 0
	v_rsq_f32_e32 v144, v144
	s_nop 0
	v_mul_f32_e32 v152, 0xbfb8aa3b, v144
	v_pk_mul_f32 v[156:157], v[124:125], v[152:153] op_sel_hi:[1,0]
	v_pk_mul_f32 v[154:155], v[126:127], v[152:153] op_sel_hi:[1,0]
	v_exp_f32_e32 v153, v156
	v_mul_f32_e32 v144, v144, v144
	v_add_f32_e32 v153, 1.0, v153
	v_rcp_f32_e32 v156, v153
	v_exp_f32_e32 v153, v157
	s_nop 0
	v_add_f32_e32 v153, 1.0, v153
	v_rcp_f32_e32 v157, v153
	v_exp_f32_e32 v153, v154
	v_pk_mul_f32 v[124:125], v[144:145], v[156:157] op_sel_hi:[0,1]
	v_add_f32_e32 v153, 1.0, v153
	v_rcp_f32_e32 v154, v153
	v_exp_f32_e32 v153, v155
	v_pk_mul_f32 v[120:121], v[120:121], v[124:125]
	v_add_f32_e32 v153, 1.0, v153
	v_rcp_f32_e32 v155, v153
	v_cvt_pk_bf16_f32 v124, v121, s0
	v_cvt_pk_bf16_f32 v120, v120, s0
	v_readlane_b32 s0, v254, 29
	v_pk_mul_f32 v[126:127], v[144:145], v[154:155] op_sel_hi:[0,1]
	v_pk_mul_f32 v[122:123], v[122:123], v[126:127]
	v_readlane_b32 s1, v254, 30
	v_cvt_pk_bf16_f32 v121, v122, v123
	v_lshlrev_b32_e32 v122, 16, v124
	v_pk_mul_f32 v[124:125], v[116:117], v[152:153] op_sel_hi:[1,0]
	v_or_b32_sdwa v120, v122, v120 dst_sel:DWORD dst_unused:UNUSED_PAD src0_sel:DWORD src1_sel:WORD_0
	v_pk_mul_f32 v[122:123], v[118:119], v[152:153] op_sel_hi:[1,0]
	v_exp_f32_e32 v124, v124
	v_exp_f32_e32 v125, v125
	v_exp_f32_e32 v122, v122
	v_exp_f32_e32 v123, v123
	v_add_f32_e32 v124, 1.0, v124
	v_add_f32_e32 v125, 1.0, v125
	v_rcp_f32_e32 v124, v124
	v_rcp_f32_e32 v125, v125
	v_add_f32_e32 v122, 1.0, v122
	v_add_f32_e32 v123, 1.0, v123
	v_rcp_f32_e32 v122, v122
	v_rcp_f32_e32 v123, v123
	v_pk_mul_f32 v[116:117], v[144:145], v[124:125] op_sel_hi:[0,1]
	v_pk_mul_f32 v[112:113], v[112:113], v[116:117]
	v_pk_mul_f32 v[118:119], v[144:145], v[122:123] op_sel_hi:[0,1]
	v_pk_mul_f32 v[114:115], v[114:115], v[118:119]
	v_cvt_pk_bf16_f32 v122, v112, v113
	v_mov_b64_e32 v[112:113], s[0:1]
	v_cvt_pk_bf16_f32 v123, v114, v115
	v_mad_i64_i32 v[116:117], s[0:1], v138, s9, v[112:113]
	v_lshlrev_b64 v[114:115], 1, v[142:143]
	v_lshl_add_u64 v[116:117], v[116:117], 0, v[114:115]
	global_store_dwordx4 v[116:117], v[120:123], off
	v_fmamk_f32 v116, v232, 0x3a800000, v194
	s_nop 0
	v_rsq_f32_e32 v116, v116
	s_nop 0
	v_mul_f32_e32 v118, 0xbfb8aa3b, v116
	v_pk_mul_f32 v[120:121], v[108:109], v[118:119] op_sel_hi:[1,0]
	v_pk_mul_f32 v[122:123], v[110:111], v[118:119] op_sel_hi:[1,0]
	v_exp_f32_e32 v117, v120
	v_mul_f32_e32 v116, v116, v116
	v_add_f32_e32 v117, 1.0, v117
	v_rcp_f32_e32 v120, v117
	v_exp_f32_e32 v117, v121
	s_nop 0
	v_add_f32_e32 v117, 1.0, v117
	v_rcp_f32_e32 v121, v117
	v_exp_f32_e32 v117, v122
	s_nop 0
	v_add_f32_e32 v117, 1.0, v117
	v_rcp_f32_e32 v122, v117
	v_exp_f32_e32 v117, v123
	s_nop 0
	v_add_f32_e32 v117, 1.0, v117
	v_rcp_f32_e32 v123, v117
	v_pk_mul_f32 v[108:109], v[116:117], v[120:121] op_sel_hi:[0,1]
	v_pk_mul_f32 v[104:105], v[104:105], v[108:109]
	v_pk_mul_f32 v[110:111], v[116:117], v[122:123] op_sel_hi:[0,1]
	v_pk_mul_f32 v[106:107], v[106:107], v[110:111]
	v_cvt_pk_bf16_f32 v108, v105, s0
	v_cvt_pk_bf16_f32 v104, v104, s0
	v_cvt_pk_bf16_f32 v105, v106, v107
	v_lshlrev_b32_e32 v106, 16, v108
	v_pk_mul_f32 v[108:109], v[100:101], v[118:119] op_sel_hi:[1,0]
	v_or_b32_sdwa v104, v106, v104 dst_sel:DWORD dst_unused:UNUSED_PAD src0_sel:DWORD src1_sel:WORD_0
	v_pk_mul_f32 v[106:107], v[102:103], v[118:119] op_sel_hi:[1,0]
	v_exp_f32_e32 v108, v108
	v_exp_f32_e32 v109, v109
	v_exp_f32_e32 v106, v106
	v_exp_f32_e32 v107, v107
	v_add_f32_e32 v108, 1.0, v108
	v_add_f32_e32 v109, 1.0, v109
	v_rcp_f32_e32 v108, v108
	v_rcp_f32_e32 v109, v109
	v_add_f32_e32 v106, 1.0, v106
	v_add_f32_e32 v107, 1.0, v107
	v_rcp_f32_e32 v106, v106
	v_rcp_f32_e32 v107, v107
	v_pk_mul_f32 v[100:101], v[116:117], v[108:109] op_sel_hi:[0,1]
	v_pk_mul_f32 v[96:97], v[96:97], v[100:101]
	v_pk_mul_f32 v[102:103], v[116:117], v[106:107] op_sel_hi:[0,1]
	v_pk_mul_f32 v[98:99], v[98:99], v[102:103]
	v_cvt_pk_bf16_f32 v106, v96, v97
	v_mad_i64_i32 v[96:97], s[0:1], v150, s9, v[112:113]
	v_cvt_pk_bf16_f32 v107, v98, v99
	v_lshl_add_u64 v[96:97], v[96:97], 0, v[114:115]
	global_store_dwordx4 v[96:97], v[104:107], off
	v_fmamk_f32 v96, v233, 0x3a800000, v194
	s_nop 0
	v_rsq_f32_e32 v96, v96
	s_nop 0
	v_mov_b32_e32 v97, v96
	v_mul_f32_e32 v96, 0xbfb8aa3b, v97
	v_pk_mul_f32 v[102:103], v[92:93], v[96:97] op_sel_hi:[1,0]
	v_mul_f32_e32 v98, v97, v97
	v_pk_mul_f32 v[100:101], v[94:95], v[96:97] op_sel_hi:[1,0]
	v_exp_f32_e32 v97, v102
	s_nop 0
	v_add_f32_e32 v97, 1.0, v97
	v_rcp_f32_e32 v102, v97
	v_exp_f32_e32 v97, v103
	s_nop 0
	v_add_f32_e32 v97, 1.0, v97
	v_rcp_f32_e32 v103, v97
	v_exp_f32_e32 v97, v100
	v_pk_mul_f32 v[92:93], v[98:99], v[102:103] op_sel_hi:[0,1]
	v_add_f32_e32 v97, 1.0, v97
	v_rcp_f32_e32 v100, v97
	v_exp_f32_e32 v97, v101
	v_pk_mul_f32 v[88:89], v[88:89], v[92:93]
	v_add_f32_e32 v97, 1.0, v97
	v_rcp_f32_e32 v101, v97
	v_cvt_pk_bf16_f32 v92, v89, s0
	v_cvt_pk_bf16_f32 v88, v88, s0
	v_pk_mul_f32 v[94:95], v[98:99], v[100:101] op_sel_hi:[0,1]
	v_pk_mul_f32 v[90:91], v[90:91], v[94:95]
	s_nop 0
	v_cvt_pk_bf16_f32 v89, v90, v91
	v_lshlrev_b32_e32 v90, 16, v92
	v_pk_mul_f32 v[92:93], v[84:85], v[96:97] op_sel_hi:[1,0]
	v_or_b32_sdwa v88, v90, v88 dst_sel:DWORD dst_unused:UNUSED_PAD src0_sel:DWORD src1_sel:WORD_0
	v_pk_mul_f32 v[90:91], v[86:87], v[96:97] op_sel_hi:[1,0]
	v_exp_f32_e32 v92, v92
	v_exp_f32_e32 v93, v93
	v_exp_f32_e32 v90, v90
	v_exp_f32_e32 v91, v91
	v_add_f32_e32 v92, 1.0, v92
	v_add_f32_e32 v93, 1.0, v93
	v_rcp_f32_e32 v92, v92
	v_rcp_f32_e32 v93, v93
	v_add_f32_e32 v90, 1.0, v90
	v_add_f32_e32 v91, 1.0, v91
	v_rcp_f32_e32 v90, v90
	v_rcp_f32_e32 v91, v91
	v_pk_mul_f32 v[84:85], v[98:99], v[92:93] op_sel_hi:[0,1]
	v_pk_mul_f32 v[80:81], v[80:81], v[84:85]
	v_pk_mul_f32 v[86:87], v[98:99], v[90:91] op_sel_hi:[0,1]
	v_pk_mul_f32 v[82:83], v[82:83], v[86:87]
	v_cvt_pk_bf16_f32 v90, v80, v81
	v_mad_i64_i32 v[80:81], s[0:1], v148, s9, v[112:113]
	v_cvt_pk_bf16_f32 v91, v82, v83
	v_lshl_add_u64 v[80:81], v[80:81], 0, v[114:115]
	global_store_dwordx4 v[80:81], v[88:91], off
	v_fmamk_f32 v80, v234, 0x3a800000, v194
	s_nop 0
	v_rsq_f32_e32 v80, v80
	s_nop 0
	v_mov_b32_e32 v81, v80
	v_mul_f32_e32 v80, 0xbfb8aa3b, v81
	v_pk_mul_f32 v[86:87], v[76:77], v[80:81] op_sel_hi:[1,0]
	v_mul_f32_e32 v82, v81, v81
	v_pk_mul_f32 v[84:85], v[78:79], v[80:81] op_sel_hi:[1,0]
	v_exp_f32_e32 v81, v86
	s_nop 0
	v_add_f32_e32 v81, 1.0, v81
	v_rcp_f32_e32 v86, v81
	v_exp_f32_e32 v81, v87
	s_nop 0
	v_add_f32_e32 v81, 1.0, v81
	v_rcp_f32_e32 v87, v81
	v_exp_f32_e32 v81, v84
	v_pk_mul_f32 v[76:77], v[82:83], v[86:87] op_sel_hi:[0,1]
	v_add_f32_e32 v81, 1.0, v81
	v_rcp_f32_e32 v84, v81
	v_exp_f32_e32 v81, v85
	v_pk_mul_f32 v[72:73], v[72:73], v[76:77]
	v_add_f32_e32 v81, 1.0, v81
	v_rcp_f32_e32 v85, v81
	v_cvt_pk_bf16_f32 v76, v73, s0
	v_cvt_pk_bf16_f32 v72, v72, s0
	v_pk_mul_f32 v[78:79], v[82:83], v[84:85] op_sel_hi:[0,1]
	v_pk_mul_f32 v[74:75], v[74:75], v[78:79]
	s_nop 0
	v_cvt_pk_bf16_f32 v73, v74, v75
	v_lshlrev_b32_e32 v74, 16, v76
	v_pk_mul_f32 v[76:77], v[68:69], v[80:81] op_sel_hi:[1,0]
	v_or_b32_sdwa v72, v74, v72 dst_sel:DWORD dst_unused:UNUSED_PAD src0_sel:DWORD src1_sel:WORD_0
	v_pk_mul_f32 v[74:75], v[70:71], v[80:81] op_sel_hi:[1,0]
	v_exp_f32_e32 v76, v76
	v_exp_f32_e32 v77, v77
	v_exp_f32_e32 v74, v74
	v_exp_f32_e32 v75, v75
	v_add_f32_e32 v76, 1.0, v76
	v_add_f32_e32 v77, 1.0, v77
	v_rcp_f32_e32 v76, v76
	v_rcp_f32_e32 v77, v77
	v_add_f32_e32 v74, 1.0, v74
	v_add_f32_e32 v75, 1.0, v75
	v_rcp_f32_e32 v74, v74
	v_rcp_f32_e32 v75, v75
	v_pk_mul_f32 v[68:69], v[82:83], v[76:77] op_sel_hi:[0,1]
	v_pk_mul_f32 v[64:65], v[64:65], v[68:69]
	v_add_u32_e32 v69, 0x90, v138
	v_pk_mul_f32 v[70:71], v[82:83], v[74:75] op_sel_hi:[0,1]
	v_pk_mul_f32 v[66:67], v[66:67], v[70:71]
	v_cvt_pk_bf16_f32 v74, v64, v65
	v_mad_i64_i32 v[64:65], s[0:1], v139, s9, v[112:113]
	v_cvt_pk_bf16_f32 v75, v66, v67
	v_lshl_add_u64 v[64:65], v[64:65], 0, v[114:115]
	global_store_dwordx4 v[64:65], v[72:75], off
	v_add_u32_e32 v67, 0x80, v138
	v_add_u32_e32 v66, 0xa0, v138
	v_add_u32_e32 v64, 0xb0, v138
	v_fmamk_f32 v68, v235, 0x3a800000, v194
	s_nop 0
	v_rsq_f32_e32 v68, v68
	s_nop 0
	v_mov_b32_e32 v70, v68
	v_mul_f32_e32 v68, 0xbfb8aa3b, v70
	v_pk_mul_f32 v[74:75], v[60:61], v[68:69] op_sel_hi:[1,0]
	v_pk_mul_f32 v[72:73], v[62:63], v[68:69] op_sel_hi:[1,0]
	v_exp_f32_e32 v74, v74
	v_exp_f32_e32 v75, v75
	v_exp_f32_e32 v72, v72
	v_exp_f32_e32 v73, v73
	v_add_f32_e32 v74, 1.0, v74
	v_add_f32_e32 v75, 1.0, v75
	v_rcp_f32_e32 v74, v74
	v_rcp_f32_e32 v75, v75
	v_add_f32_e32 v72, 1.0, v72
	v_add_f32_e32 v73, 1.0, v73
	v_rcp_f32_e32 v72, v72
	v_rcp_f32_e32 v73, v73
	v_mul_f32_e32 v70, v70, v70
	v_pk_mul_f32 v[60:61], v[70:71], v[74:75] op_sel_hi:[0,1]
	v_pk_mul_f32 v[56:57], v[56:57], v[60:61]
	v_pk_mul_f32 v[62:63], v[70:71], v[72:73] op_sel_hi:[0,1]
	v_pk_mul_f32 v[58:59], v[58:59], v[62:63]
	v_cvt_pk_bf16_f32 v60, v57, s0
	v_cvt_pk_bf16_f32 v56, v56, s0
	v_cvt_pk_bf16_f32 v57, v58, v59
	v_lshlrev_b32_e32 v58, 16, v60
	v_pk_mul_f32 v[60:61], v[52:53], v[68:69] op_sel_hi:[1,0]
	v_or_b32_sdwa v56, v58, v56 dst_sel:DWORD dst_unused:UNUSED_PAD src0_sel:DWORD src1_sel:WORD_0
	v_pk_mul_f32 v[58:59], v[54:55], v[68:69] op_sel_hi:[1,0]
	v_exp_f32_e32 v60, v60
	v_exp_f32_e32 v61, v61
	v_exp_f32_e32 v58, v58
	v_exp_f32_e32 v59, v59
	v_add_f32_e32 v60, 1.0, v60
	v_add_f32_e32 v61, 1.0, v61
	v_rcp_f32_e32 v60, v60
	v_rcp_f32_e32 v61, v61
	v_add_f32_e32 v58, 1.0, v58
	v_add_f32_e32 v59, 1.0, v59
	v_rcp_f32_e32 v58, v58
	v_rcp_f32_e32 v59, v59
	v_pk_mul_f32 v[52:53], v[70:71], v[60:61] op_sel_hi:[0,1]
	v_pk_mul_f32 v[48:49], v[48:49], v[52:53]
	v_pk_mul_f32 v[54:55], v[70:71], v[58:59] op_sel_hi:[0,1]
	v_pk_mul_f32 v[50:51], v[50:51], v[54:55]
	v_cvt_pk_bf16_f32 v58, v48, v49
	v_mad_i64_i32 v[48:49], s[0:1], v67, s9, v[112:113]
	v_cvt_pk_bf16_f32 v59, v50, v51
	v_lshl_add_u64 v[48:49], v[48:49], 0, v[114:115]
	global_store_dwordx4 v[48:49], v[56:59], off
	v_fmamk_f32 v48, v236, 0x3a800000, v194
	s_nop 0
	v_rsq_f32_e32 v48, v48
	s_nop 0
	v_mov_b32_e32 v49, v48
	v_mul_f32_e32 v48, 0xbfb8aa3b, v49
	v_pk_mul_f32 v[54:55], v[44:45], v[48:49] op_sel_hi:[1,0]
	v_mul_f32_e32 v50, v49, v49
	v_pk_mul_f32 v[52:53], v[46:47], v[48:49] op_sel_hi:[1,0]
	v_exp_f32_e32 v49, v54
	s_nop 0
	v_add_f32_e32 v49, 1.0, v49
	v_rcp_f32_e32 v54, v49
	v_exp_f32_e32 v49, v55
	s_nop 0
	v_add_f32_e32 v49, 1.0, v49
	v_rcp_f32_e32 v55, v49
	v_exp_f32_e32 v49, v52
	v_pk_mul_f32 v[44:45], v[50:51], v[54:55] op_sel_hi:[0,1]
	v_add_f32_e32 v49, 1.0, v49
	v_rcp_f32_e32 v52, v49
	v_exp_f32_e32 v49, v53
	v_pk_mul_f32 v[40:41], v[40:41], v[44:45]
	v_add_f32_e32 v49, 1.0, v49
	v_rcp_f32_e32 v53, v49
	v_cvt_pk_bf16_f32 v44, v41, s0
	v_cvt_pk_bf16_f32 v40, v40, s0
	v_pk_mul_f32 v[46:47], v[50:51], v[52:53] op_sel_hi:[0,1]
	v_pk_mul_f32 v[42:43], v[42:43], v[46:47]
	s_nop 0
	v_cvt_pk_bf16_f32 v41, v42, v43
	v_lshlrev_b32_e32 v42, 16, v44
	v_pk_mul_f32 v[44:45], v[36:37], v[48:49] op_sel_hi:[1,0]
	v_or_b32_sdwa v40, v42, v40 dst_sel:DWORD dst_unused:UNUSED_PAD src0_sel:DWORD src1_sel:WORD_0
	v_pk_mul_f32 v[42:43], v[38:39], v[48:49] op_sel_hi:[1,0]
	v_exp_f32_e32 v44, v44
	v_exp_f32_e32 v45, v45
	v_exp_f32_e32 v42, v42
	v_exp_f32_e32 v43, v43
	v_add_f32_e32 v44, 1.0, v44
	v_add_f32_e32 v45, 1.0, v45
	v_rcp_f32_e32 v44, v44
	v_rcp_f32_e32 v45, v45
	v_add_f32_e32 v42, 1.0, v42
	v_add_f32_e32 v43, 1.0, v43
	v_rcp_f32_e32 v42, v42
	v_rcp_f32_e32 v43, v43
	v_pk_mul_f32 v[36:37], v[50:51], v[44:45] op_sel_hi:[0,1]
	v_pk_mul_f32 v[32:33], v[32:33], v[36:37]
	v_pk_mul_f32 v[38:39], v[50:51], v[42:43] op_sel_hi:[0,1]
	v_pk_mul_f32 v[34:35], v[34:35], v[38:39]
	v_cvt_pk_bf16_f32 v42, v32, v33
	v_mad_i64_i32 v[32:33], s[0:1], v69, s9, v[112:113]
	v_cvt_pk_bf16_f32 v43, v34, v35
	v_lshl_add_u64 v[32:33], v[32:33], 0, v[114:115]
	global_store_dwordx4 v[32:33], v[40:43], off
	v_fmamk_f32 v32, v237, 0x3a800000, v194
	s_nop 0
	v_rsq_f32_e32 v32, v32
	s_nop 0
	v_mov_b32_e32 v33, v32
	v_mul_f32_e32 v32, 0xbfb8aa3b, v33
	v_pk_mul_f32 v[38:39], v[28:29], v[32:33] op_sel_hi:[1,0]
	v_mul_f32_e32 v34, v33, v33
	v_pk_mul_f32 v[36:37], v[30:31], v[32:33] op_sel_hi:[1,0]
	v_exp_f32_e32 v33, v38
	s_nop 0
	v_add_f32_e32 v33, 1.0, v33
	v_rcp_f32_e32 v38, v33
	v_exp_f32_e32 v33, v39
	s_nop 0
	v_add_f32_e32 v33, 1.0, v33
	v_rcp_f32_e32 v39, v33
	v_exp_f32_e32 v33, v36
	v_pk_mul_f32 v[28:29], v[34:35], v[38:39] op_sel_hi:[0,1]
	v_add_f32_e32 v33, 1.0, v33
	v_rcp_f32_e32 v36, v33
	v_exp_f32_e32 v33, v37
	v_pk_mul_f32 v[24:25], v[24:25], v[28:29]
	v_add_f32_e32 v33, 1.0, v33
	v_rcp_f32_e32 v37, v33
	v_cvt_pk_bf16_f32 v28, v25, s0
	v_cvt_pk_bf16_f32 v24, v24, s0
	v_pk_mul_f32 v[30:31], v[34:35], v[36:37] op_sel_hi:[0,1]
	v_pk_mul_f32 v[26:27], v[26:27], v[30:31]
	s_nop 0
	v_cvt_pk_bf16_f32 v25, v26, v27
	v_lshlrev_b32_e32 v26, 16, v28
	v_pk_mul_f32 v[28:29], v[20:21], v[32:33] op_sel_hi:[1,0]
	v_or_b32_sdwa v24, v26, v24 dst_sel:DWORD dst_unused:UNUSED_PAD src0_sel:DWORD src1_sel:WORD_0
	v_pk_mul_f32 v[26:27], v[22:23], v[32:33] op_sel_hi:[1,0]
	v_exp_f32_e32 v28, v28
	v_exp_f32_e32 v29, v29
	v_exp_f32_e32 v26, v26
	v_exp_f32_e32 v27, v27
	v_add_f32_e32 v28, 1.0, v28
	v_add_f32_e32 v29, 1.0, v29
	v_rcp_f32_e32 v28, v28
	v_rcp_f32_e32 v29, v29
	v_add_f32_e32 v26, 1.0, v26
	v_add_f32_e32 v27, 1.0, v27
	v_rcp_f32_e32 v26, v26
	v_rcp_f32_e32 v27, v27
	v_pk_mul_f32 v[20:21], v[34:35], v[28:29] op_sel_hi:[0,1]
	v_pk_mul_f32 v[16:17], v[16:17], v[20:21]
	v_pk_mul_f32 v[22:23], v[34:35], v[26:27] op_sel_hi:[0,1]
	v_pk_mul_f32 v[18:19], v[18:19], v[22:23]
	v_cvt_pk_bf16_f32 v26, v16, v17
	v_mad_i64_i32 v[16:17], s[0:1], v66, s9, v[112:113]
	v_cvt_pk_bf16_f32 v27, v18, v19
	v_lshl_add_u64 v[16:17], v[16:17], 0, v[114:115]
	global_store_dwordx4 v[16:17], v[24:27], off
	v_fmamk_f32 v16, v238, 0x3a800000, v194
	s_nop 0
	v_rsq_f32_e32 v16, v16
	s_nop 0
	v_mov_b32_e32 v17, v16
	v_mul_f32_e32 v16, 0xbfb8aa3b, v17
	v_pk_mul_f32 v[22:23], v[12:13], v[16:17] op_sel_hi:[1,0]
	v_mul_f32_e32 v18, v17, v17
	v_pk_mul_f32 v[20:21], v[14:15], v[16:17] op_sel_hi:[1,0]
	v_exp_f32_e32 v17, v22
	s_and_b64 vcc, exec, s[4:5]
	v_add_f32_e32 v17, 1.0, v17
	v_rcp_f32_e32 v22, v17
	v_exp_f32_e32 v17, v23
	s_nop 0
	v_add_f32_e32 v17, 1.0, v17
	v_rcp_f32_e32 v23, v17
	v_exp_f32_e32 v17, v20
	v_pk_mul_f32 v[12:13], v[18:19], v[22:23] op_sel_hi:[0,1]
	v_add_f32_e32 v17, 1.0, v17
	v_rcp_f32_e32 v20, v17
	v_exp_f32_e32 v17, v21
	v_pk_mul_f32 v[8:9], v[8:9], v[12:13]
	v_add_f32_e32 v17, 1.0, v17
	v_rcp_f32_e32 v21, v17
	v_cvt_pk_bf16_f32 v12, v9, s0
	v_cvt_pk_bf16_f32 v8, v8, s0
	v_pk_mul_f32 v[14:15], v[18:19], v[20:21] op_sel_hi:[0,1]
	v_pk_mul_f32 v[10:11], v[10:11], v[14:15]
	s_nop 0
	v_cvt_pk_bf16_f32 v9, v10, v11
	v_lshlrev_b32_e32 v10, 16, v12
	v_pk_mul_f32 v[12:13], v[4:5], v[16:17] op_sel_hi:[1,0]
	v_or_b32_sdwa v8, v10, v8 dst_sel:DWORD dst_unused:UNUSED_PAD src0_sel:DWORD src1_sel:WORD_0
	v_pk_mul_f32 v[10:11], v[6:7], v[16:17] op_sel_hi:[1,0]
	v_exp_f32_e32 v12, v12
	v_exp_f32_e32 v13, v13
	v_exp_f32_e32 v10, v10
	v_exp_f32_e32 v11, v11
	v_add_f32_e32 v12, 1.0, v12
	v_add_f32_e32 v13, 1.0, v13
	v_rcp_f32_e32 v12, v12
	v_rcp_f32_e32 v13, v13
	v_add_f32_e32 v10, 1.0, v10
	v_add_f32_e32 v11, 1.0, v11
	v_rcp_f32_e32 v10, v10
	v_rcp_f32_e32 v11, v11
	v_pk_mul_f32 v[4:5], v[18:19], v[12:13] op_sel_hi:[0,1]
	v_pk_mul_f32 v[0:1], v[0:1], v[4:5]
	v_pk_mul_f32 v[6:7], v[18:19], v[10:11] op_sel_hi:[0,1]
	v_pk_mul_f32 v[2:3], v[2:3], v[6:7]
	v_cvt_pk_bf16_f32 v10, v0, v1
	v_mad_i64_i32 v[0:1], s[0:1], v64, s9, v[112:113]
	v_cvt_pk_bf16_f32 v11, v2, v3
	v_lshl_add_u64 v[0:1], v[0:1], 0, v[114:115]
	s_mov_b32 s0, s10
	global_store_dwordx4 v[0:1], v[8:11], off
	s_cbranch_vccz .LBB0_399
	s_waitcnt vmcnt(0)
	s_cmpk_gt_u32 s25, 0xff
	s_cbranch_scc1 .LBB0_406
	s_barrier

.LBB0_1623:
	s_add_u32 s22, s20, 0x100
	s_addc_u32 s23, s21, 0
	s_add_i32 s46, 0, 0x10000
	ds_read_b128 v[128:131], v216
	ds_read_b128 v[132:135], v216 offset:1024
	ds_read_b128 v[136:139], v216 offset:2048
	ds_read_b128 v[140:143], v216 offset:3072
	s_cmp_eq_u32 s45, 40
	s_cselect_b32 s27, s7, s23
	s_cselect_b32 s26, s6, s22
	s_cselect_b32 s25, s9, s44
	s_cselect_b32 s24, s8, s33
	s_add_i32 m0, s34, 0xc000
	ds_read_b128 v[144:147], v198
	ds_read_b128 v[148:151], v198 offset:1024
	ds_read_b128 v[152:155], v198 offset:2048
	ds_read_b128 v[156:159], v198 offset:3072
	ds_read_b128 v[160:163], v198 offset:4096
	ds_read_b128 v[164:167], v198 offset:5120
	ds_read_b128 v[168:171], v198 offset:6144
	ds_read_b128 v[172:175], v198 offset:7168
	global_load_lds_dwordx4 v214, s[20:21]
	s_add_i32 m0, s34, 0xe000
	s_nop 0
	global_load_lds_dwordx4 v212, s[20:21]
	s_waitcnt lgkmcnt(8)
	s_barrier
	s_waitcnt lgkmcnt(0)
	s_setprio 1
	v_mfma_f32_16x16x32_bf16 v[124:127], v[128:131], v[144:147], v[124:127]
	v_mfma_f32_16x16x32_bf16 v[120:123], v[136:139], v[144:147], v[120:123]
	v_mfma_f32_16x16x32_bf16 v[108:111], v[128:131], v[152:155], v[108:111]
	v_mfma_f32_16x16x32_bf16 v[104:107], v[136:139], v[152:155], v[104:107]
	v_mfma_f32_16x16x32_bf16 v[92:95], v[128:131], v[160:163], v[92:95]
	v_mfma_f32_16x16x32_bf16 v[88:91], v[136:139], v[160:163], v[88:91]
	v_mfma_f32_16x16x32_bf16 v[76:79], v[128:131], v[168:171], v[76:79]
	v_mfma_f32_16x16x32_bf16 v[72:75], v[136:139], v[168:171], v[72:75]
	v_mfma_f32_16x16x32_bf16 v[124:127], v[132:135], v[148:151], v[124:127]
	v_mfma_f32_16x16x32_bf16 v[120:123], v[140:143], v[148:151], v[120:123]
	v_mfma_f32_16x16x32_bf16 v[108:111], v[132:135], v[156:159], v[108:111]
	v_mfma_f32_16x16x32_bf16 v[104:107], v[140:143], v[156:159], v[104:107]
	v_mfma_f32_16x16x32_bf16 v[92:95], v[132:135], v[164:167], v[92:95]
	v_mfma_f32_16x16x32_bf16 v[88:91], v[140:143], v[164:167], v[88:91]
	v_mfma_f32_16x16x32_bf16 v[76:79], v[132:135], v[172:175], v[76:79]
	v_mfma_f32_16x16x32_bf16 v[72:75], v[140:143], v[172:175], v[72:75]
	s_setprio 0
	s_barrier
	s_add_i32 s47, 0, 0x14000
	s_add_i32 s20, s46, s31
	s_mov_b32 m0, s20
	ds_read_b128 v[176:179], v217
	ds_read_b128 v[180:183], v217 offset:1024
	ds_read_b128 v[184:187], v217 offset:2048
	ds_read_b128 v[188:191], v217 offset:3072
	global_load_lds_dwordx4 v192, s[24:25]
	s_add_i32 m0, s20, 0x2000
	s_nop 0
	global_load_lds_dwordx4 v210, s[24:25]
	s_barrier
	s_waitcnt lgkmcnt(0)
	s_setprio 1
	v_mfma_f32_16x16x32_bf16 v[116:119], v[176:179], v[144:147], v[116:119]
	v_mfma_f32_16x16x32_bf16 v[112:115], v[184:187], v[144:147], v[112:115]
	v_mfma_f32_16x16x32_bf16 v[100:103], v[176:179], v[152:155], v[100:103]
	v_mfma_f32_16x16x32_bf16 v[96:99], v[184:187], v[152:155], v[96:99]
	v_mfma_f32_16x16x32_bf16 v[84:87], v[176:179], v[160:163], v[84:87]
	v_mfma_f32_16x16x32_bf16 v[80:83], v[184:187], v[160:163], v[80:83]
	v_mfma_f32_16x16x32_bf16 v[68:71], v[176:179], v[168:171], v[68:71]
	v_mfma_f32_16x16x32_bf16 v[64:67], v[184:187], v[168:171], v[64:67]
	v_mfma_f32_16x16x32_bf16 v[116:119], v[180:183], v[148:151], v[116:119]
	v_mfma_f32_16x16x32_bf16 v[112:115], v[188:191], v[148:151], v[112:115]
	v_mfma_f32_16x16x32_bf16 v[100:103], v[180:183], v[156:159], v[100:103]
	v_mfma_f32_16x16x32_bf16 v[96:99], v[188:191], v[156:159], v[96:99]
	v_mfma_f32_16x16x32_bf16 v[84:87], v[180:183], v[164:167], v[84:87]
	v_mfma_f32_16x16x32_bf16 v[80:83], v[188:191], v[164:167], v[80:83]
	v_mfma_f32_16x16x32_bf16 v[68:71], v[180:183], v[172:175], v[68:71]
	v_mfma_f32_16x16x32_bf16 v[64:67], v[188:191], v[172:175], v[64:67]
	s_setprio 0
	s_mov_b32 m0, s34
	s_add_u32 vcc_lo, s26, 0x80
	s_addc_u32 vcc_hi, s27, 0
	s_barrier
	ds_read_b128 v[144:147], v198 offset:16384
	ds_read_b128 v[148:151], v198 offset:17408
	ds_read_b128 v[152:155], v198 offset:18432
	ds_read_b128 v[156:159], v198 offset:19456
	ds_read_b128 v[160:163], v198 offset:20480
	ds_read_b128 v[164:167], v198 offset:21504
	ds_read_b128 v[168:171], v198 offset:22528
	ds_read_b128 v[172:175], v198 offset:23552
	global_load_lds_dwordx4 v206, s[26:27]
	s_mov_b32 m0, s35
	s_nop 0
	global_load_lds_dwordx4 v208, s[26:27]
	s_barrier
	s_waitcnt lgkmcnt(0)
	s_setprio 1
	v_mfma_f32_16x16x32_bf16 v[60:63], v[128:131], v[144:147], v[60:63]
	v_mfma_f32_16x16x32_bf16 v[56:59], v[136:139], v[144:147], v[56:59]
	v_mfma_f32_16x16x32_bf16 v[44:47], v[128:131], v[152:155], v[44:47]
	v_mfma_f32_16x16x32_bf16 v[40:43], v[136:139], v[152:155], v[40:43]
	v_mfma_f32_16x16x32_bf16 v[28:31], v[128:131], v[160:163], v[28:31]
	v_mfma_f32_16x16x32_bf16 v[24:27], v[136:139], v[160:163], v[24:27]
	v_mfma_f32_16x16x32_bf16 v[12:15], v[128:131], v[168:171], v[12:15]
	v_mfma_f32_16x16x32_bf16 v[8:11], v[136:139], v[168:171], v[8:11]
	v_mfma_f32_16x16x32_bf16 v[60:63], v[132:135], v[148:151], v[60:63]
	v_mfma_f32_16x16x32_bf16 v[56:59], v[140:143], v[148:151], v[56:59]
	v_mfma_f32_16x16x32_bf16 v[44:47], v[132:135], v[156:159], v[44:47]
	v_mfma_f32_16x16x32_bf16 v[40:43], v[140:143], v[156:159], v[40:43]
	v_mfma_f32_16x16x32_bf16 v[28:31], v[132:135], v[164:167], v[28:31]
	v_mfma_f32_16x16x32_bf16 v[24:27], v[140:143], v[164:167], v[24:27]
	v_mfma_f32_16x16x32_bf16 v[12:15], v[132:135], v[172:175], v[12:15]
	v_mfma_f32_16x16x32_bf16 v[8:11], v[140:143], v[172:175], v[8:11]
	s_setprio 0
	s_barrier
	s_add_u32 s20, s24, 0xb0000
	s_addc_u32 s21, s25, 0
	s_add_i32 s46, s47, s31
	s_mov_b32 m0, s46
	s_nop 0
	global_load_lds_dwordx4 v192, s[20:21]
	s_add_i32 m0, s46, 0x2000
	s_nop 0
	global_load_lds_dwordx4 v210, s[20:21]
	s_waitcnt vmcnt(6)
	s_barrier
	s_setprio 1
	v_mfma_f32_16x16x32_bf16 v[52:55], v[176:179], v[144:147], v[52:55]
	v_mfma_f32_16x16x32_bf16 v[48:51], v[184:187], v[144:147], v[48:51]
	v_mfma_f32_16x16x32_bf16 v[36:39], v[176:179], v[152:155], v[36:39]
	v_mfma_f32_16x16x32_bf16 v[32:35], v[184:187], v[152:155], v[32:35]
	v_mfma_f32_16x16x32_bf16 v[20:23], v[176:179], v[160:163], v[20:23]
	v_mfma_f32_16x16x32_bf16 v[16:19], v[184:187], v[160:163], v[16:19]
	v_mfma_f32_16x16x32_bf16 v[4:7], v[176:179], v[168:171], v[4:7]
	v_mfma_f32_16x16x32_bf16 v[0:3], v[184:187], v[168:171], v[0:3]
	v_mfma_f32_16x16x32_bf16 v[52:55], v[180:183], v[148:151], v[52:55]
	v_mfma_f32_16x16x32_bf16 v[48:51], v[188:191], v[148:151], v[48:51]
	v_mfma_f32_16x16x32_bf16 v[36:39], v[180:183], v[156:159], v[36:39]
	v_mfma_f32_16x16x32_bf16 v[32:35], v[188:191], v[156:159], v[32:35]
	v_mfma_f32_16x16x32_bf16 v[20:23], v[180:183], v[164:167], v[20:23]
	v_mfma_f32_16x16x32_bf16 v[16:19], v[188:191], v[164:167], v[16:19]
	v_mfma_f32_16x16x32_bf16 v[4:7], v[180:183], v[172:175], v[4:7]
	v_mfma_f32_16x16x32_bf16 v[0:3], v[188:191], v[172:175], v[0:3]
	s_setprio 0
	s_add_i32 s46, 0, 0x18000
	s_barrier
	ds_read_b128 v[128:131], v218
	ds_read_b128 v[132:135], v218 offset:1024
	ds_read_b128 v[136:139], v218 offset:2048
	ds_read_b128 v[140:143], v218 offset:3072
	s_add_u32 s20, s26, 0xb0000
	s_addc_u32 s21, s27, 0
	s_mov_b32 m0, s36
	ds_read_b128 v[144:147], v198 offset:32768
	ds_read_b128 v[148:151], v198 offset:33792
	ds_read_b128 v[152:155], v198 offset:34816
	ds_read_b128 v[156:159], v198 offset:35840
	ds_read_b128 v[160:163], v198 offset:36864
	ds_read_b128 v[164:167], v198 offset:37888
	ds_read_b128 v[168:171], v198 offset:38912
	ds_read_b128 v[172:175], v198 offset:39936
	global_load_lds_dwordx4 v206, s[20:21]
	s_mov_b32 m0, s37
	s_nop 0
	global_load_lds_dwordx4 v208, s[20:21]
	s_waitcnt lgkmcnt(8)
	s_barrier
	s_waitcnt lgkmcnt(0)
	s_setprio 1
	v_mfma_f32_16x16x32_bf16 v[124:127], v[128:131], v[144:147], v[124:127]
	v_mfma_f32_16x16x32_bf16 v[120:123], v[136:139], v[144:147], v[120:123]
	v_mfma_f32_16x16x32_bf16 v[108:111], v[128:131], v[152:155], v[108:111]
	v_mfma_f32_16x16x32_bf16 v[104:107], v[136:139], v[152:155], v[104:107]
	v_mfma_f32_16x16x32_bf16 v[92:95], v[128:131], v[160:163], v[92:95]
	v_mfma_f32_16x16x32_bf16 v[88:91], v[136:139], v[160:163], v[88:91]
	v_mfma_f32_16x16x32_bf16 v[76:79], v[128:131], v[168:171], v[76:79]
	v_mfma_f32_16x16x32_bf16 v[72:75], v[136:139], v[168:171], v[72:75]
	v_mfma_f32_16x16x32_bf16 v[124:127], v[132:135], v[148:151], v[124:127]
	v_mfma_f32_16x16x32_bf16 v[120:123], v[140:143], v[148:151], v[120:123]
	v_mfma_f32_16x16x32_bf16 v[108:111], v[132:135], v[156:159], v[108:111]
	v_mfma_f32_16x16x32_bf16 v[104:107], v[140:143], v[156:159], v[104:107]
	v_mfma_f32_16x16x32_bf16 v[92:95], v[132:135], v[164:167], v[92:95]
	v_mfma_f32_16x16x32_bf16 v[88:91], v[140:143], v[164:167], v[88:91]
	v_mfma_f32_16x16x32_bf16 v[76:79], v[132:135], v[172:175], v[76:79]
	v_mfma_f32_16x16x32_bf16 v[72:75], v[140:143], v[172:175], v[72:75]
	s_setprio 0
	s_barrier
	s_add_i32 s26, 0, 0x1c000
	s_add_i32 s20, s46, s31
	s_add_u32 s100, s24, 0x80
	s_addc_u32 s101, s25, 0
	s_mov_b32 m0, s20
	ds_read_b128 v[176:179], v219
	ds_read_b128 v[180:183], v219 offset:1024
	ds_read_b128 v[184:187], v219 offset:2048
	ds_read_b128 v[188:191], v219 offset:3072
	global_load_lds_dwordx4 v192, s[100:101]
	s_add_i32 m0, s20, 0x2000
	s_nop 0
	global_load_lds_dwordx4 v210, s[100:101]
	s_barrier
	s_waitcnt lgkmcnt(0)
	s_setprio 1
	v_mfma_f32_16x16x32_bf16 v[116:119], v[176:179], v[144:147], v[116:119]
	v_mfma_f32_16x16x32_bf16 v[112:115], v[184:187], v[144:147], v[112:115]
	v_mfma_f32_16x16x32_bf16 v[100:103], v[176:179], v[152:155], v[100:103]
	v_mfma_f32_16x16x32_bf16 v[96:99], v[184:187], v[152:155], v[96:99]
	v_mfma_f32_16x16x32_bf16 v[84:87], v[176:179], v[160:163], v[84:87]
	v_mfma_f32_16x16x32_bf16 v[80:83], v[184:187], v[160:163], v[80:83]
	v_mfma_f32_16x16x32_bf16 v[68:71], v[176:179], v[168:171], v[68:71]
	v_mfma_f32_16x16x32_bf16 v[64:67], v[184:187], v[168:171], v[64:67]
	v_mfma_f32_16x16x32_bf16 v[116:119], v[180:183], v[148:151], v[116:119]
	v_mfma_f32_16x16x32_bf16 v[112:115], v[188:191], v[148:151], v[112:115]
	v_mfma_f32_16x16x32_bf16 v[100:103], v[180:183], v[156:159], v[100:103]
	v_mfma_f32_16x16x32_bf16 v[96:99], v[188:191], v[156:159], v[96:99]
	v_mfma_f32_16x16x32_bf16 v[84:87], v[180:183], v[164:167], v[84:87]
	v_mfma_f32_16x16x32_bf16 v[80:83], v[188:191], v[164:167], v[80:83]
	v_mfma_f32_16x16x32_bf16 v[68:71], v[180:183], v[172:175], v[68:71]
	v_mfma_f32_16x16x32_bf16 v[64:67], v[188:191], v[172:175], v[64:67]
	s_setprio 0
	s_mov_b32 m0, s38
	s_barrier
	ds_read_b128 v[144:147], v198 offset:49152
	ds_read_b128 v[148:151], v198 offset:50176
	ds_read_b128 v[152:155], v198 offset:51200
	ds_read_b128 v[156:159], v198 offset:52224
	ds_read_b128 v[160:163], v198 offset:53248
	ds_read_b128 v[164:167], v198 offset:54272
	ds_read_b128 v[168:171], v198 offset:55296
	ds_read_b128 v[172:175], v198 offset:56320
	global_load_lds_dwordx4 v206, vcc
	s_mov_b32 m0, s39
	s_nop 0
	global_load_lds_dwordx4 v208, vcc
	s_barrier
	s_waitcnt lgkmcnt(0)
	s_setprio 1
	v_mfma_f32_16x16x32_bf16 v[60:63], v[128:131], v[144:147], v[60:63]
	v_mfma_f32_16x16x32_bf16 v[56:59], v[136:139], v[144:147], v[56:59]
	v_mfma_f32_16x16x32_bf16 v[44:47], v[128:131], v[152:155], v[44:47]
	v_mfma_f32_16x16x32_bf16 v[40:43], v[136:139], v[152:155], v[40:43]
	v_mfma_f32_16x16x32_bf16 v[28:31], v[128:131], v[160:163], v[28:31]
	v_mfma_f32_16x16x32_bf16 v[24:27], v[136:139], v[160:163], v[24:27]
	v_mfma_f32_16x16x32_bf16 v[12:15], v[128:131], v[168:171], v[12:15]
	v_mfma_f32_16x16x32_bf16 v[8:11], v[136:139], v[168:171], v[8:11]
	v_mfma_f32_16x16x32_bf16 v[60:63], v[132:135], v[148:151], v[60:63]
	v_mfma_f32_16x16x32_bf16 v[56:59], v[140:143], v[148:151], v[56:59]
	v_mfma_f32_16x16x32_bf16 v[44:47], v[132:135], v[156:159], v[44:47]
	v_mfma_f32_16x16x32_bf16 v[40:43], v[140:143], v[156:159], v[40:43]
	v_mfma_f32_16x16x32_bf16 v[28:31], v[132:135], v[164:167], v[28:31]
	v_mfma_f32_16x16x32_bf16 v[24:27], v[140:143], v[164:167], v[24:27]
	v_mfma_f32_16x16x32_bf16 v[12:15], v[132:135], v[172:175], v[12:15]
	v_mfma_f32_16x16x32_bf16 v[8:11], v[140:143], v[172:175], v[8:11]
	s_setprio 0
	s_barrier
	s_add_u32 s20, s24, 0xb0080
	s_addc_u32 s21, s25, 0
	s_add_i32 s24, s26, s31
	s_mov_b32 m0, s24
	s_nop 0
	global_load_lds_dwordx4 v192, s[20:21]
	s_add_i32 m0, s24, 0x2000
	s_nop 0
	global_load_lds_dwordx4 v210, s[20:21]
	s_waitcnt vmcnt(6)
	s_barrier
	s_setprio 1
	v_mfma_f32_16x16x32_bf16 v[52:55], v[176:179], v[144:147], v[52:55]
	v_mfma_f32_16x16x32_bf16 v[48:51], v[184:187], v[144:147], v[48:51]
	v_mfma_f32_16x16x32_bf16 v[36:39], v[176:179], v[152:155], v[36:39]
	v_mfma_f32_16x16x32_bf16 v[32:35], v[184:187], v[152:155], v[32:35]
	v_mfma_f32_16x16x32_bf16 v[20:23], v[176:179], v[160:163], v[20:23]
	v_mfma_f32_16x16x32_bf16 v[16:19], v[184:187], v[160:163], v[16:19]
	v_mfma_f32_16x16x32_bf16 v[4:7], v[176:179], v[168:171], v[4:7]
	v_mfma_f32_16x16x32_bf16 v[0:3], v[184:187], v[168:171], v[0:3]
	v_mfma_f32_16x16x32_bf16 v[52:55], v[180:183], v[148:151], v[52:55]
	v_mfma_f32_16x16x32_bf16 v[48:51], v[188:191], v[148:151], v[48:51]
	v_mfma_f32_16x16x32_bf16 v[36:39], v[180:183], v[156:159], v[36:39]
	v_mfma_f32_16x16x32_bf16 v[32:35], v[188:191], v[156:159], v[32:35]
	v_mfma_f32_16x16x32_bf16 v[20:23], v[180:183], v[164:167], v[20:23]
	v_mfma_f32_16x16x32_bf16 v[16:19], v[188:191], v[164:167], v[16:19]
	v_mfma_f32_16x16x32_bf16 v[4:7], v[180:183], v[172:175], v[4:7]
	v_mfma_f32_16x16x32_bf16 v[0:3], v[188:191], v[172:175], v[0:3]
	s_setprio 0
	s_add_i32 s45, s45, 2
	s_add_u32 s33, s33, 0x100
	s_addc_u32 s44, s44, 0
	s_cmp_gt_u32 s45, 41
	s_mov_b64 s[20:21], s[22:23]
	s_barrier
	s_cbranch_scc0 .LBB0_1623
	v_mov_b32_e32 v128, v252
	s_lshl_b32 s1, s1, 8
	v_readfirstlane_b32 s20, v128
	s_ashr_i32 s21, s20, 2
	s_andn2_b32 s21, s21, 63
	s_add_i32 s21, s21, s1
	s_lshr_b32 s1, s20, 1
	s_and_b32 s1, s1, 0x60
	s_lshl_b32 s0, s0, 8
	v_and_or_b32 v244, v128, 15, s21
	v_lshrrev_b32_e32 v128, 1, v128
	s_or_b32 s0, s1, s0
	v_and_b32_e32 v129, 64, v195
	v_and_or_b32 v216, v128, 24, s0
	v_xor_b32_e32 v128, 16, v195
	v_add_u32_e32 v129, 64, v129
	v_cmp_lt_i32_e32 vcc, v128, v129
	v_ashrrev_i32_e32 v245, 31, v244
	v_lshlrev_b64 v[220:221], 10, v[244:245]
	v_cndmask_b32_e32 v128, v195, v128, vcc
	v_lshlrev_b32_e32 v200, 2, v128
	v_xor_b32_e32 v128, 32, v195
	v_cmp_lt_i32_e32 vcc, v128, v129
	v_ashrrev_i32_e32 v217, 31, v216
	v_or_b32_e32 v218, 0x80, v216
	v_cndmask_b32_e32 v128, v195, v128, vcc
	v_lshlrev_b32_e32 v199, 2, v128
	v_lshl_add_u64 v[128:129], v[220:221], 0, v[216:217]
	v_lshlrev_b64 v[128:129], 1, v[128:129]
	v_lshl_add_u64 v[240:241], s[18:19], 0, v[128:129]
	v_lshl_add_u64 v[246:247], s[10:11], 0, v[128:129]
	global_load_dwordx4 v[188:191], v[240:241], off
	global_load_dwordx4 v[180:183], v[240:241], off offset:256
	global_load_dwordx4 v[184:187], v[246:247], off
	v_ashrrev_i32_e32 v219, 31, v218
	v_lshl_add_u64 v[128:129], v[220:221], 0, v[218:219]
	v_lshl_add_u64 v[242:243], v[128:129], 1, s[10:11]
	v_or_b32_e32 v128, 16, v244
	v_ashrrev_i32_e32 v129, 31, v128
	v_lshlrev_b64 v[128:129], 10, v[128:129]
	v_lshl_add_u64 v[130:131], v[128:129], 0, v[216:217]
	v_lshl_add_u64 v[128:129], v[128:129], 0, v[218:219]
	v_lshl_add_u64 v[236:237], v[128:129], 1, s[10:11]
	v_or_b32_e32 v128, 32, v244
	v_ashrrev_i32_e32 v129, 31, v128
	v_lshlrev_b64 v[130:131], 1, v[130:131]
	v_lshlrev_b64 v[128:129], 10, v[128:129]
	v_lshl_add_u64 v[234:235], s[18:19], 0, v[130:131]
	v_lshl_add_u64 v[238:239], s[10:11], 0, v[130:131]
	v_lshl_add_u64 v[130:131], v[128:129], 0, v[216:217]
	v_lshl_add_u64 v[128:129], v[128:129], 0, v[218:219]
	v_lshl_add_u64 v[230:231], v[128:129], 1, s[10:11]
	v_or_b32_e32 v128, 48, v244
	v_ashrrev_i32_e32 v129, 31, v128
	v_lshlrev_b64 v[130:131], 1, v[130:131]
	v_lshlrev_b64 v[128:129], 10, v[128:129]
	v_lshl_add_u64 v[226:227], s[18:19], 0, v[130:131]
	v_lshl_add_u64 v[232:233], s[10:11], 0, v[130:131]
	v_lshl_add_u64 v[130:131], v[128:129], 0, v[216:217]
	v_lshlrev_b64 v[130:131], 1, v[130:131]
	v_lshl_add_u64 v[132:133], v[128:129], 0, v[218:219]
	v_lshl_add_u64 v[222:223], s[18:19], 0, v[130:131]
	v_lshl_add_u64 v[228:229], s[10:11], 0, v[130:131]
	v_lshl_add_u64 v[224:225], v[132:133], 1, s[10:11]
	global_load_dwordx4 v[176:179], v[242:243], off
	global_load_dwordx4 v[172:175], v[234:235], off
	global_load_dwordx4 v[164:167], v[234:235], off offset:256
	global_load_dwordx4 v[168:171], v[238:239], off
	global_load_dwordx4 v[160:163], v[236:237], off
	global_load_dwordx4 v[156:159], v[226:227], off
	global_load_dwordx4 v[132:135], v[224:225], off
	global_load_dwordx4 v[152:155], v[232:233], off
	global_load_dwordx4 v[144:147], v[230:231], off
	global_load_dwordx4 v[148:151], v[226:227], off offset:256
	global_load_dwordx4 v[136:139], v[228:229], off
	global_load_dwordx4 v[140:143], v[222:223], off
	global_load_dwordx4 v[128:131], v[222:223], off offset:256
	v_cmp_gt_u32_e32 vcc, 16, v195
	s_waitcnt vmcnt(0)
	v_lshlrev_b32_e32 v248, 16, v188
	v_and_b32_e32 v249, 0xffff0000, v188
	v_lshlrev_b32_e32 v250, 16, v184
	v_and_b32_e32 v251, 0xffff0000, v184
	v_lshlrev_b32_e32 v188, 16, v189
	v_and_b32_e32 v189, 0xffff0000, v189
	v_lshlrev_b32_e32 v184, 16, v185
	v_and_b32_e32 v185, 0xffff0000, v185
	v_pk_add_f32 v[248:249], v[248:249], v[250:251]
	v_pk_add_f32 v[184:185], v[188:189], v[184:185]
	v_pk_fma_f32 v[188:189], v[124:125], 0.5, v[248:249] op_sel_hi:[1,0,1]
	v_pk_fma_f32 v[184:185], v[126:127], 0.5, v[184:185] op_sel_hi:[1,0,1]
	v_lshlrev_b32_e32 v124, 16, v190
	v_and_b32_e32 v125, 0xffff0000, v190
	v_lshlrev_b32_e32 v126, 16, v186
	v_and_b32_e32 v127, 0xffff0000, v186
	v_pk_add_f32 v[124:125], v[124:125], v[126:127]
	v_lshlrev_b32_e32 v126, 16, v191
	v_and_b32_e32 v127, 0xffff0000, v191
	v_lshlrev_b32_e32 v186, 16, v187
	v_and_b32_e32 v187, 0xffff0000, v187
	v_pk_add_f32 v[126:127], v[126:127], v[186:187]
	v_pk_fma_f32 v[190:191], v[120:121], 0.5, v[124:125] op_sel_hi:[1,0,1]
	v_cvt_pk_bf16_f32 v120, v188, v189
	v_pk_fma_f32 v[186:187], v[122:123], 0.5, v[126:127] op_sel_hi:[1,0,1]
	v_and_b32_e32 v123, 0xffff0000, v120
	v_lshlrev_b32_e32 v122, 16, v120
	v_pk_add_f32 v[122:123], v[188:189], v[122:123] neg_lo:[0,1] neg_hi:[0,1]
	v_cvt_pk_bf16_f32 v121, v184, v185
	v_cvt_pk_bf16_f32 v124, v122, v123
	v_and_b32_e32 v123, 0xffff0000, v121
	v_lshlrev_b32_e32 v122, 16, v121
	v_pk_add_f32 v[122:123], v[184:185], v[122:123] neg_lo:[0,1] neg_hi:[0,1]
	s_nop 0
	v_cvt_pk_bf16_f32 v125, v122, v123
	v_cvt_pk_bf16_f32 v122, v190, v191
	v_cvt_pk_bf16_f32 v123, v186, v187
	v_and_b32_e32 v127, 0xffff0000, v122
	v_lshlrev_b32_e32 v126, 16, v122
	v_and_b32_e32 v249, 0xffff0000, v123
	v_lshlrev_b32_e32 v248, 16, v123
	v_pk_add_f32 v[126:127], v[190:191], v[126:127] neg_lo:[0,1] neg_hi:[0,1]
	v_pk_add_f32 v[248:249], v[186:187], v[248:249] neg_lo:[0,1] neg_hi:[0,1]
	v_cvt_pk_bf16_f32 v126, v126, v127
	v_cvt_pk_bf16_f32 v127, v248, v249
	global_store_dwordx4 v[240:241], v[120:123], off
	global_store_dwordx4 v[246:247], v[124:127], off
	s_nop 0
	v_pk_mul_f32 v[122:123], v[190:191], v[190:191]
	v_pk_mul_f32 v[120:121], v[186:187], v[186:187]
	v_pk_fma_f32 v[122:123], v[188:189], v[188:189], v[122:123]
	v_pk_fma_f32 v[120:121], v[184:185], v[184:185], v[120:121]
	v_add_f32_e32 v122, v122, v123
	v_add_f32_e32 v120, v120, v122
	v_add_f32_e32 v120, v121, v120
	ds_bpermute_b32 v121, v200, v120
	v_lshl_add_u64 v[184:185], v[244:245], 2, s[14:15]
	s_waitcnt lgkmcnt(0)
	v_add_f32_e32 v120, v120, v121
	ds_bpermute_b32 v121, v199, v120
	s_and_saveexec_b64 s[20:21], vcc
	s_cbranch_execz .LBB0_1626
	s_waitcnt lgkmcnt(0)
	v_add_f32_e32 v120, v120, v121
	global_atomic_add_f32 v[184:185], v120, off

.LBB0_1681:
	s_add_u32 s31, s12, s42
	s_addc_u32 s33, s13, s43
	s_add_u32 s35, s31, 0x100
	s_addc_u32 s46, s33, 0
	s_and_b64 s[44:45], s[40:41], exec
	s_cselect_b32 s47, s0, s46
	s_cselect_b32 s46, s1, s35
	s_add_u32 s35, s10, s42
	s_addc_u32 s42, s11, s43
	s_add_u32 s35, s35, 0x100
	s_addc_u32 s42, s42, 0
	s_add_i32 s72, 0, 0x10000
	s_and_b64 s[40:41], s[40:41], exec
	s_cselect_b32 s49, s7, s42
	s_cselect_b32 s48, s9, s35
	s_add_u32 s50, s31, 0x10080
	s_addc_u32 s51, s33, 0
	s_add_i32 s82, s72, s58
	s_add_i32 m0, s59, 0xc000
	s_add_i32 s83, s59, 0xe000
	s_add_i32 s75, 0, 0x14000
	s_add_i32 s74, s82, 0x2000
	s_add_u32 s44, s48, 0x10000
	v_add_u32_e32 v148, s72, v150
	s_addc_u32 s45, s49, 0
	s_add_i32 s69, s75, s58
	ds_read_b128 v[136:139], v148
	ds_read_b128 v[140:143], v148 offset:1024
	ds_read_b128 v[144:147], v148 offset:2048
	ds_read_b128 v[152:155], v148 offset:3072
	s_add_i32 s68, s69, 0x2000
	s_add_i32 s67, 0, 0x18000
	s_add_u32 s42, s46, 0x10000
	s_addc_u32 s43, s47, 0
	s_add_i32 s35, s67, s58
	s_add_i32 s33, 0, 0x1c000
	s_add_i32 s31, s35, 0x2000
	s_add_u32 s40, s48, 0x10080
	s_addc_u32 s41, s49, 0
	s_add_i32 s73, s33, s58
	s_add_i32 s72, s73, 0x2000
	v_lshl_add_u64 v[148:149], s[50:51], 0, v[128:129]
	ds_read_b128 v[156:159], v151
	ds_read_b128 v[160:163], v151 offset:1024
	ds_read_b128 v[164:167], v151 offset:2048
	ds_read_b128 v[168:171], v151 offset:3072
	ds_read_b128 v[172:175], v151 offset:4096
	ds_read_b128 v[176:179], v151 offset:5120
	ds_read_b128 v[180:183], v151 offset:6144
	ds_read_b128 v[184:187], v151 offset:7168
	global_load_lds_dwordx4 v[148:149], off
	v_lshl_add_u64 v[148:149], s[50:51], 0, v[132:133]
	s_mov_b32 m0, s83
	s_nop 0
	global_load_lds_dwordx4 v[148:149], off
	s_waitcnt lgkmcnt(8)
	s_barrier
	s_waitcnt lgkmcnt(0)
	s_setprio 1
	v_mfma_f32_16x16x32_bf16 v[124:127], v[136:139], v[156:159], v[124:127]
	v_mfma_f32_16x16x32_bf16 v[120:123], v[144:147], v[156:159], v[120:123]
	v_mfma_f32_16x16x32_bf16 v[108:111], v[136:139], v[164:167], v[108:111]
	v_mfma_f32_16x16x32_bf16 v[104:107], v[144:147], v[164:167], v[104:107]
	v_mfma_f32_16x16x32_bf16 v[92:95], v[136:139], v[172:175], v[92:95]
	v_mfma_f32_16x16x32_bf16 v[88:91], v[144:147], v[172:175], v[88:91]
	v_mfma_f32_16x16x32_bf16 v[76:79], v[136:139], v[180:183], v[76:79]
	v_mfma_f32_16x16x32_bf16 v[72:75], v[144:147], v[180:183], v[72:75]
	v_mfma_f32_16x16x32_bf16 v[124:127], v[140:143], v[160:163], v[124:127]
	v_mfma_f32_16x16x32_bf16 v[120:123], v[152:155], v[160:163], v[120:123]
	v_mfma_f32_16x16x32_bf16 v[108:111], v[140:143], v[168:171], v[108:111]
	v_mfma_f32_16x16x32_bf16 v[104:107], v[152:155], v[168:171], v[104:107]
	v_mfma_f32_16x16x32_bf16 v[92:95], v[140:143], v[176:179], v[92:95]
	v_mfma_f32_16x16x32_bf16 v[88:91], v[152:155], v[176:179], v[88:91]
	v_mfma_f32_16x16x32_bf16 v[76:79], v[140:143], v[184:187], v[76:79]
	v_mfma_f32_16x16x32_bf16 v[72:75], v[152:155], v[184:187], v[72:75]
	s_setprio 0
	s_barrier
	v_add_u32_e32 v148, s75, v150
	s_mov_b32 m0, s82
	ds_read_b128 v[188:191], v148
	ds_read_b128 v[198:201], v148 offset:1024
	ds_read_b128 v[206:209], v148 offset:2048
	ds_read_b128 v[210:213], v148 offset:3072
	v_lshl_add_u64 v[148:149], s[48:49], 0, v[130:131]
	global_load_lds_dwordx4 v[148:149], off
	v_lshl_add_u64 v[214:215], s[48:49], 0, v[134:135]
	s_mov_b32 m0, s74
	s_nop 0
	global_load_lds_dwordx4 v[214:215], off
	s_barrier
	s_waitcnt lgkmcnt(0)
	s_setprio 1
	v_mfma_f32_16x16x32_bf16 v[116:119], v[188:191], v[156:159], v[116:119]
	v_mfma_f32_16x16x32_bf16 v[112:115], v[206:209], v[156:159], v[112:115]
	v_mfma_f32_16x16x32_bf16 v[100:103], v[188:191], v[164:167], v[100:103]
	v_mfma_f32_16x16x32_bf16 v[96:99], v[206:209], v[164:167], v[96:99]
	v_mfma_f32_16x16x32_bf16 v[84:87], v[188:191], v[172:175], v[84:87]
	v_mfma_f32_16x16x32_bf16 v[80:83], v[206:209], v[172:175], v[80:83]
	v_mfma_f32_16x16x32_bf16 v[68:71], v[188:191], v[180:183], v[68:71]
	v_mfma_f32_16x16x32_bf16 v[64:67], v[206:209], v[180:183], v[64:67]
	v_mfma_f32_16x16x32_bf16 v[116:119], v[198:201], v[160:163], v[116:119]
	v_mfma_f32_16x16x32_bf16 v[112:115], v[210:213], v[160:163], v[112:115]
	v_mfma_f32_16x16x32_bf16 v[100:103], v[198:201], v[168:171], v[100:103]
	v_mfma_f32_16x16x32_bf16 v[96:99], v[210:213], v[168:171], v[96:99]
	v_mfma_f32_16x16x32_bf16 v[84:87], v[198:201], v[176:179], v[84:87]
	v_mfma_f32_16x16x32_bf16 v[80:83], v[210:213], v[176:179], v[80:83]
	v_mfma_f32_16x16x32_bf16 v[68:71], v[198:201], v[184:187], v[68:71]
	v_mfma_f32_16x16x32_bf16 v[64:67], v[210:213], v[184:187], v[64:67]
	s_setprio 0
	s_mov_b32 m0, s59
	v_lshl_add_u64 v[216:217], s[46:47], 0, v[128:129]
	s_barrier
	ds_read_b128 v[156:159], v151 offset:16384
	ds_read_b128 v[160:163], v151 offset:17408
	ds_read_b128 v[164:167], v151 offset:18432
	ds_read_b128 v[168:171], v151 offset:19456
	ds_read_b128 v[172:175], v151 offset:20480
	ds_read_b128 v[176:179], v151 offset:21504
	ds_read_b128 v[180:183], v151 offset:22528
	ds_read_b128 v[184:187], v151 offset:23552
	global_load_lds_dwordx4 v[216:217], off
	v_lshl_add_u64 v[218:219], s[46:47], 0, v[132:133]
	s_mov_b32 m0, s60
	s_nop 0
	global_load_lds_dwordx4 v[218:219], off
	s_barrier
	s_waitcnt lgkmcnt(0)
	s_setprio 1
	v_mfma_f32_16x16x32_bf16 v[60:63], v[136:139], v[156:159], v[60:63]
	v_mfma_f32_16x16x32_bf16 v[56:59], v[144:147], v[156:159], v[56:59]
	v_mfma_f32_16x16x32_bf16 v[44:47], v[136:139], v[164:167], v[44:47]
	v_mfma_f32_16x16x32_bf16 v[40:43], v[144:147], v[164:167], v[40:43]
	v_mfma_f32_16x16x32_bf16 v[28:31], v[136:139], v[172:175], v[28:31]
	v_mfma_f32_16x16x32_bf16 v[24:27], v[144:147], v[172:175], v[24:27]
	v_mfma_f32_16x16x32_bf16 v[12:15], v[136:139], v[180:183], v[12:15]
	v_mfma_f32_16x16x32_bf16 v[8:11], v[144:147], v[180:183], v[8:11]
	v_mfma_f32_16x16x32_bf16 v[60:63], v[140:143], v[160:163], v[60:63]
	v_mfma_f32_16x16x32_bf16 v[56:59], v[152:155], v[160:163], v[56:59]
	v_mfma_f32_16x16x32_bf16 v[44:47], v[140:143], v[168:171], v[44:47]
	v_mfma_f32_16x16x32_bf16 v[40:43], v[152:155], v[168:171], v[40:43]
	v_mfma_f32_16x16x32_bf16 v[28:31], v[140:143], v[176:179], v[28:31]
	v_mfma_f32_16x16x32_bf16 v[24:27], v[152:155], v[176:179], v[24:27]
	v_mfma_f32_16x16x32_bf16 v[12:15], v[140:143], v[184:187], v[12:15]
	v_mfma_f32_16x16x32_bf16 v[8:11], v[152:155], v[184:187], v[8:11]
	s_setprio 0
	s_barrier
	s_mov_b32 m0, s69
	v_lshl_add_u64 v[136:137], s[44:45], 0, v[130:131]
	global_load_lds_dwordx4 v[136:137], off
	v_lshl_add_u64 v[136:137], s[44:45], 0, v[134:135]
	s_mov_b32 m0, s68
	s_nop 0
	global_load_lds_dwordx4 v[136:137], off
	s_waitcnt vmcnt(6)
	s_barrier
	s_setprio 1
	v_mfma_f32_16x16x32_bf16 v[52:55], v[188:191], v[156:159], v[52:55]
	v_mfma_f32_16x16x32_bf16 v[48:51], v[206:209], v[156:159], v[48:51]
	v_mfma_f32_16x16x32_bf16 v[36:39], v[188:191], v[164:167], v[36:39]
	v_mfma_f32_16x16x32_bf16 v[32:35], v[206:209], v[164:167], v[32:35]
	v_mfma_f32_16x16x32_bf16 v[20:23], v[188:191], v[172:175], v[20:23]
	v_mfma_f32_16x16x32_bf16 v[16:19], v[206:209], v[172:175], v[16:19]
	v_mfma_f32_16x16x32_bf16 v[4:7], v[188:191], v[180:183], v[4:7]
	v_mfma_f32_16x16x32_bf16 v[0:3], v[206:209], v[180:183], v[0:3]
	v_mfma_f32_16x16x32_bf16 v[52:55], v[198:201], v[160:163], v[52:55]
	v_mfma_f32_16x16x32_bf16 v[48:51], v[210:213], v[160:163], v[48:51]
	v_mfma_f32_16x16x32_bf16 v[36:39], v[198:201], v[168:171], v[36:39]
	v_mfma_f32_16x16x32_bf16 v[32:35], v[210:213], v[168:171], v[32:35]
	v_mfma_f32_16x16x32_bf16 v[20:23], v[198:201], v[176:179], v[20:23]
	v_mfma_f32_16x16x32_bf16 v[16:19], v[210:213], v[176:179], v[16:19]
	v_mfma_f32_16x16x32_bf16 v[4:7], v[198:201], v[184:187], v[4:7]
	v_mfma_f32_16x16x32_bf16 v[0:3], v[210:213], v[184:187], v[0:3]
	s_setprio 0
	v_add_u32_e32 v152, s67, v150
	s_barrier
	ds_read_b128 v[136:139], v152
	ds_read_b128 v[140:143], v152 offset:1024
	ds_read_b128 v[144:147], v152 offset:2048
	ds_read_b128 v[152:155], v152 offset:3072
	s_mov_b32 m0, s61
	v_lshl_add_u64 v[188:189], s[42:43], 0, v[128:129]
	ds_read_b128 v[156:159], v151 offset:32768
	ds_read_b128 v[160:163], v151 offset:33792
	ds_read_b128 v[164:167], v151 offset:34816
	ds_read_b128 v[168:171], v151 offset:35840
	ds_read_b128 v[172:175], v151 offset:36864
	ds_read_b128 v[176:179], v151 offset:37888
	ds_read_b128 v[180:183], v151 offset:38912
	ds_read_b128 v[184:187], v151 offset:39936
	global_load_lds_dwordx4 v[188:189], off
	v_lshl_add_u64 v[188:189], s[42:43], 0, v[132:133]
	s_mov_b32 m0, s62
	s_nop 0
	global_load_lds_dwordx4 v[188:189], off
	s_waitcnt lgkmcnt(8)
	s_barrier
	s_waitcnt lgkmcnt(0)
	s_setprio 1
	v_mfma_f32_16x16x32_bf16 v[124:127], v[136:139], v[156:159], v[124:127]
	v_mfma_f32_16x16x32_bf16 v[120:123], v[144:147], v[156:159], v[120:123]
	v_mfma_f32_16x16x32_bf16 v[108:111], v[136:139], v[164:167], v[108:111]
	v_mfma_f32_16x16x32_bf16 v[104:107], v[144:147], v[164:167], v[104:107]
	v_mfma_f32_16x16x32_bf16 v[92:95], v[136:139], v[172:175], v[92:95]
	v_mfma_f32_16x16x32_bf16 v[88:91], v[144:147], v[172:175], v[88:91]
	v_mfma_f32_16x16x32_bf16 v[76:79], v[136:139], v[180:183], v[76:79]
	v_mfma_f32_16x16x32_bf16 v[72:75], v[144:147], v[180:183], v[72:75]
	v_mfma_f32_16x16x32_bf16 v[124:127], v[140:143], v[160:163], v[124:127]
	v_mfma_f32_16x16x32_bf16 v[120:123], v[152:155], v[160:163], v[120:123]
	v_mfma_f32_16x16x32_bf16 v[108:111], v[140:143], v[168:171], v[108:111]
	v_mfma_f32_16x16x32_bf16 v[104:107], v[152:155], v[168:171], v[104:107]
	v_mfma_f32_16x16x32_bf16 v[92:95], v[140:143], v[176:179], v[92:95]
	v_mfma_f32_16x16x32_bf16 v[88:91], v[152:155], v[176:179], v[88:91]
	v_mfma_f32_16x16x32_bf16 v[76:79], v[140:143], v[184:187], v[76:79]
	v_mfma_f32_16x16x32_bf16 v[72:75], v[152:155], v[184:187], v[72:75]
	s_setprio 0
	s_barrier
	s_mov_b32 m0, s35
	v_add_u32_e32 v192, s33, v150
	v_lshl_add_u64 v[148:149], v[148:149], 0, s[80:81]
	ds_read_b128 v[188:191], v192
	ds_read_b128 v[198:201], v192 offset:1024
	ds_read_b128 v[206:209], v192 offset:2048
	ds_read_b128 v[210:213], v192 offset:3072
	global_load_lds_dwordx4 v[148:149], off
	v_lshl_add_u64 v[148:149], v[214:215], 0, s[80:81]
	s_mov_b32 m0, s31
	s_nop 0
	global_load_lds_dwordx4 v[148:149], off
	s_barrier
	s_waitcnt lgkmcnt(0)
	s_setprio 1
	v_mfma_f32_16x16x32_bf16 v[116:119], v[188:191], v[156:159], v[116:119]
	v_mfma_f32_16x16x32_bf16 v[112:115], v[206:209], v[156:159], v[112:115]
	v_mfma_f32_16x16x32_bf16 v[100:103], v[188:191], v[164:167], v[100:103]
	v_mfma_f32_16x16x32_bf16 v[96:99], v[206:209], v[164:167], v[96:99]
	v_mfma_f32_16x16x32_bf16 v[84:87], v[188:191], v[172:175], v[84:87]
	v_mfma_f32_16x16x32_bf16 v[80:83], v[206:209], v[172:175], v[80:83]
	v_mfma_f32_16x16x32_bf16 v[68:71], v[188:191], v[180:183], v[68:71]
	v_mfma_f32_16x16x32_bf16 v[64:67], v[206:209], v[180:183], v[64:67]
	v_mfma_f32_16x16x32_bf16 v[116:119], v[198:201], v[160:163], v[116:119]
	v_mfma_f32_16x16x32_bf16 v[112:115], v[210:213], v[160:163], v[112:115]
	v_mfma_f32_16x16x32_bf16 v[100:103], v[198:201], v[168:171], v[100:103]
	v_mfma_f32_16x16x32_bf16 v[96:99], v[210:213], v[168:171], v[96:99]
	v_mfma_f32_16x16x32_bf16 v[84:87], v[198:201], v[176:179], v[84:87]
	v_mfma_f32_16x16x32_bf16 v[80:83], v[210:213], v[176:179], v[80:83]
	v_mfma_f32_16x16x32_bf16 v[68:71], v[198:201], v[184:187], v[68:71]
	v_mfma_f32_16x16x32_bf16 v[64:67], v[210:213], v[184:187], v[64:67]
	s_setprio 0
	s_mov_b32 m0, s63
	v_lshl_add_u64 v[148:149], v[216:217], 0, s[80:81]
	s_barrier
	ds_read_b128 v[156:159], v151 offset:49152
	ds_read_b128 v[160:163], v151 offset:50176
	ds_read_b128 v[164:167], v151 offset:51200
	ds_read_b128 v[168:171], v151 offset:52224
	ds_read_b128 v[172:175], v151 offset:53248
	ds_read_b128 v[176:179], v151 offset:54272
	ds_read_b128 v[180:183], v151 offset:55296
	ds_read_b128 v[184:187], v151 offset:56320
	global_load_lds_dwordx4 v[148:149], off
	v_lshl_add_u64 v[148:149], v[218:219], 0, s[80:81]
	s_mov_b32 m0, s64
	s_nop 0
	global_load_lds_dwordx4 v[148:149], off
	s_barrier
	s_waitcnt lgkmcnt(0)
	s_setprio 1
	v_mfma_f32_16x16x32_bf16 v[60:63], v[136:139], v[156:159], v[60:63]
	v_mfma_f32_16x16x32_bf16 v[56:59], v[144:147], v[156:159], v[56:59]
	v_mfma_f32_16x16x32_bf16 v[44:47], v[136:139], v[164:167], v[44:47]
	v_mfma_f32_16x16x32_bf16 v[40:43], v[144:147], v[164:167], v[40:43]
	v_mfma_f32_16x16x32_bf16 v[28:31], v[136:139], v[172:175], v[28:31]
	v_mfma_f32_16x16x32_bf16 v[24:27], v[144:147], v[172:175], v[24:27]
	v_mfma_f32_16x16x32_bf16 v[12:15], v[136:139], v[180:183], v[12:15]
	v_mfma_f32_16x16x32_bf16 v[8:11], v[144:147], v[180:183], v[8:11]
	v_mfma_f32_16x16x32_bf16 v[60:63], v[140:143], v[160:163], v[60:63]
	v_mfma_f32_16x16x32_bf16 v[56:59], v[152:155], v[160:163], v[56:59]
	v_mfma_f32_16x16x32_bf16 v[44:47], v[140:143], v[168:171], v[44:47]
	v_mfma_f32_16x16x32_bf16 v[40:43], v[152:155], v[168:171], v[40:43]
	v_mfma_f32_16x16x32_bf16 v[28:31], v[140:143], v[176:179], v[28:31]
	v_mfma_f32_16x16x32_bf16 v[24:27], v[152:155], v[176:179], v[24:27]
	v_mfma_f32_16x16x32_bf16 v[12:15], v[140:143], v[184:187], v[12:15]
	v_mfma_f32_16x16x32_bf16 v[8:11], v[152:155], v[184:187], v[8:11]
	s_setprio 0
	s_barrier
	s_mov_b32 m0, s73
	v_lshl_add_u64 v[136:137], s[40:41], 0, v[130:131]
	global_load_lds_dwordx4 v[136:137], off
	v_lshl_add_u64 v[136:137], s[40:41], 0, v[134:135]
	s_mov_b32 m0, s72
	s_nop 0
	global_load_lds_dwordx4 v[136:137], off
	s_waitcnt vmcnt(6)
	s_barrier
	s_setprio 1
	v_mfma_f32_16x16x32_bf16 v[52:55], v[188:191], v[156:159], v[52:55]
	v_mfma_f32_16x16x32_bf16 v[48:51], v[206:209], v[156:159], v[48:51]
	v_mfma_f32_16x16x32_bf16 v[36:39], v[188:191], v[164:167], v[36:39]
	v_mfma_f32_16x16x32_bf16 v[32:35], v[206:209], v[164:167], v[32:35]
	v_mfma_f32_16x16x32_bf16 v[20:23], v[188:191], v[172:175], v[20:23]
	v_mfma_f32_16x16x32_bf16 v[16:19], v[206:209], v[172:175], v[16:19]
	v_mfma_f32_16x16x32_bf16 v[4:7], v[188:191], v[180:183], v[4:7]
	v_mfma_f32_16x16x32_bf16 v[0:3], v[206:209], v[180:183], v[0:3]
	v_mfma_f32_16x16x32_bf16 v[52:55], v[198:201], v[160:163], v[52:55]
	v_mfma_f32_16x16x32_bf16 v[48:51], v[210:213], v[160:163], v[48:51]
	v_mfma_f32_16x16x32_bf16 v[36:39], v[198:201], v[168:171], v[36:39]
	v_mfma_f32_16x16x32_bf16 v[32:35], v[210:213], v[168:171], v[32:35]
	v_mfma_f32_16x16x32_bf16 v[20:23], v[198:201], v[176:179], v[20:23]
	v_mfma_f32_16x16x32_bf16 v[16:19], v[210:213], v[176:179], v[16:19]
	v_mfma_f32_16x16x32_bf16 v[4:7], v[198:201], v[184:187], v[4:7]
	v_mfma_f32_16x16x32_bf16 v[0:3], v[210:213], v[184:187], v[0:3]
	s_setprio 0
	s_andn2_b64 vcc, exec, s[14:15]
	s_mov_b64 s[40:41], -1
	s_mov_b64 s[14:15], 0
	s_mov_b64 s[42:43], 0x100
	s_barrier
	s_cbranch_vccz .LBB0_1681
	v_mov_b32_e32 v137, v252
	s_lshl_b32 s0, s8, 8
	v_readfirstlane_b32 s1, v137
	s_ashr_i32 s7, s1, 2
	s_lshr_b32 s1, s1, 1
	s_andn2_b32 s7, s7, 63
	s_and_b32 s1, s1, 0x60
	v_lshrrev_b32_e32 v138, 1, v137
	s_lshl_b32 s6, s6, 8
	v_and_b32_e32 v147, 15, v137
	s_add_i32 s0, s7, s0
	v_and_b32_e32 v160, 24, v138
	s_or_b32 s31, s1, s6
	v_or_b32_e32 v136, s0, v147
	v_or_b32_e32 v156, s31, v160
	v_and_b32_e32 v153, 4, v138
	v_lshlrev_b32_e32 v137, 1, v137
	v_lshlrev_b32_e32 v138, 13, v156
	v_and_or_b32 v154, v137, 8, v153
	v_ashrrev_i32_e32 v137, 31, v136
	v_and_b32_e32 v152, 0x70000, v138
	v_lshl_add_u64 v[138:139], v[136:137], 2, s[24:25]
	global_load_dword v137, v[138:139], off
	v_or_b32_e32 v144, 16, v136
	v_ashrrev_i32_e32 v145, 31, v144
	v_or_b32_e32 v142, 32, v136
	v_lshl_add_u64 v[140:141], v[144:145], 2, s[24:25]
	v_ashrrev_i32_e32 v143, 31, v142
	global_load_dword v155, v[140:141], off
	v_lshl_add_u64 v[140:141], v[142:143], 2, s[24:25]
	global_load_dword v145, v[140:141], off
	v_or_b32_e32 v140, 48, v136
	v_ashrrev_i32_e32 v141, 31, v140
	v_lshl_add_u64 v[148:149], v[140:141], 2, s[24:25]
	global_load_dword v143, v[148:149], off
	v_add_u32_e32 v158, 0xffffc000, v136
	v_lshlrev_b32_e32 v146, 1, v158
	v_and_b32_e32 v141, 0x7fffffc3, v158
	v_and_b32_e32 v146, 8, v146
	v_or3_b32 v157, v141, v146, v153
	s_ashr_i32 s1, s0, 10
	s_and_b32 s35, s1, -8
	s_movk_i32 s1, 0x1fc3
	s_movk_i32 s44, 0x3fff
	v_and_or_b32 v159, v136, s1, v154
	s_movk_i32 s1, 0x1ff
	v_cmp_lt_i32_e64 s[12:13], s44, v136
	s_waitcnt vmcnt(0)
	v_fmamk_f32 v137, v137, 0x3b800000, v194
	v_cmp_gt_f32_e32 vcc, s2, v137
	v_mul_f32_e32 v141, 0x4b800000, v137
	s_nop 0
	v_cndmask_b32_e32 v137, v137, v141, vcc
	v_rsq_f32_e32 v137, v137
	s_nop 0
	v_mul_f32_e32 v141, 0x45800000, v137
	v_cndmask_b32_e32 v146, v137, v141, vcc
	v_pk_mul_f32 v[126:127], v[126:127], v[146:147] op_sel_hi:[1,0]
	v_pk_mul_f32 v[124:125], v[124:125], v[146:147] op_sel_hi:[1,0]
	v_cmp_lt_i32_e32 vcc, s1, v156
	v_add_u32_e32 v141, 0xfffffe00, v156
	s_and_saveexec_b64 s[6:7], vcc
	s_xor_b64 s[6:7], exec, s[6:7]
	s_cbranch_execz .LBB0_1688
	s_and_saveexec_b64 s[8:9], s[12:13]
	s_xor_b64 s[8:9], exec, s[8:9]
	v_lshlrev_b32_e32 v192, 6, v141
	v_lshl_add_u64 v[148:149], v[192:193], 1, s[22:23]
	s_or_saveexec_b64 s[8:9], s[8:9]
	v_mov_b32_e32 v137, 64
	v_mov_b32_e32 v161, v157
	s_xor_b64 exec, exec, s[8:9]
	v_lshrrev_b32_e32 v137, 6, v141
	v_add_u32_e32 v148, s35, v137
	v_ashrrev_i32_e32 v149, 31, v148
	v_lshlrev_b64 v[148:149], 20, v[148:149]
	v_lshl_add_u64 v[148:149], s[28:29], 0, v[148:149]
	v_lshlrev_b32_e32 v192, 1, v152
	v_lshl_add_u64 v[148:149], v[148:149], 0, v[192:193]
	v_mov_b32_e32 v137, 0x2000
	v_mov_b32_e32 v161, v159
	s_or_b64 exec, exec, s[8:9]
	v_lshlrev_b32_e32 v192, 1, v161
	v_lshl_add_u64 v[148:149], v[148:149], 0, v[192:193]
	v_cvt_pk_bf16_f32 v124, v124, s0
	v_lshlrev_b32_e32 v192, 1, v137
	global_store_short v[148:149], v124, off
	v_cvt_pk_bf16_f32 v161, v125, s0
	v_lshl_add_u64 v[124:125], v[148:149], 0, v[192:193]
	v_lshlrev_b32_e32 v192, 2, v137
	global_store_short v[124:125], v161, off
	v_cvt_pk_bf16_f32 v126, v126, s0
	v_lshl_add_u64 v[124:125], v[148:149], 0, v[192:193]
	global_store_short v[124:125], v126, off
	v_mul_u32_u24_e32 v124, 3, v137
	v_lshlrev_b32_e32 v192, 1, v124
	v_cvt_pk_bf16_f32 v126, v127, s0
	v_lshl_add_u64 v[124:125], v[148:149], 0, v[192:193]
	global_store_short v[124:125], v126, off

.LBB0_2148:
	s_add_u32 s34, s30, 0xfffc0080
	s_addc_u32 s35, s31, -1
	s_add_i32 s51, 0, 0x10000
	v_add_u32_e32 v146, s51, v148
	ds_read_b128 v[138:141], v146
	ds_read_b128 v[142:145], v146 offset:1024
	ds_read_b128 v[150:153], v146 offset:2048
	ds_read_b128 v[154:157], v146 offset:3072
	s_cmp_eq_u32 s33, 12
	s_cselect_b32 s37, s0, s35
	s_cselect_b32 s36, s1, s34
	s_cselect_b32 s35, s7, s25
	s_cselect_b32 s34, s9, s19
	s_add_i32 m0, s44, 0xc000
	ds_read_b128 v[158:161], v149
	ds_read_b128 v[162:165], v149 offset:1024
	ds_read_b128 v[166:169], v149 offset:2048
	ds_read_b128 v[170:173], v149 offset:3072
	ds_read_b128 v[174:177], v149 offset:4096
	ds_read_b128 v[178:181], v149 offset:5120
	ds_read_b128 v[182:185], v149 offset:6144
	ds_read_b128 v[186:189], v149 offset:7168
	global_load_lds_dwordx4 v134, s[30:31]
	s_add_i32 m0, s44, 0xe000
	s_nop 0
	global_load_lds_dwordx4 v136, s[30:31]
	s_waitcnt lgkmcnt(8)
	s_barrier
	s_waitcnt lgkmcnt(0)
	s_setprio 1
	v_mfma_f32_16x16x32_bf16 v[124:127], v[138:141], v[158:161], v[124:127]
	v_mfma_f32_16x16x32_bf16 v[120:123], v[150:153], v[158:161], v[120:123]
	v_mfma_f32_16x16x32_bf16 v[108:111], v[138:141], v[166:169], v[108:111]
	v_mfma_f32_16x16x32_bf16 v[104:107], v[150:153], v[166:169], v[104:107]
	v_mfma_f32_16x16x32_bf16 v[92:95], v[138:141], v[174:177], v[92:95]
	v_mfma_f32_16x16x32_bf16 v[88:91], v[150:153], v[174:177], v[88:91]
	v_mfma_f32_16x16x32_bf16 v[76:79], v[138:141], v[182:185], v[76:79]
	v_mfma_f32_16x16x32_bf16 v[72:75], v[150:153], v[182:185], v[72:75]
	v_mfma_f32_16x16x32_bf16 v[124:127], v[142:145], v[162:165], v[124:127]
	v_mfma_f32_16x16x32_bf16 v[120:123], v[154:157], v[162:165], v[120:123]
	v_mfma_f32_16x16x32_bf16 v[108:111], v[142:145], v[170:173], v[108:111]
	v_mfma_f32_16x16x32_bf16 v[104:107], v[154:157], v[170:173], v[104:107]
	v_mfma_f32_16x16x32_bf16 v[92:95], v[142:145], v[178:181], v[92:95]
	v_mfma_f32_16x16x32_bf16 v[88:91], v[154:157], v[178:181], v[88:91]
	v_mfma_f32_16x16x32_bf16 v[76:79], v[142:145], v[186:189], v[76:79]
	v_mfma_f32_16x16x32_bf16 v[72:75], v[154:157], v[186:189], v[72:75]
	s_setprio 0
	s_barrier
	s_add_i32 s54, 0, 0x14000
	v_add_u32_e32 v146, s54, v148
	s_add_i32 s51, s51, s43
	ds_read_b128 v[198:201], v146
	ds_read_b128 v[206:209], v146 offset:1024
	ds_read_b128 v[210:213], v146 offset:2048
	ds_read_b128 v[214:217], v146 offset:3072
	s_mov_b32 m0, s51
	s_nop 0
	global_load_lds_dwordx4 v192, s[34:35]
	s_add_i32 m0, s51, 0x2000
	s_nop 0
	global_load_lds_dwordx4 v132, s[34:35]
	s_barrier
	s_waitcnt lgkmcnt(0)
	s_setprio 1
	v_mfma_f32_16x16x32_bf16 v[116:119], v[198:201], v[158:161], v[116:119]
	v_mfma_f32_16x16x32_bf16 v[112:115], v[210:213], v[158:161], v[112:115]
	v_mfma_f32_16x16x32_bf16 v[100:103], v[198:201], v[166:169], v[100:103]
	v_mfma_f32_16x16x32_bf16 v[96:99], v[210:213], v[166:169], v[96:99]
	v_mfma_f32_16x16x32_bf16 v[84:87], v[198:201], v[174:177], v[84:87]
	v_mfma_f32_16x16x32_bf16 v[80:83], v[210:213], v[174:177], v[80:83]
	v_mfma_f32_16x16x32_bf16 v[68:71], v[198:201], v[182:185], v[68:71]
	v_mfma_f32_16x16x32_bf16 v[64:67], v[210:213], v[182:185], v[64:67]
	v_mfma_f32_16x16x32_bf16 v[116:119], v[206:209], v[162:165], v[116:119]
	v_mfma_f32_16x16x32_bf16 v[112:115], v[214:217], v[162:165], v[112:115]
	v_mfma_f32_16x16x32_bf16 v[100:103], v[206:209], v[170:173], v[100:103]
	v_mfma_f32_16x16x32_bf16 v[96:99], v[214:217], v[170:173], v[96:99]
	v_mfma_f32_16x16x32_bf16 v[84:87], v[206:209], v[178:181], v[84:87]
	v_mfma_f32_16x16x32_bf16 v[80:83], v[214:217], v[178:181], v[80:83]
	v_mfma_f32_16x16x32_bf16 v[68:71], v[206:209], v[186:189], v[68:71]
	v_mfma_f32_16x16x32_bf16 v[64:67], v[214:217], v[186:189], v[64:67]
	s_setprio 0
	s_mov_b32 m0, s44
	s_add_u32 vcc_lo, s36, 0x80
	s_addc_u32 vcc_hi, s37, 0
	s_barrier
	ds_read_b128 v[158:161], v149 offset:16384
	ds_read_b128 v[162:165], v149 offset:17408
	ds_read_b128 v[166:169], v149 offset:18432
	ds_read_b128 v[170:173], v149 offset:19456
	ds_read_b128 v[174:177], v149 offset:20480
	ds_read_b128 v[178:181], v149 offset:21504
	ds_read_b128 v[182:185], v149 offset:22528
	ds_read_b128 v[186:189], v149 offset:23552
	global_load_lds_dwordx4 v128, s[36:37]
	s_mov_b32 m0, s45
	s_nop 0
	global_load_lds_dwordx4 v130, s[36:37]
	s_barrier
	s_waitcnt lgkmcnt(0)
	s_setprio 1
	v_mfma_f32_16x16x32_bf16 v[60:63], v[138:141], v[158:161], v[60:63]
	v_mfma_f32_16x16x32_bf16 v[56:59], v[150:153], v[158:161], v[56:59]
	v_mfma_f32_16x16x32_bf16 v[44:47], v[138:141], v[166:169], v[44:47]
	v_mfma_f32_16x16x32_bf16 v[40:43], v[150:153], v[166:169], v[40:43]
	v_mfma_f32_16x16x32_bf16 v[28:31], v[138:141], v[174:177], v[28:31]
	v_mfma_f32_16x16x32_bf16 v[24:27], v[150:153], v[174:177], v[24:27]
	v_mfma_f32_16x16x32_bf16 v[12:15], v[138:141], v[182:185], v[12:15]
	v_mfma_f32_16x16x32_bf16 v[8:11], v[150:153], v[182:185], v[8:11]
	v_mfma_f32_16x16x32_bf16 v[60:63], v[142:145], v[162:165], v[60:63]
	v_mfma_f32_16x16x32_bf16 v[56:59], v[154:157], v[162:165], v[56:59]
	v_mfma_f32_16x16x32_bf16 v[44:47], v[142:145], v[170:173], v[44:47]
	v_mfma_f32_16x16x32_bf16 v[40:43], v[154:157], v[170:173], v[40:43]
	v_mfma_f32_16x16x32_bf16 v[28:31], v[142:145], v[178:181], v[28:31]
	v_mfma_f32_16x16x32_bf16 v[24:27], v[154:157], v[178:181], v[24:27]
	v_mfma_f32_16x16x32_bf16 v[12:15], v[142:145], v[186:189], v[12:15]
	v_mfma_f32_16x16x32_bf16 v[8:11], v[154:157], v[186:189], v[8:11]
	s_setprio 0
	s_barrier
	s_add_u32 s52, s34, 0x40000
	s_addc_u32 s53, s35, 0
	s_add_i32 s51, s54, s43
	s_mov_b32 m0, s51
	s_nop 0
	global_load_lds_dwordx4 v192, s[52:53]
	s_add_i32 m0, s51, 0x2000
	s_nop 0
	global_load_lds_dwordx4 v132, s[52:53]
	s_waitcnt vmcnt(6)
	s_barrier
	s_setprio 1
	v_mfma_f32_16x16x32_bf16 v[52:55], v[198:201], v[158:161], v[52:55]
	v_mfma_f32_16x16x32_bf16 v[48:51], v[210:213], v[158:161], v[48:51]
	v_mfma_f32_16x16x32_bf16 v[36:39], v[198:201], v[166:169], v[36:39]
	v_mfma_f32_16x16x32_bf16 v[32:35], v[210:213], v[166:169], v[32:35]
	v_mfma_f32_16x16x32_bf16 v[20:23], v[198:201], v[174:177], v[20:23]
	v_mfma_f32_16x16x32_bf16 v[16:19], v[210:213], v[174:177], v[16:19]
	v_mfma_f32_16x16x32_bf16 v[4:7], v[198:201], v[182:185], v[4:7]
	v_mfma_f32_16x16x32_bf16 v[0:3], v[210:213], v[182:185], v[0:3]
	v_mfma_f32_16x16x32_bf16 v[52:55], v[206:209], v[162:165], v[52:55]
	v_mfma_f32_16x16x32_bf16 v[48:51], v[214:217], v[162:165], v[48:51]
	v_mfma_f32_16x16x32_bf16 v[36:39], v[206:209], v[170:173], v[36:39]
	v_mfma_f32_16x16x32_bf16 v[32:35], v[214:217], v[170:173], v[32:35]
	v_mfma_f32_16x16x32_bf16 v[20:23], v[206:209], v[178:181], v[20:23]
	v_mfma_f32_16x16x32_bf16 v[16:19], v[214:217], v[178:181], v[16:19]
	v_mfma_f32_16x16x32_bf16 v[4:7], v[206:209], v[186:189], v[4:7]
	v_mfma_f32_16x16x32_bf16 v[0:3], v[214:217], v[186:189], v[0:3]
	s_setprio 0
	s_add_i32 s51, 0, 0x18000
	v_add_u32_e32 v154, s51, v148
	s_barrier
	ds_read_b128 v[138:141], v154
	ds_read_b128 v[142:145], v154 offset:1024
	ds_read_b128 v[150:153], v154 offset:2048
	ds_read_b128 v[154:157], v154 offset:3072
	s_add_u32 s36, s36, 0x40000
	s_addc_u32 s37, s37, 0
	s_mov_b32 m0, s46
	ds_read_b128 v[158:161], v149 offset:32768
	ds_read_b128 v[162:165], v149 offset:33792
	ds_read_b128 v[166:169], v149 offset:34816
	ds_read_b128 v[170:173], v149 offset:35840
	ds_read_b128 v[174:177], v149 offset:36864
	ds_read_b128 v[178:181], v149 offset:37888
	ds_read_b128 v[182:185], v149 offset:38912
	ds_read_b128 v[186:189], v149 offset:39936
	global_load_lds_dwordx4 v128, s[36:37]
	s_mov_b32 m0, s47
	s_nop 0
	global_load_lds_dwordx4 v130, s[36:37]
	s_waitcnt lgkmcnt(8)
	s_barrier
	s_waitcnt lgkmcnt(0)
	s_setprio 1
	v_mfma_f32_16x16x32_bf16 v[124:127], v[138:141], v[158:161], v[124:127]
	v_mfma_f32_16x16x32_bf16 v[120:123], v[150:153], v[158:161], v[120:123]
	v_mfma_f32_16x16x32_bf16 v[108:111], v[138:141], v[166:169], v[108:111]
	v_mfma_f32_16x16x32_bf16 v[104:107], v[150:153], v[166:169], v[104:107]
	v_mfma_f32_16x16x32_bf16 v[92:95], v[138:141], v[174:177], v[92:95]
	v_mfma_f32_16x16x32_bf16 v[88:91], v[150:153], v[174:177], v[88:91]
	v_mfma_f32_16x16x32_bf16 v[76:79], v[138:141], v[182:185], v[76:79]
	v_mfma_f32_16x16x32_bf16 v[72:75], v[150:153], v[182:185], v[72:75]
	v_mfma_f32_16x16x32_bf16 v[124:127], v[142:145], v[162:165], v[124:127]
	v_mfma_f32_16x16x32_bf16 v[120:123], v[154:157], v[162:165], v[120:123]
	v_mfma_f32_16x16x32_bf16 v[108:111], v[142:145], v[170:173], v[108:111]
	v_mfma_f32_16x16x32_bf16 v[104:107], v[154:157], v[170:173], v[104:107]
	v_mfma_f32_16x16x32_bf16 v[92:95], v[142:145], v[178:181], v[92:95]
	v_mfma_f32_16x16x32_bf16 v[88:91], v[154:157], v[178:181], v[88:91]
	v_mfma_f32_16x16x32_bf16 v[76:79], v[142:145], v[186:189], v[76:79]
	v_mfma_f32_16x16x32_bf16 v[72:75], v[154:157], v[186:189], v[72:75]
	s_setprio 0
	s_barrier
	s_add_i32 s36, 0, 0x1c000
	s_add_i32 s37, s51, s43
	v_add_u32_e32 v196, s36, v148
	s_add_u32 s100, s34, 0x80
	s_addc_u32 s101, s35, 0
	s_mov_b32 m0, s37
	ds_read_b128 v[198:201], v196
	ds_read_b128 v[206:209], v196 offset:1024
	ds_read_b128 v[210:213], v196 offset:2048
	ds_read_b128 v[214:217], v196 offset:3072
	global_load_lds_dwordx4 v192, s[100:101]
	s_add_i32 m0, s37, 0x2000
	s_nop 0
	global_load_lds_dwordx4 v132, s[100:101]
	s_barrier
	s_waitcnt lgkmcnt(0)
	s_setprio 1
	v_mfma_f32_16x16x32_bf16 v[116:119], v[198:201], v[158:161], v[116:119]
	v_mfma_f32_16x16x32_bf16 v[112:115], v[210:213], v[158:161], v[112:115]
	v_mfma_f32_16x16x32_bf16 v[100:103], v[198:201], v[166:169], v[100:103]
	v_mfma_f32_16x16x32_bf16 v[96:99], v[210:213], v[166:169], v[96:99]
	v_mfma_f32_16x16x32_bf16 v[84:87], v[198:201], v[174:177], v[84:87]
	v_mfma_f32_16x16x32_bf16 v[80:83], v[210:213], v[174:177], v[80:83]
	v_mfma_f32_16x16x32_bf16 v[68:71], v[198:201], v[182:185], v[68:71]
	v_mfma_f32_16x16x32_bf16 v[64:67], v[210:213], v[182:185], v[64:67]
	v_mfma_f32_16x16x32_bf16 v[116:119], v[206:209], v[162:165], v[116:119]
	v_mfma_f32_16x16x32_bf16 v[112:115], v[214:217], v[162:165], v[112:115]
	v_mfma_f32_16x16x32_bf16 v[100:103], v[206:209], v[170:173], v[100:103]
	v_mfma_f32_16x16x32_bf16 v[96:99], v[214:217], v[170:173], v[96:99]
	v_mfma_f32_16x16x32_bf16 v[84:87], v[206:209], v[178:181], v[84:87]
	v_mfma_f32_16x16x32_bf16 v[80:83], v[214:217], v[178:181], v[80:83]
	v_mfma_f32_16x16x32_bf16 v[68:71], v[206:209], v[186:189], v[68:71]
	v_mfma_f32_16x16x32_bf16 v[64:67], v[214:217], v[186:189], v[64:67]
	s_setprio 0
	s_mov_b32 m0, s48
	s_barrier
	ds_read_b128 v[158:161], v149 offset:49152
	ds_read_b128 v[162:165], v149 offset:50176
	ds_read_b128 v[166:169], v149 offset:51200
	ds_read_b128 v[170:173], v149 offset:52224
	ds_read_b128 v[174:177], v149 offset:53248
	ds_read_b128 v[178:181], v149 offset:54272
	ds_read_b128 v[182:185], v149 offset:55296
	ds_read_b128 v[186:189], v149 offset:56320
	global_load_lds_dwordx4 v128, vcc
	s_mov_b32 m0, s49
	s_nop 0
	global_load_lds_dwordx4 v130, vcc
	s_barrier
	s_waitcnt lgkmcnt(0)
	s_setprio 1
	v_mfma_f32_16x16x32_bf16 v[60:63], v[138:141], v[158:161], v[60:63]
	v_mfma_f32_16x16x32_bf16 v[56:59], v[150:153], v[158:161], v[56:59]
	v_mfma_f32_16x16x32_bf16 v[44:47], v[138:141], v[166:169], v[44:47]
	v_mfma_f32_16x16x32_bf16 v[40:43], v[150:153], v[166:169], v[40:43]
	v_mfma_f32_16x16x32_bf16 v[28:31], v[138:141], v[174:177], v[28:31]
	v_mfma_f32_16x16x32_bf16 v[24:27], v[150:153], v[174:177], v[24:27]
	v_mfma_f32_16x16x32_bf16 v[12:15], v[138:141], v[182:185], v[12:15]
	v_mfma_f32_16x16x32_bf16 v[8:11], v[150:153], v[182:185], v[8:11]
	v_mfma_f32_16x16x32_bf16 v[60:63], v[142:145], v[162:165], v[60:63]
	v_mfma_f32_16x16x32_bf16 v[56:59], v[154:157], v[162:165], v[56:59]
	v_mfma_f32_16x16x32_bf16 v[44:47], v[142:145], v[170:173], v[44:47]
	v_mfma_f32_16x16x32_bf16 v[40:43], v[154:157], v[170:173], v[40:43]
	v_mfma_f32_16x16x32_bf16 v[28:31], v[142:145], v[178:181], v[28:31]
	v_mfma_f32_16x16x32_bf16 v[24:27], v[154:157], v[178:181], v[24:27]
	v_mfma_f32_16x16x32_bf16 v[12:15], v[142:145], v[186:189], v[12:15]
	v_mfma_f32_16x16x32_bf16 v[8:11], v[154:157], v[186:189], v[8:11]
	s_setprio 0
	s_barrier
	s_add_u32 s34, s34, 0x40080
	s_addc_u32 s35, s35, 0
	s_add_i32 s36, s36, s43
	s_mov_b32 m0, s36
	s_nop 0
	global_load_lds_dwordx4 v192, s[34:35]
	s_add_i32 m0, s36, 0x2000
	s_nop 0
	global_load_lds_dwordx4 v132, s[34:35]
	s_waitcnt vmcnt(6)
	s_barrier
	s_setprio 1
	v_mfma_f32_16x16x32_bf16 v[52:55], v[198:201], v[158:161], v[52:55]
	v_mfma_f32_16x16x32_bf16 v[48:51], v[210:213], v[158:161], v[48:51]
	v_mfma_f32_16x16x32_bf16 v[36:39], v[198:201], v[166:169], v[36:39]
	v_mfma_f32_16x16x32_bf16 v[32:35], v[210:213], v[166:169], v[32:35]
	v_mfma_f32_16x16x32_bf16 v[20:23], v[198:201], v[174:177], v[20:23]
	v_mfma_f32_16x16x32_bf16 v[16:19], v[210:213], v[174:177], v[16:19]
	v_mfma_f32_16x16x32_bf16 v[4:7], v[198:201], v[182:185], v[4:7]
	v_mfma_f32_16x16x32_bf16 v[0:3], v[210:213], v[182:185], v[0:3]
	v_mfma_f32_16x16x32_bf16 v[52:55], v[206:209], v[162:165], v[52:55]
	v_mfma_f32_16x16x32_bf16 v[48:51], v[214:217], v[162:165], v[48:51]
	v_mfma_f32_16x16x32_bf16 v[36:39], v[206:209], v[170:173], v[36:39]
	v_mfma_f32_16x16x32_bf16 v[32:35], v[214:217], v[170:173], v[32:35]
	v_mfma_f32_16x16x32_bf16 v[20:23], v[206:209], v[178:181], v[20:23]
	v_mfma_f32_16x16x32_bf16 v[16:19], v[214:217], v[178:181], v[16:19]
	v_mfma_f32_16x16x32_bf16 v[4:7], v[206:209], v[186:189], v[4:7]
	v_mfma_f32_16x16x32_bf16 v[0:3], v[214:217], v[186:189], v[0:3]
	s_setprio 0
	s_add_i32 s33, s33, 2
	s_add_u32 s30, s30, 0x100
	s_addc_u32 s31, s31, 0
	s_add_u32 s19, s19, 0x100
	s_addc_u32 s25, s25, 0
	s_cmp_gt_u32 s33, 13
	s_barrier
	s_cbranch_scc0 .LBB0_2148
	v_mov_b32_e32 v138, v252
	s_lshl_b32 s1, s8, 8
	v_readfirstlane_b32 s0, v138
	s_ashr_i32 s7, s0, 2
	s_andn2_b32 s7, s7, 63
	s_add_i32 s7, s7, s1
	v_and_or_b32 v140, v138, 15, s7
	v_ashrrev_i32_e32 v141, 31, v140
	v_lshl_add_u64 v[142:143], v[140:141], 2, s[14:15]
	global_load_dword v139, v[142:143], off
	global_load_dword v153, v[142:143], off offset:64
	global_load_dword v152, v[142:143], off offset:128
	global_load_dword v151, v[142:143], off offset:192
	s_lshl_b32 s1, s6, 8
	s_lshr_b32 s0, s0, 1
	s_and_b32 s0, s0, 0x60
	v_lshrrev_b32_e32 v138, 1, v138
	s_or_b32 s0, s0, s1
	v_and_or_b32 v138, v138, 24, s0
	v_mad_i64_i32 v[154:155], s[0:1], v140, s55, 0
	v_cmp_gt_i32_e32 vcc, s55, v138
	s_waitcnt vmcnt(0)
	v_fmamk_f32 v139, v139, 0x3a800000, v194
	v_mul_f32_e32 v144, 0x4b800000, v139
	v_cmp_gt_f32_e64 s[6:7], s2, v139
	s_nop 1
	v_cndmask_b32_e64 v139, v139, v144, s[6:7]
	v_rsq_f32_e32 v144, v139
	v_ashrrev_i32_e32 v139, 31, v138
	v_mul_f32_e32 v145, 0x45800000, v144
	v_cndmask_b32_e64 v144, v144, v145, s[6:7]
	v_pk_mul_f32 v[126:127], v[126:127], v[144:145] op_sel_hi:[1,0]
	v_pk_mul_f32 v[124:125], v[124:125], v[144:145] op_sel_hi:[1,0]
	v_pk_mul_f32 v[146:147], v[122:123], v[144:145] op_sel_hi:[1,0]
	v_pk_mul_f32 v[120:121], v[120:121], v[144:145] op_sel_hi:[1,0]
	v_lshl_add_u64 v[122:123], v[154:155], 1, s[12:13]
	s_and_saveexec_b64 s[6:7], vcc
	s_cbranch_execz .LBB0_2151
	v_cvt_pk_bf16_f32 v150, v125, v127
	v_cvt_pk_bf16_f32 v145, v124, v126
	v_and_b32_e32 v154, 0xffff0000, v150
	v_lshlrev_b32_e32 v150, 16, v150
	v_or_b32_sdwa v155, v154, v145 dst_sel:DWORD dst_unused:UNUSED_PAD src0_sel:DWORD src1_sel:WORD_1
	v_or_b32_sdwa v154, v150, v145 dst_sel:DWORD dst_unused:UNUSED_PAD src0_sel:DWORD src1_sel:WORD_0
	v_cvt_pk_bf16_f32 v150, v121, v147
	v_cvt_pk_bf16_f32 v145, v120, v146
	v_and_b32_e32 v156, 0xffff0000, v150
	v_lshlrev_b32_e32 v150, 16, v150
	v_lshl_add_u64 v[158:159], v[138:139], 1, v[122:123]
	v_or_b32_sdwa v157, v156, v145 dst_sel:DWORD dst_unused:UNUSED_PAD src0_sel:DWORD src1_sel:WORD_1
	v_or_b32_sdwa v156, v150, v145 dst_sel:DWORD dst_unused:UNUSED_PAD src0_sel:DWORD src1_sel:WORD_0
	global_store_dwordx4 v[158:159], v[154:157], off

.LBB0_2292:
	s_add_u32 s8, s12, 0x100
	s_addc_u32 s9, s13, 0
	s_add_i32 s53, 0, 0x10000
	v_add_u32_e32 v140, s53, v196
	ds_read_b128 v[128:131], v140
	ds_read_b128 v[132:135], v140 offset:1024
	ds_read_b128 v[136:139], v140 offset:2048
	ds_read_b128 v[140:143], v140 offset:3072
	s_cmp_eq_u32 s52, 2
	s_cselect_b32 s15, s31, s9
	s_cselect_b32 s14, s30, s8
	s_cselect_b32 s11, s35, s51
	s_cselect_b32 s10, s34, s33
	s_add_i32 m0, s42, 0xc000
	ds_read_b128 v[144:147], v198
	ds_read_b128 v[148:151], v198 offset:1024
	ds_read_b128 v[152:155], v198 offset:2048
	ds_read_b128 v[156:159], v198 offset:3072
	ds_read_b128 v[160:163], v198 offset:4096
	ds_read_b128 v[164:167], v198 offset:5120
	ds_read_b128 v[168:171], v198 offset:6144
	ds_read_b128 v[172:175], v198 offset:7168
	global_load_lds_dwordx4 v190, s[12:13]
	s_add_i32 m0, s42, 0xe000
	s_nop 0
	global_load_lds_dwordx4 v206, s[12:13]
	s_waitcnt lgkmcnt(8)
	s_barrier
	s_waitcnt lgkmcnt(0)
	s_setprio 1
	v_mfma_f32_16x16x32_bf16 v[124:127], v[128:131], v[144:147], v[124:127]
	v_mfma_f32_16x16x32_bf16 v[120:123], v[136:139], v[144:147], v[120:123]
	v_mfma_f32_16x16x32_bf16 v[108:111], v[128:131], v[152:155], v[108:111]
	v_mfma_f32_16x16x32_bf16 v[104:107], v[136:139], v[152:155], v[104:107]
	v_mfma_f32_16x16x32_bf16 v[92:95], v[128:131], v[160:163], v[92:95]
	v_mfma_f32_16x16x32_bf16 v[88:91], v[136:139], v[160:163], v[88:91]
	v_mfma_f32_16x16x32_bf16 v[76:79], v[128:131], v[168:171], v[76:79]
	v_mfma_f32_16x16x32_bf16 v[72:75], v[136:139], v[168:171], v[72:75]
	v_mfma_f32_16x16x32_bf16 v[124:127], v[132:135], v[148:151], v[124:127]
	v_mfma_f32_16x16x32_bf16 v[120:123], v[140:143], v[148:151], v[120:123]
	v_mfma_f32_16x16x32_bf16 v[108:111], v[132:135], v[156:159], v[108:111]
	v_mfma_f32_16x16x32_bf16 v[104:107], v[140:143], v[156:159], v[104:107]
	v_mfma_f32_16x16x32_bf16 v[92:95], v[132:135], v[164:167], v[92:95]
	v_mfma_f32_16x16x32_bf16 v[88:91], v[140:143], v[164:167], v[88:91]
	v_mfma_f32_16x16x32_bf16 v[76:79], v[132:135], v[172:175], v[76:79]
	v_mfma_f32_16x16x32_bf16 v[72:75], v[140:143], v[172:175], v[72:75]
	s_setprio 0
	s_barrier
	s_add_i32 s54, 0, 0x14000
	v_add_u32_e32 v184, s54, v196
	s_add_i32 s12, s53, s41
	ds_read_b128 v[176:179], v184
	ds_read_b128 v[180:183], v184 offset:1024
	ds_read_b128 v[208:211], v184 offset:2048
	ds_read_b128 v[212:215], v184 offset:3072
	s_mov_b32 m0, s12
	s_nop 0
	global_load_lds_dwordx4 v186, s[10:11]
	s_add_i32 m0, s12, 0x2000
	s_nop 0
	global_load_lds_dwordx4 v188, s[10:11]
	s_barrier
	s_waitcnt lgkmcnt(0)
	s_setprio 1
	v_mfma_f32_16x16x32_bf16 v[116:119], v[176:179], v[144:147], v[116:119]
	v_mfma_f32_16x16x32_bf16 v[112:115], v[208:211], v[144:147], v[112:115]
	v_mfma_f32_16x16x32_bf16 v[100:103], v[176:179], v[152:155], v[100:103]
	v_mfma_f32_16x16x32_bf16 v[96:99], v[208:211], v[152:155], v[96:99]
	v_mfma_f32_16x16x32_bf16 v[84:87], v[176:179], v[160:163], v[84:87]
	v_mfma_f32_16x16x32_bf16 v[80:83], v[208:211], v[160:163], v[80:83]
	v_mfma_f32_16x16x32_bf16 v[68:71], v[176:179], v[168:171], v[68:71]
	v_mfma_f32_16x16x32_bf16 v[64:67], v[208:211], v[168:171], v[64:67]
	v_mfma_f32_16x16x32_bf16 v[116:119], v[180:183], v[148:151], v[116:119]
	v_mfma_f32_16x16x32_bf16 v[112:115], v[212:215], v[148:151], v[112:115]
	v_mfma_f32_16x16x32_bf16 v[100:103], v[180:183], v[156:159], v[100:103]
	v_mfma_f32_16x16x32_bf16 v[96:99], v[212:215], v[156:159], v[96:99]
	v_mfma_f32_16x16x32_bf16 v[84:87], v[180:183], v[164:167], v[84:87]
	v_mfma_f32_16x16x32_bf16 v[80:83], v[212:215], v[164:167], v[80:83]
	v_mfma_f32_16x16x32_bf16 v[68:71], v[180:183], v[172:175], v[68:71]
	v_mfma_f32_16x16x32_bf16 v[64:67], v[212:215], v[172:175], v[64:67]
	s_setprio 0
	s_mov_b32 m0, s42
	s_barrier
	ds_read_b128 v[144:147], v198 offset:16384
	ds_read_b128 v[148:151], v198 offset:17408
	ds_read_b128 v[152:155], v198 offset:18432
	ds_read_b128 v[156:159], v198 offset:19456
	ds_read_b128 v[160:163], v198 offset:20480
	ds_read_b128 v[164:167], v198 offset:21504
	ds_read_b128 v[168:171], v198 offset:22528
	ds_read_b128 v[172:175], v198 offset:23552
	global_load_lds_dwordx4 v186, s[14:15]
	s_mov_b32 m0, s43
	s_nop 0
	global_load_lds_dwordx4 v188, s[14:15]
	s_barrier
	s_waitcnt lgkmcnt(0)
	s_setprio 1
	v_mfma_f32_16x16x32_bf16 v[60:63], v[128:131], v[144:147], v[60:63]
	v_mfma_f32_16x16x32_bf16 v[56:59], v[136:139], v[144:147], v[56:59]
	v_mfma_f32_16x16x32_bf16 v[44:47], v[128:131], v[152:155], v[44:47]
	v_mfma_f32_16x16x32_bf16 v[40:43], v[136:139], v[152:155], v[40:43]
	v_mfma_f32_16x16x32_bf16 v[28:31], v[128:131], v[160:163], v[28:31]
	v_mfma_f32_16x16x32_bf16 v[24:27], v[136:139], v[160:163], v[24:27]
	v_mfma_f32_16x16x32_bf16 v[12:15], v[128:131], v[168:171], v[12:15]
	v_mfma_f32_16x16x32_bf16 v[8:11], v[136:139], v[168:171], v[8:11]
	v_mfma_f32_16x16x32_bf16 v[60:63], v[132:135], v[148:151], v[60:63]
	v_mfma_f32_16x16x32_bf16 v[56:59], v[140:143], v[148:151], v[56:59]
	v_mfma_f32_16x16x32_bf16 v[44:47], v[132:135], v[156:159], v[44:47]
	v_mfma_f32_16x16x32_bf16 v[40:43], v[140:143], v[156:159], v[40:43]
	v_mfma_f32_16x16x32_bf16 v[28:31], v[132:135], v[164:167], v[28:31]
	v_mfma_f32_16x16x32_bf16 v[24:27], v[140:143], v[164:167], v[24:27]
	v_mfma_f32_16x16x32_bf16 v[12:15], v[132:135], v[172:175], v[12:15]
	v_mfma_f32_16x16x32_bf16 v[8:11], v[140:143], v[172:175], v[8:11]
	s_setprio 0
	s_barrier
	s_add_u32 s12, s10, 0x18000
	s_addc_u32 s13, s11, 0
	s_add_i32 s53, s54, s41
	s_mov_b32 m0, s53
	s_nop 0
	global_load_lds_dwordx4 v186, s[12:13]
	s_add_i32 m0, s53, 0x2000
	s_nop 0
	global_load_lds_dwordx4 v188, s[12:13]
	s_waitcnt vmcnt(6)
	s_barrier
	s_setprio 1
	v_mfma_f32_16x16x32_bf16 v[52:55], v[176:179], v[144:147], v[52:55]
	v_mfma_f32_16x16x32_bf16 v[48:51], v[208:211], v[144:147], v[48:51]
	v_mfma_f32_16x16x32_bf16 v[36:39], v[176:179], v[152:155], v[36:39]
	v_mfma_f32_16x16x32_bf16 v[32:35], v[208:211], v[152:155], v[32:35]
	v_mfma_f32_16x16x32_bf16 v[20:23], v[176:179], v[160:163], v[20:23]
	v_mfma_f32_16x16x32_bf16 v[16:19], v[208:211], v[160:163], v[16:19]
	v_mfma_f32_16x16x32_bf16 v[4:7], v[176:179], v[168:171], v[4:7]
	v_mfma_f32_16x16x32_bf16 v[0:3], v[208:211], v[168:171], v[0:3]
	v_mfma_f32_16x16x32_bf16 v[52:55], v[180:183], v[148:151], v[52:55]
	v_mfma_f32_16x16x32_bf16 v[48:51], v[212:215], v[148:151], v[48:51]
	v_mfma_f32_16x16x32_bf16 v[36:39], v[180:183], v[156:159], v[36:39]
	v_mfma_f32_16x16x32_bf16 v[32:35], v[212:215], v[156:159], v[32:35]
	v_mfma_f32_16x16x32_bf16 v[20:23], v[180:183], v[164:167], v[20:23]
	v_mfma_f32_16x16x32_bf16 v[16:19], v[212:215], v[164:167], v[16:19]
	v_mfma_f32_16x16x32_bf16 v[4:7], v[180:183], v[172:175], v[4:7]
	v_mfma_f32_16x16x32_bf16 v[0:3], v[212:215], v[172:175], v[0:3]
	s_setprio 0
	s_add_i32 s53, 0, 0x18000
	v_add_u32_e32 v140, s53, v196
	s_barrier
	ds_read_b128 v[128:131], v140
	ds_read_b128 v[132:135], v140 offset:1024
	ds_read_b128 v[136:139], v140 offset:2048
	ds_read_b128 v[140:143], v140 offset:3072
	s_add_u32 s12, s14, 0x18000
	s_addc_u32 s13, s15, 0
	s_mov_b32 m0, s44
	ds_read_b128 v[144:147], v198 offset:32768
	ds_read_b128 v[148:151], v198 offset:33792
	ds_read_b128 v[152:155], v198 offset:34816
	ds_read_b128 v[156:159], v198 offset:35840
	ds_read_b128 v[160:163], v198 offset:36864
	ds_read_b128 v[164:167], v198 offset:37888
	ds_read_b128 v[168:171], v198 offset:38912
	ds_read_b128 v[172:175], v198 offset:39936
	global_load_lds_dwordx4 v186, s[12:13]
	s_mov_b32 m0, s45
	s_nop 0
	global_load_lds_dwordx4 v188, s[12:13]
	s_waitcnt lgkmcnt(8)
	s_barrier
	s_waitcnt lgkmcnt(0)
	s_setprio 1
	v_mfma_f32_16x16x32_bf16 v[124:127], v[128:131], v[144:147], v[124:127]
	v_mfma_f32_16x16x32_bf16 v[120:123], v[136:139], v[144:147], v[120:123]
	v_mfma_f32_16x16x32_bf16 v[108:111], v[128:131], v[152:155], v[108:111]
	v_mfma_f32_16x16x32_bf16 v[104:107], v[136:139], v[152:155], v[104:107]
	v_mfma_f32_16x16x32_bf16 v[92:95], v[128:131], v[160:163], v[92:95]
	v_mfma_f32_16x16x32_bf16 v[88:91], v[136:139], v[160:163], v[88:91]
	v_mfma_f32_16x16x32_bf16 v[76:79], v[128:131], v[168:171], v[76:79]
	v_mfma_f32_16x16x32_bf16 v[72:75], v[136:139], v[168:171], v[72:75]
	v_mfma_f32_16x16x32_bf16 v[124:127], v[132:135], v[148:151], v[124:127]
	v_mfma_f32_16x16x32_bf16 v[120:123], v[140:143], v[148:151], v[120:123]
	v_mfma_f32_16x16x32_bf16 v[108:111], v[132:135], v[156:159], v[108:111]
	v_mfma_f32_16x16x32_bf16 v[104:107], v[140:143], v[156:159], v[104:107]
	v_mfma_f32_16x16x32_bf16 v[92:95], v[132:135], v[164:167], v[92:95]
	v_mfma_f32_16x16x32_bf16 v[88:91], v[140:143], v[164:167], v[88:91]
	v_mfma_f32_16x16x32_bf16 v[76:79], v[132:135], v[172:175], v[76:79]
	v_mfma_f32_16x16x32_bf16 v[72:75], v[140:143], v[172:175], v[72:75]
	s_setprio 0
	s_barrier
	s_add_i32 s12, 0, 0x1c000
	s_add_i32 s13, s53, s41
	v_add_u32_e32 v192, s12, v196
	s_add_u32 s100, s10, 0x80
	s_addc_u32 s101, s11, 0
	s_mov_b32 m0, s13
	ds_read_b128 v[176:179], v192
	ds_read_b128 v[180:183], v192 offset:1024
	ds_read_b128 v[208:211], v192 offset:2048
	ds_read_b128 v[212:215], v192 offset:3072
	global_load_lds_dwordx4 v186, s[100:101]
	s_add_i32 m0, s13, 0x2000
	s_nop 0
	global_load_lds_dwordx4 v188, s[100:101]
	s_barrier
	s_waitcnt lgkmcnt(0)
	s_setprio 1
	v_mfma_f32_16x16x32_bf16 v[116:119], v[176:179], v[144:147], v[116:119]
	v_mfma_f32_16x16x32_bf16 v[112:115], v[208:211], v[144:147], v[112:115]
	v_mfma_f32_16x16x32_bf16 v[100:103], v[176:179], v[152:155], v[100:103]
	v_mfma_f32_16x16x32_bf16 v[96:99], v[208:211], v[152:155], v[96:99]
	v_mfma_f32_16x16x32_bf16 v[84:87], v[176:179], v[160:163], v[84:87]
	v_mfma_f32_16x16x32_bf16 v[80:83], v[208:211], v[160:163], v[80:83]
	v_mfma_f32_16x16x32_bf16 v[68:71], v[176:179], v[168:171], v[68:71]
	v_mfma_f32_16x16x32_bf16 v[64:67], v[208:211], v[168:171], v[64:67]
	v_mfma_f32_16x16x32_bf16 v[116:119], v[180:183], v[148:151], v[116:119]
	v_mfma_f32_16x16x32_bf16 v[112:115], v[212:215], v[148:151], v[112:115]
	v_mfma_f32_16x16x32_bf16 v[100:103], v[180:183], v[156:159], v[100:103]
	v_mfma_f32_16x16x32_bf16 v[96:99], v[212:215], v[156:159], v[96:99]
	v_mfma_f32_16x16x32_bf16 v[84:87], v[180:183], v[164:167], v[84:87]
	v_mfma_f32_16x16x32_bf16 v[80:83], v[212:215], v[164:167], v[80:83]
	v_mfma_f32_16x16x32_bf16 v[68:71], v[180:183], v[172:175], v[68:71]
	v_mfma_f32_16x16x32_bf16 v[64:67], v[212:215], v[172:175], v[64:67]
	s_setprio 0
	s_mov_b32 m0, s46
	s_add_u32 s100, s14, 0x80
	s_addc_u32 s101, s15, 0
	s_barrier
	ds_read_b128 v[144:147], v198 offset:49152
	ds_read_b128 v[148:151], v198 offset:50176
	ds_read_b128 v[152:155], v198 offset:51200
	ds_read_b128 v[156:159], v198 offset:52224
	ds_read_b128 v[160:163], v198 offset:53248
	ds_read_b128 v[164:167], v198 offset:54272
	ds_read_b128 v[168:171], v198 offset:55296
	ds_read_b128 v[172:175], v198 offset:56320
	global_load_lds_dwordx4 v186, s[100:101]
	s_mov_b32 m0, s47
	s_nop 0
	global_load_lds_dwordx4 v188, s[100:101]
	s_barrier
	s_waitcnt lgkmcnt(0)
	s_setprio 1
	v_mfma_f32_16x16x32_bf16 v[60:63], v[128:131], v[144:147], v[60:63]
	v_mfma_f32_16x16x32_bf16 v[56:59], v[136:139], v[144:147], v[56:59]
	v_mfma_f32_16x16x32_bf16 v[44:47], v[128:131], v[152:155], v[44:47]
	v_mfma_f32_16x16x32_bf16 v[40:43], v[136:139], v[152:155], v[40:43]
	v_mfma_f32_16x16x32_bf16 v[28:31], v[128:131], v[160:163], v[28:31]
	v_mfma_f32_16x16x32_bf16 v[24:27], v[136:139], v[160:163], v[24:27]
	v_mfma_f32_16x16x32_bf16 v[12:15], v[128:131], v[168:171], v[12:15]
	v_mfma_f32_16x16x32_bf16 v[8:11], v[136:139], v[168:171], v[8:11]
	v_mfma_f32_16x16x32_bf16 v[60:63], v[132:135], v[148:151], v[60:63]
	v_mfma_f32_16x16x32_bf16 v[56:59], v[140:143], v[148:151], v[56:59]
	v_mfma_f32_16x16x32_bf16 v[44:47], v[132:135], v[156:159], v[44:47]
	v_mfma_f32_16x16x32_bf16 v[40:43], v[140:143], v[156:159], v[40:43]
	v_mfma_f32_16x16x32_bf16 v[28:31], v[132:135], v[164:167], v[28:31]
	v_mfma_f32_16x16x32_bf16 v[24:27], v[140:143], v[164:167], v[24:27]
	v_mfma_f32_16x16x32_bf16 v[12:15], v[132:135], v[172:175], v[12:15]
	v_mfma_f32_16x16x32_bf16 v[8:11], v[140:143], v[172:175], v[8:11]
	s_setprio 0
	s_barrier
	s_add_u32 s10, s10, 0x18080
	s_addc_u32 s11, s11, 0
	s_add_i32 s12, s12, s41
	s_mov_b32 m0, s12
	s_nop 0
	global_load_lds_dwordx4 v186, s[10:11]
	s_add_i32 m0, s12, 0x2000
	s_nop 0
	global_load_lds_dwordx4 v188, s[10:11]
	s_waitcnt vmcnt(6)
	s_barrier
	s_setprio 1
	v_mfma_f32_16x16x32_bf16 v[52:55], v[176:179], v[144:147], v[52:55]
	v_mfma_f32_16x16x32_bf16 v[48:51], v[208:211], v[144:147], v[48:51]
	v_mfma_f32_16x16x32_bf16 v[36:39], v[176:179], v[152:155], v[36:39]
	v_mfma_f32_16x16x32_bf16 v[32:35], v[208:211], v[152:155], v[32:35]
	v_mfma_f32_16x16x32_bf16 v[20:23], v[176:179], v[160:163], v[20:23]
	v_mfma_f32_16x16x32_bf16 v[16:19], v[208:211], v[160:163], v[16:19]
	v_mfma_f32_16x16x32_bf16 v[4:7], v[176:179], v[168:171], v[4:7]
	v_mfma_f32_16x16x32_bf16 v[0:3], v[208:211], v[168:171], v[0:3]
	v_mfma_f32_16x16x32_bf16 v[52:55], v[180:183], v[148:151], v[52:55]
	v_mfma_f32_16x16x32_bf16 v[48:51], v[212:215], v[148:151], v[48:51]
	v_mfma_f32_16x16x32_bf16 v[36:39], v[180:183], v[156:159], v[36:39]
	v_mfma_f32_16x16x32_bf16 v[32:35], v[212:215], v[156:159], v[32:35]
	v_mfma_f32_16x16x32_bf16 v[20:23], v[180:183], v[164:167], v[20:23]
	v_mfma_f32_16x16x32_bf16 v[16:19], v[212:215], v[164:167], v[16:19]
	v_mfma_f32_16x16x32_bf16 v[4:7], v[180:183], v[172:175], v[4:7]
	v_mfma_f32_16x16x32_bf16 v[0:3], v[212:215], v[172:175], v[0:3]
	s_setprio 0
	s_add_i32 s52, s52, 2
	s_add_u32 s33, s33, 0x100
	s_addc_u32 s51, s51, 0
	s_cmp_gt_u32 s52, 3
	s_mov_b64 s[12:13], s[8:9]
	s_barrier
	s_cbranch_scc0 .LBB0_2292
	v_mov_b32_e32 v128, v252
	s_lshl_b32 s1, s1, 8
	v_readfirstlane_b32 s8, v128
	s_ashr_i32 s9, s8, 2
	s_andn2_b32 s9, s9, 63
	s_add_i32 s9, s9, s1
	v_and_or_b32 v208, v128, 15, s9
	v_ashrrev_i32_e32 v209, 31, v208
	v_lshl_add_u64 v[210:211], v[208:209], 2, s[26:27]
	global_load_dword v225, v[210:211], off
	s_lshr_b32 s1, s8, 1
	s_and_b32 s1, s1, 0x60
	s_lshl_b32 s0, s0, 8
	v_lshrrev_b32_e32 v128, 2, v128
	s_or_b32 s0, s1, s0
	s_movk_i32 s1, 0x1fcf
	v_and_b32_e32 v226, 12, v128
	v_and_or_b32 v128, v208, s1, 16
	s_movk_i32 s1, 0x4000
	v_cmp_gt_i32_e32 vcc, s1, v208
	s_mul_hi_i32 s1, s0, 0x2aaaaaab
	s_lshr_b32 s8, s1, 31
	s_lshr_b32 s1, s1, 4
	s_add_i32 s1, s1, s8
	s_mulk_i32 s1, 0x60
	v_add_u32_e32 v129, 0x7ffc000, v208
	s_sub_i32 s1, s0, s1
	v_lshlrev_b32_e32 v199, 1, v226
	v_cndmask_b32_e32 v128, v129, v128, vcc
	s_cmp_eq_u32 s1, 64
	v_lshl_or_b32 v192, v128, 5, v199
	s_cselect_b64 s[10:11], -1, 0
	v_lshl_add_u64 v[128:129], v[192:193], 2, s[28:29]
	v_mov_b32_e32 v160, 0
	s_and_b64 vcc, exec, s[10:11]
	v_mov_b32_e32 v178, 0
	v_mov_b32_e32 v218, 0
	v_mov_b32_e32 v179, 0
	v_mov_b32_e32 v219, 0
	v_mov_b32_e32 v182, 0
	v_mov_b32_e32 v220, 0
	v_mov_b32_e32 v183, 0
	v_mov_b32_e32 v221, 0
	s_cbranch_vccz .LBB0_2295
	global_load_dwordx4 v[178:181], v[128:129], off
	global_load_dwordx4 v[182:185], v[128:129], off offset:16
	s_waitcnt vmcnt(0)
	v_mov_b32_e32 v218, v179
	v_mov_b32_e32 v179, v180
	v_mov_b32_e32 v219, v181
	v_mov_b32_e32 v220, v183
	v_mov_b32_e32 v183, v184
	v_mov_b32_e32 v221, v185

.LBB0_2484:
	s_add_u32 s34, s30, 0xfffe0080
	s_addc_u32 s35, s31, -1
	s_add_i32 s53, 0, 0x10000
	v_add_u32_e32 v140, s53, v196
	ds_read_b128 v[128:131], v140
	ds_read_b128 v[132:135], v140 offset:1024
	ds_read_b128 v[136:139], v140 offset:2048
	ds_read_b128 v[140:143], v140 offset:3072
	s_cmp_eq_u32 s52, 4
	s_cselect_b32 s37, s0, s35
	s_cselect_b32 s36, s1, s34
	s_cselect_b32 s35, s15, s33
	s_cselect_b32 s34, s21, s27
	s_add_i32 m0, s29, 0xc000
	ds_read_b128 v[144:147], v198
	ds_read_b128 v[148:151], v198 offset:1024
	ds_read_b128 v[152:155], v198 offset:2048
	ds_read_b128 v[156:159], v198 offset:3072
	ds_read_b128 v[160:163], v198 offset:4096
	ds_read_b128 v[164:167], v198 offset:5120
	ds_read_b128 v[168:171], v198 offset:6144
	ds_read_b128 v[172:175], v198 offset:7168
	global_load_lds_dwordx4 v212, s[30:31]
	s_add_i32 m0, s29, 0xe000
	s_nop 0
	global_load_lds_dwordx4 v214, s[30:31]
	s_waitcnt lgkmcnt(8)
	s_barrier
	s_waitcnt lgkmcnt(0)
	s_setprio 1
	v_mfma_f32_16x16x32_bf16 v[124:127], v[128:131], v[144:147], v[124:127]
	v_mfma_f32_16x16x32_bf16 v[120:123], v[136:139], v[144:147], v[120:123]
	v_mfma_f32_16x16x32_bf16 v[108:111], v[128:131], v[152:155], v[108:111]
	v_mfma_f32_16x16x32_bf16 v[104:107], v[136:139], v[152:155], v[104:107]
	v_mfma_f32_16x16x32_bf16 v[92:95], v[128:131], v[160:163], v[92:95]
	v_mfma_f32_16x16x32_bf16 v[88:91], v[136:139], v[160:163], v[88:91]
	v_mfma_f32_16x16x32_bf16 v[76:79], v[128:131], v[168:171], v[76:79]
	v_mfma_f32_16x16x32_bf16 v[72:75], v[136:139], v[168:171], v[72:75]
	v_mfma_f32_16x16x32_bf16 v[124:127], v[132:135], v[148:151], v[124:127]
	v_mfma_f32_16x16x32_bf16 v[120:123], v[140:143], v[148:151], v[120:123]
	v_mfma_f32_16x16x32_bf16 v[108:111], v[132:135], v[156:159], v[108:111]
	v_mfma_f32_16x16x32_bf16 v[104:107], v[140:143], v[156:159], v[104:107]
	v_mfma_f32_16x16x32_bf16 v[92:95], v[132:135], v[164:167], v[92:95]
	v_mfma_f32_16x16x32_bf16 v[88:91], v[140:143], v[164:167], v[88:91]
	v_mfma_f32_16x16x32_bf16 v[76:79], v[132:135], v[172:175], v[76:79]
	v_mfma_f32_16x16x32_bf16 v[72:75], v[140:143], v[172:175], v[72:75]
	s_setprio 0
	s_barrier
	s_add_i32 s56, 0, 0x14000
	s_add_i32 s53, s53, s45
	v_add_u32_e32 v188, s56, v196
	s_mov_b32 m0, s53
	ds_read_b128 v[176:179], v188
	ds_read_b128 v[180:183], v188 offset:1024
	ds_read_b128 v[184:187], v188 offset:2048
	ds_read_b128 v[188:191], v188 offset:3072
	global_load_lds_dwordx4 v192, s[34:35]
	s_add_i32 m0, s53, 0x2000
	s_nop 0
	global_load_lds_dwordx4 v210, s[34:35]
	s_barrier
	s_waitcnt lgkmcnt(0)
	s_setprio 1
	v_mfma_f32_16x16x32_bf16 v[116:119], v[176:179], v[144:147], v[116:119]
	v_mfma_f32_16x16x32_bf16 v[112:115], v[184:187], v[144:147], v[112:115]
	v_mfma_f32_16x16x32_bf16 v[100:103], v[176:179], v[152:155], v[100:103]
	v_mfma_f32_16x16x32_bf16 v[96:99], v[184:187], v[152:155], v[96:99]
	v_mfma_f32_16x16x32_bf16 v[84:87], v[176:179], v[160:163], v[84:87]
	v_mfma_f32_16x16x32_bf16 v[80:83], v[184:187], v[160:163], v[80:83]
	v_mfma_f32_16x16x32_bf16 v[68:71], v[176:179], v[168:171], v[68:71]
	v_mfma_f32_16x16x32_bf16 v[64:67], v[184:187], v[168:171], v[64:67]
	v_mfma_f32_16x16x32_bf16 v[116:119], v[180:183], v[148:151], v[116:119]
	v_mfma_f32_16x16x32_bf16 v[112:115], v[188:191], v[148:151], v[112:115]
	v_mfma_f32_16x16x32_bf16 v[100:103], v[180:183], v[156:159], v[100:103]
	v_mfma_f32_16x16x32_bf16 v[96:99], v[188:191], v[156:159], v[96:99]
	v_mfma_f32_16x16x32_bf16 v[84:87], v[180:183], v[164:167], v[84:87]
	v_mfma_f32_16x16x32_bf16 v[80:83], v[188:191], v[164:167], v[80:83]
	v_mfma_f32_16x16x32_bf16 v[68:71], v[180:183], v[172:175], v[68:71]
	v_mfma_f32_16x16x32_bf16 v[64:67], v[188:191], v[172:175], v[64:67]
	s_setprio 0
	s_mov_b32 m0, s29
	s_add_u32 vcc_lo, s36, 0x80
	s_addc_u32 vcc_hi, s37, 0
	s_barrier
	ds_read_b128 v[144:147], v198 offset:16384
	ds_read_b128 v[148:151], v198 offset:17408
	ds_read_b128 v[152:155], v198 offset:18432
	ds_read_b128 v[156:159], v198 offset:19456
	ds_read_b128 v[160:163], v198 offset:20480
	ds_read_b128 v[164:167], v198 offset:21504
	ds_read_b128 v[168:171], v198 offset:22528
	ds_read_b128 v[172:175], v198 offset:23552
	global_load_lds_dwordx4 v206, s[36:37]
	s_mov_b32 m0, s46
	s_nop 0
	global_load_lds_dwordx4 v208, s[36:37]
	s_barrier
	s_waitcnt lgkmcnt(0)
	s_setprio 1
	v_mfma_f32_16x16x32_bf16 v[60:63], v[128:131], v[144:147], v[60:63]
	v_mfma_f32_16x16x32_bf16 v[56:59], v[136:139], v[144:147], v[56:59]
	v_mfma_f32_16x16x32_bf16 v[44:47], v[128:131], v[152:155], v[44:47]
	v_mfma_f32_16x16x32_bf16 v[40:43], v[136:139], v[152:155], v[40:43]
	v_mfma_f32_16x16x32_bf16 v[28:31], v[128:131], v[160:163], v[28:31]
	v_mfma_f32_16x16x32_bf16 v[24:27], v[136:139], v[160:163], v[24:27]
	v_mfma_f32_16x16x32_bf16 v[12:15], v[128:131], v[168:171], v[12:15]
	v_mfma_f32_16x16x32_bf16 v[8:11], v[136:139], v[168:171], v[8:11]
	v_mfma_f32_16x16x32_bf16 v[60:63], v[132:135], v[148:151], v[60:63]
	v_mfma_f32_16x16x32_bf16 v[56:59], v[140:143], v[148:151], v[56:59]
	v_mfma_f32_16x16x32_bf16 v[44:47], v[132:135], v[156:159], v[44:47]
	v_mfma_f32_16x16x32_bf16 v[40:43], v[140:143], v[156:159], v[40:43]
	v_mfma_f32_16x16x32_bf16 v[28:31], v[132:135], v[164:167], v[28:31]
	v_mfma_f32_16x16x32_bf16 v[24:27], v[140:143], v[164:167], v[24:27]
	v_mfma_f32_16x16x32_bf16 v[12:15], v[132:135], v[172:175], v[12:15]
	v_mfma_f32_16x16x32_bf16 v[8:11], v[140:143], v[172:175], v[8:11]
	s_setprio 0
	s_barrier
	s_add_u32 s54, s34, 0x20000
	s_addc_u32 s55, s35, 0
	s_add_i32 s53, s56, s45
	s_mov_b32 m0, s53
	s_nop 0
	global_load_lds_dwordx4 v192, s[54:55]
	s_add_i32 m0, s53, 0x2000
	s_nop 0
	global_load_lds_dwordx4 v210, s[54:55]
	s_waitcnt vmcnt(6)
	s_barrier
	s_setprio 1
	v_mfma_f32_16x16x32_bf16 v[52:55], v[176:179], v[144:147], v[52:55]
	v_mfma_f32_16x16x32_bf16 v[48:51], v[184:187], v[144:147], v[48:51]
	v_mfma_f32_16x16x32_bf16 v[36:39], v[176:179], v[152:155], v[36:39]
	v_mfma_f32_16x16x32_bf16 v[32:35], v[184:187], v[152:155], v[32:35]
	v_mfma_f32_16x16x32_bf16 v[20:23], v[176:179], v[160:163], v[20:23]
	v_mfma_f32_16x16x32_bf16 v[16:19], v[184:187], v[160:163], v[16:19]
	v_mfma_f32_16x16x32_bf16 v[4:7], v[176:179], v[168:171], v[4:7]
	v_mfma_f32_16x16x32_bf16 v[0:3], v[184:187], v[168:171], v[0:3]
	v_mfma_f32_16x16x32_bf16 v[52:55], v[180:183], v[148:151], v[52:55]
	v_mfma_f32_16x16x32_bf16 v[48:51], v[188:191], v[148:151], v[48:51]
	v_mfma_f32_16x16x32_bf16 v[36:39], v[180:183], v[156:159], v[36:39]
	v_mfma_f32_16x16x32_bf16 v[32:35], v[188:191], v[156:159], v[32:35]
	v_mfma_f32_16x16x32_bf16 v[20:23], v[180:183], v[164:167], v[20:23]
	v_mfma_f32_16x16x32_bf16 v[16:19], v[188:191], v[164:167], v[16:19]
	v_mfma_f32_16x16x32_bf16 v[4:7], v[180:183], v[172:175], v[4:7]
	v_mfma_f32_16x16x32_bf16 v[0:3], v[188:191], v[172:175], v[0:3]
	s_setprio 0
	s_add_i32 s53, 0, 0x18000
	v_add_u32_e32 v140, s53, v196
	s_barrier
	ds_read_b128 v[128:131], v140
	ds_read_b128 v[132:135], v140 offset:1024
	ds_read_b128 v[136:139], v140 offset:2048
	ds_read_b128 v[140:143], v140 offset:3072
	s_add_u32 s36, s36, 0x20000
	s_addc_u32 s37, s37, 0
	s_mov_b32 m0, s47
	ds_read_b128 v[144:147], v198 offset:32768
	ds_read_b128 v[148:151], v198 offset:33792
	ds_read_b128 v[152:155], v198 offset:34816
	ds_read_b128 v[156:159], v198 offset:35840
	ds_read_b128 v[160:163], v198 offset:36864
	ds_read_b128 v[164:167], v198 offset:37888
	ds_read_b128 v[168:171], v198 offset:38912
	ds_read_b128 v[172:175], v198 offset:39936
	global_load_lds_dwordx4 v206, s[36:37]
	s_mov_b32 m0, s48
	s_nop 0
	global_load_lds_dwordx4 v208, s[36:37]
	s_waitcnt lgkmcnt(8)
	s_barrier
	s_waitcnt lgkmcnt(0)
	s_setprio 1
	v_mfma_f32_16x16x32_bf16 v[124:127], v[128:131], v[144:147], v[124:127]
	v_mfma_f32_16x16x32_bf16 v[120:123], v[136:139], v[144:147], v[120:123]
	v_mfma_f32_16x16x32_bf16 v[108:111], v[128:131], v[152:155], v[108:111]
	v_mfma_f32_16x16x32_bf16 v[104:107], v[136:139], v[152:155], v[104:107]
	v_mfma_f32_16x16x32_bf16 v[92:95], v[128:131], v[160:163], v[92:95]
	v_mfma_f32_16x16x32_bf16 v[88:91], v[136:139], v[160:163], v[88:91]
	v_mfma_f32_16x16x32_bf16 v[76:79], v[128:131], v[168:171], v[76:79]
	v_mfma_f32_16x16x32_bf16 v[72:75], v[136:139], v[168:171], v[72:75]
	v_mfma_f32_16x16x32_bf16 v[124:127], v[132:135], v[148:151], v[124:127]
	v_mfma_f32_16x16x32_bf16 v[120:123], v[140:143], v[148:151], v[120:123]
	v_mfma_f32_16x16x32_bf16 v[108:111], v[132:135], v[156:159], v[108:111]
	v_mfma_f32_16x16x32_bf16 v[104:107], v[140:143], v[156:159], v[104:107]
	v_mfma_f32_16x16x32_bf16 v[92:95], v[132:135], v[164:167], v[92:95]
	v_mfma_f32_16x16x32_bf16 v[88:91], v[140:143], v[164:167], v[88:91]
	v_mfma_f32_16x16x32_bf16 v[76:79], v[132:135], v[172:175], v[76:79]
	v_mfma_f32_16x16x32_bf16 v[72:75], v[140:143], v[172:175], v[72:75]
	s_setprio 0
	s_barrier
	s_add_i32 s36, 0, 0x1c000
	s_add_i32 s37, s53, s45
	v_add_u32_e32 v188, s36, v196
	s_add_u32 s100, s34, 0x80
	s_addc_u32 s101, s35, 0
	s_mov_b32 m0, s37
	ds_read_b128 v[176:179], v188
	ds_read_b128 v[180:183], v188 offset:1024
	ds_read_b128 v[184:187], v188 offset:2048
	ds_read_b128 v[188:191], v188 offset:3072
	global_load_lds_dwordx4 v192, s[100:101]
	s_add_i32 m0, s37, 0x2000
	s_nop 0
	global_load_lds_dwordx4 v210, s[100:101]
	s_barrier
	s_waitcnt lgkmcnt(0)
	s_setprio 1
	v_mfma_f32_16x16x32_bf16 v[116:119], v[176:179], v[144:147], v[116:119]
	v_mfma_f32_16x16x32_bf16 v[112:115], v[184:187], v[144:147], v[112:115]
	v_mfma_f32_16x16x32_bf16 v[100:103], v[176:179], v[152:155], v[100:103]
	v_mfma_f32_16x16x32_bf16 v[96:99], v[184:187], v[152:155], v[96:99]
	v_mfma_f32_16x16x32_bf16 v[84:87], v[176:179], v[160:163], v[84:87]
	v_mfma_f32_16x16x32_bf16 v[80:83], v[184:187], v[160:163], v[80:83]
	v_mfma_f32_16x16x32_bf16 v[68:71], v[176:179], v[168:171], v[68:71]
	v_mfma_f32_16x16x32_bf16 v[64:67], v[184:187], v[168:171], v[64:67]
	v_mfma_f32_16x16x32_bf16 v[116:119], v[180:183], v[148:151], v[116:119]
	v_mfma_f32_16x16x32_bf16 v[112:115], v[188:191], v[148:151], v[112:115]
	v_mfma_f32_16x16x32_bf16 v[100:103], v[180:183], v[156:159], v[100:103]
	v_mfma_f32_16x16x32_bf16 v[96:99], v[188:191], v[156:159], v[96:99]
	v_mfma_f32_16x16x32_bf16 v[84:87], v[180:183], v[164:167], v[84:87]
	v_mfma_f32_16x16x32_bf16 v[80:83], v[188:191], v[164:167], v[80:83]
	v_mfma_f32_16x16x32_bf16 v[68:71], v[180:183], v[172:175], v[68:71]
	v_mfma_f32_16x16x32_bf16 v[64:67], v[188:191], v[172:175], v[64:67]
	s_setprio 0
	s_mov_b32 m0, s49
	s_barrier
	ds_read_b128 v[144:147], v198 offset:49152
	ds_read_b128 v[148:151], v198 offset:50176
	ds_read_b128 v[152:155], v198 offset:51200
	ds_read_b128 v[156:159], v198 offset:52224
	ds_read_b128 v[160:163], v198 offset:53248
	ds_read_b128 v[164:167], v198 offset:54272
	ds_read_b128 v[168:171], v198 offset:55296
	ds_read_b128 v[172:175], v198 offset:56320
	global_load_lds_dwordx4 v206, vcc
	s_mov_b32 m0, s50
	s_nop 0
	global_load_lds_dwordx4 v208, vcc
	s_barrier
	s_waitcnt lgkmcnt(0)
	s_setprio 1
	v_mfma_f32_16x16x32_bf16 v[60:63], v[128:131], v[144:147], v[60:63]
	v_mfma_f32_16x16x32_bf16 v[56:59], v[136:139], v[144:147], v[56:59]
	v_mfma_f32_16x16x32_bf16 v[44:47], v[128:131], v[152:155], v[44:47]
	v_mfma_f32_16x16x32_bf16 v[40:43], v[136:139], v[152:155], v[40:43]
	v_mfma_f32_16x16x32_bf16 v[28:31], v[128:131], v[160:163], v[28:31]
	v_mfma_f32_16x16x32_bf16 v[24:27], v[136:139], v[160:163], v[24:27]
	v_mfma_f32_16x16x32_bf16 v[12:15], v[128:131], v[168:171], v[12:15]
	v_mfma_f32_16x16x32_bf16 v[8:11], v[136:139], v[168:171], v[8:11]
	v_mfma_f32_16x16x32_bf16 v[60:63], v[132:135], v[148:151], v[60:63]
	v_mfma_f32_16x16x32_bf16 v[56:59], v[140:143], v[148:151], v[56:59]
	v_mfma_f32_16x16x32_bf16 v[44:47], v[132:135], v[156:159], v[44:47]
	v_mfma_f32_16x16x32_bf16 v[40:43], v[140:143], v[156:159], v[40:43]
	v_mfma_f32_16x16x32_bf16 v[28:31], v[132:135], v[164:167], v[28:31]
	v_mfma_f32_16x16x32_bf16 v[24:27], v[140:143], v[164:167], v[24:27]
	v_mfma_f32_16x16x32_bf16 v[12:15], v[132:135], v[172:175], v[12:15]
	v_mfma_f32_16x16x32_bf16 v[8:11], v[140:143], v[172:175], v[8:11]
	s_setprio 0
	s_barrier
	s_add_u32 s34, s34, 0x20080
	s_addc_u32 s35, s35, 0
	s_add_i32 s36, s36, s45
	s_mov_b32 m0, s36
	s_nop 0
	global_load_lds_dwordx4 v192, s[34:35]
	s_add_i32 m0, s36, 0x2000
	s_nop 0
	global_load_lds_dwordx4 v210, s[34:35]
	s_waitcnt vmcnt(6)
	s_barrier
	s_setprio 1
	v_mfma_f32_16x16x32_bf16 v[52:55], v[176:179], v[144:147], v[52:55]
	v_mfma_f32_16x16x32_bf16 v[48:51], v[184:187], v[144:147], v[48:51]
	v_mfma_f32_16x16x32_bf16 v[36:39], v[176:179], v[152:155], v[36:39]
	v_mfma_f32_16x16x32_bf16 v[32:35], v[184:187], v[152:155], v[32:35]
	v_mfma_f32_16x16x32_bf16 v[20:23], v[176:179], v[160:163], v[20:23]
	v_mfma_f32_16x16x32_bf16 v[16:19], v[184:187], v[160:163], v[16:19]
	v_mfma_f32_16x16x32_bf16 v[4:7], v[176:179], v[168:171], v[4:7]
	v_mfma_f32_16x16x32_bf16 v[0:3], v[184:187], v[168:171], v[0:3]
	v_mfma_f32_16x16x32_bf16 v[52:55], v[180:183], v[148:151], v[52:55]
	v_mfma_f32_16x16x32_bf16 v[48:51], v[188:191], v[148:151], v[48:51]
	v_mfma_f32_16x16x32_bf16 v[36:39], v[180:183], v[156:159], v[36:39]
	v_mfma_f32_16x16x32_bf16 v[32:35], v[188:191], v[156:159], v[32:35]
	v_mfma_f32_16x16x32_bf16 v[20:23], v[180:183], v[164:167], v[20:23]
	v_mfma_f32_16x16x32_bf16 v[16:19], v[188:191], v[164:167], v[16:19]
	v_mfma_f32_16x16x32_bf16 v[4:7], v[180:183], v[172:175], v[4:7]
	v_mfma_f32_16x16x32_bf16 v[0:3], v[188:191], v[172:175], v[0:3]
	s_setprio 0
	s_add_i32 s52, s52, 2
	s_add_u32 s30, s30, 0x100
	s_addc_u32 s31, s31, 0
	s_add_u32 s27, s27, 0x100
	s_addc_u32 s33, s33, 0
	s_cmp_gt_u32 s52, 5
	s_barrier
	s_cbranch_scc0 .LBB0_2484
	v_mov_b32_e32 v128, v252
	s_lshl_b32 s1, s28, 8
	v_readfirstlane_b32 s0, v128
	s_ashr_i32 s15, s0, 2
	s_andn2_b32 s15, s15, 63
	s_lshr_b32 s0, s0, 1
	s_add_i32 s15, s15, s1
	s_and_b32 s0, s0, 0x60
	s_lshl_b32 s1, s26, 8
	v_and_or_b32 v218, v128, 15, s15
	v_lshrrev_b32_e32 v128, 1, v128
	s_or_b32 s0, s0, s1
	v_and_b32_e32 v129, 64, v195
	v_and_or_b32 v216, v128, 24, s0
	v_xor_b32_e32 v128, 16, v195
	v_add_u32_e32 v129, 64, v129
	v_cmp_lt_i32_e32 vcc, v128, v129
	v_ashrrev_i32_e32 v219, 31, v218
	v_ashrrev_i32_e32 v217, 31, v216
	v_cndmask_b32_e32 v128, v195, v128, vcc
	v_lshlrev_b32_e32 v200, 2, v128
	v_xor_b32_e32 v128, 32, v195
	v_cmp_lt_i32_e32 vcc, v128, v129
	v_or_b32_e32 v220, 0x80, v216
	v_ashrrev_i32_e32 v221, 31, v220
	v_cndmask_b32_e32 v128, v195, v128, vcc
	v_lshlrev_b32_e32 v199, 2, v128
	v_lshlrev_b64 v[128:129], 10, v[218:219]
	v_lshl_add_u64 v[130:131], v[128:129], 0, v[216:217]
	v_lshlrev_b64 v[130:131], 1, v[130:131]
	v_lshl_add_u64 v[246:247], s[8:9], 0, v[130:131]
	v_lshl_add_u64 v[250:251], s[10:11], 0, v[130:131]
	global_load_dwordx4 v[188:191], v[246:247], off
	global_load_dwordx4 v[180:183], v[246:247], off offset:256
	global_load_dwordx4 v[184:187], v[250:251], off
	v_or_b32_e32 v242, 16, v218
	v_lshl_add_u64 v[128:129], v[128:129], 0, v[220:221]
	v_ashrrev_i32_e32 v243, 31, v242
	v_lshl_add_u64 v[248:249], v[128:129], 1, s[10:11]
	v_lshlrev_b64 v[128:129], 10, v[242:243]
	v_or_b32_e32 v234, 32, v218
	v_lshl_add_u64 v[130:131], v[128:129], 0, v[216:217]
	v_lshl_add_u64 v[128:129], v[128:129], 0, v[220:221]
	v_ashrrev_i32_e32 v235, 31, v234
	v_lshlrev_b64 v[130:131], 1, v[130:131]
	v_lshl_add_u64 v[240:241], v[128:129], 1, s[10:11]
	v_lshlrev_b64 v[128:129], 10, v[234:235]
	v_or_b32_e32 v226, 48, v218
	v_lshl_add_u64 v[238:239], s[8:9], 0, v[130:131]
	v_lshl_add_u64 v[244:245], s[10:11], 0, v[130:131]
	v_lshl_add_u64 v[130:131], v[128:129], 0, v[216:217]
	v_lshl_add_u64 v[128:129], v[128:129], 0, v[220:221]
	v_ashrrev_i32_e32 v227, 31, v226
	v_lshlrev_b64 v[130:131], 1, v[130:131]
	v_lshl_add_u64 v[232:233], v[128:129], 1, s[10:11]
	v_lshlrev_b64 v[128:129], 10, v[226:227]
	v_lshl_add_u64 v[228:229], s[8:9], 0, v[130:131]
	v_lshl_add_u64 v[236:237], s[10:11], 0, v[130:131]
	v_lshl_add_u64 v[130:131], v[128:129], 0, v[216:217]
	v_lshlrev_b64 v[130:131], 1, v[130:131]
	v_lshl_add_u64 v[132:133], v[128:129], 0, v[220:221]
	v_lshl_add_u64 v[222:223], s[8:9], 0, v[130:131]
	v_lshl_add_u64 v[230:231], s[10:11], 0, v[130:131]
	v_lshl_add_u64 v[224:225], v[132:133], 1, s[10:11]
	global_load_dwordx4 v[176:179], v[248:249], off
	global_load_dwordx4 v[172:175], v[238:239], off
	global_load_dwordx4 v[164:167], v[238:239], off offset:256
	global_load_dwordx4 v[168:171], v[244:245], off
	global_load_dwordx4 v[160:163], v[240:241], off
	global_load_dwordx4 v[156:159], v[228:229], off
	global_load_dwordx4 v[132:135], v[224:225], off
	global_load_dwordx4 v[152:155], v[236:237], off
	global_load_dwordx4 v[144:147], v[232:233], off
	global_load_dwordx4 v[148:151], v[228:229], off offset:256
	global_load_dwordx4 v[136:139], v[230:231], off
	global_load_dwordx4 v[140:143], v[222:223], off
	global_load_dwordx4 v[128:131], v[222:223], off offset:256
	v_cmp_gt_u32_e32 vcc, 16, v195
	s_waitcnt vmcnt(0)
	v_lshlrev_b32_e32 v202, 16, v188
	v_and_b32_e32 v203, 0xffff0000, v188
	v_lshlrev_b32_e32 v204, 16, v184
	v_and_b32_e32 v205, 0xffff0000, v184
	v_lshlrev_b32_e32 v188, 16, v189
	v_and_b32_e32 v189, 0xffff0000, v189
	v_lshlrev_b32_e32 v184, 16, v185
	v_and_b32_e32 v185, 0xffff0000, v185
	v_pk_add_f32 v[202:203], v[202:203], v[204:205]
	v_pk_add_f32 v[184:185], v[188:189], v[184:185]
	v_pk_add_f32 v[188:189], v[124:125], v[202:203]
	v_pk_add_f32 v[184:185], v[126:127], v[184:185]
	v_lshlrev_b32_e32 v124, 16, v190
	v_and_b32_e32 v125, 0xffff0000, v190
	v_lshlrev_b32_e32 v126, 16, v186
	v_and_b32_e32 v127, 0xffff0000, v186
	v_pk_add_f32 v[124:125], v[124:125], v[126:127]
	v_lshlrev_b32_e32 v126, 16, v191
	v_and_b32_e32 v127, 0xffff0000, v191
	v_lshlrev_b32_e32 v186, 16, v187
	v_and_b32_e32 v187, 0xffff0000, v187
	v_pk_add_f32 v[126:127], v[126:127], v[186:187]
	v_pk_add_f32 v[190:191], v[120:121], v[124:125]
	v_cvt_pk_bf16_f32 v120, v188, v189
	v_pk_add_f32 v[186:187], v[122:123], v[126:127]
	v_and_b32_e32 v123, 0xffff0000, v120
	v_lshlrev_b32_e32 v122, 16, v120
	v_pk_add_f32 v[122:123], v[188:189], v[122:123] neg_lo:[0,1] neg_hi:[0,1]
	v_cvt_pk_bf16_f32 v121, v184, v185
	v_cvt_pk_bf16_f32 v124, v122, v123
	v_and_b32_e32 v123, 0xffff0000, v121
	v_lshlrev_b32_e32 v122, 16, v121
	v_pk_add_f32 v[122:123], v[184:185], v[122:123] neg_lo:[0,1] neg_hi:[0,1]
	s_nop 0
	v_cvt_pk_bf16_f32 v125, v122, v123
	v_cvt_pk_bf16_f32 v122, v190, v191
	v_cvt_pk_bf16_f32 v123, v186, v187
	v_and_b32_e32 v127, 0xffff0000, v122
	v_lshlrev_b32_e32 v126, 16, v122
	v_and_b32_e32 v203, 0xffff0000, v123
	v_lshlrev_b32_e32 v202, 16, v123
	v_pk_add_f32 v[126:127], v[190:191], v[126:127] neg_lo:[0,1] neg_hi:[0,1]
	v_pk_add_f32 v[202:203], v[186:187], v[202:203] neg_lo:[0,1] neg_hi:[0,1]
	v_cvt_pk_bf16_f32 v126, v126, v127
	v_cvt_pk_bf16_f32 v127, v202, v203
	global_store_dwordx4 v[246:247], v[120:123], off
	global_store_dwordx4 v[250:251], v[124:127], off
	s_nop 0
	v_pk_mul_f32 v[122:123], v[190:191], v[190:191]
	v_pk_mul_f32 v[120:121], v[186:187], v[186:187]
	v_pk_fma_f32 v[122:123], v[188:189], v[188:189], v[122:123]
	v_pk_fma_f32 v[120:121], v[184:185], v[184:185], v[120:121]
	v_add_f32_e32 v122, v122, v123
	v_add_f32_e32 v120, v120, v122
	v_add_f32_e32 v120, v121, v120
	ds_bpermute_b32 v121, v200, v120
	s_waitcnt lgkmcnt(0)
	v_add_f32_e32 v122, v120, v121
	ds_bpermute_b32 v123, v199, v122
	v_lshl_add_u64 v[120:121], v[218:219], 2, s[12:13]
	s_and_saveexec_b64 s[26:27], vcc
	s_cbranch_execz .LBB0_2487
	s_waitcnt lgkmcnt(0)
	v_add_f32_e32 v122, v122, v123
	global_atomic_add_f32 v[120:121], v122, off

.LBB0_2698:
	s_add_u32 s23, s28, s36
	s_addc_u32 s33, s29, s37
	s_add_u32 s40, s23, 0x100
	s_addc_u32 s41, s33, 0
	s_and_b64 s[38:39], s[34:35], exec
	s_cselect_b32 s41, s0, s41
	s_cselect_b32 s40, s1, s40
	s_add_u32 s36, s26, s36
	s_addc_u32 s37, s27, s37
	s_add_u32 s36, s36, 0x100
	s_addc_u32 s37, s37, 0
	s_add_i32 s62, 0, 0x10000
	s_and_b64 s[34:35], s[34:35], exec
	s_cselect_b32 s43, s15, s37
	s_cselect_b32 s42, s17, s36
	s_add_u32 s44, s23, 0x40080
	s_addc_u32 s45, s33, 0
	s_add_i32 s66, s62, s51
	s_add_i32 m0, s25, 0xc000
	s_add_i32 s67, s25, 0xe000
	s_add_i32 s65, 0, 0x14000
	s_add_i32 s64, s66, 0x2000
	s_add_u32 s38, s42, 0x10000
	v_add_u32_e32 v60, s62, v208
	s_addc_u32 s39, s43, 0
	s_add_i32 s61, s65, s51
	ds_read_b128 v[40:43], v60
	ds_read_b128 v[44:47], v60 offset:1024
	ds_read_b128 v[56:59], v60 offset:2048
	ds_read_b128 v[60:63], v60 offset:3072
	s_add_i32 s60, s61, 0x2000
	s_add_i32 s59, 0, 0x18000
	s_add_u32 s36, s40, 0x40000
	s_addc_u32 s37, s41, 0
	s_add_i32 s58, s59, s51
	s_add_i32 s33, 0, 0x1c000
	s_add_i32 s23, s58, 0x2000
	s_add_u32 s34, s42, 0x10080
	s_addc_u32 s35, s43, 0
	s_add_i32 s63, s33, s51
	s_add_i32 s62, s63, 0x2000
	v_lshl_add_u64 v[182:183], s[44:45], 0, v[168:169]
	ds_read_b128 v[144:147], v209
	ds_read_b128 v[148:151], v209 offset:1024
	ds_read_b128 v[152:155], v209 offset:2048
	ds_read_b128 v[156:159], v209 offset:3072
	ds_read_b128 v[160:163], v209 offset:4096
	ds_read_b128 v[164:167], v209 offset:5120
	ds_read_b128 v[174:177], v209 offset:6144
	ds_read_b128 v[178:181], v209 offset:7168
	global_load_lds_dwordx4 v[182:183], off
	v_lshl_add_u64 v[182:183], s[44:45], 0, v[170:171]
	s_mov_b32 m0, s67
	s_nop 0
	global_load_lds_dwordx4 v[182:183], off
	s_waitcnt lgkmcnt(8)
	s_barrier
	s_waitcnt lgkmcnt(0)
	s_setprio 1
	v_mfma_f32_16x16x32_bf16 v[140:143], v[40:43], v[144:147], v[140:143]
	v_mfma_f32_16x16x32_bf16 v[136:139], v[56:59], v[144:147], v[136:139]
	v_mfma_f32_16x16x32_bf16 v[124:127], v[40:43], v[152:155], v[124:127]
	v_mfma_f32_16x16x32_bf16 v[120:123], v[56:59], v[152:155], v[120:123]
	v_mfma_f32_16x16x32_bf16 v[108:111], v[40:43], v[160:163], v[108:111]
	v_mfma_f32_16x16x32_bf16 v[104:107], v[56:59], v[160:163], v[104:107]
	v_mfma_f32_16x16x32_bf16 v[92:95], v[40:43], v[174:177], v[92:95]
	v_mfma_f32_16x16x32_bf16 v[88:91], v[56:59], v[174:177], v[88:91]
	v_mfma_f32_16x16x32_bf16 v[140:143], v[44:47], v[148:151], v[140:143]
	v_mfma_f32_16x16x32_bf16 v[136:139], v[60:63], v[148:151], v[136:139]
	v_mfma_f32_16x16x32_bf16 v[124:127], v[44:47], v[156:159], v[124:127]
	v_mfma_f32_16x16x32_bf16 v[120:123], v[60:63], v[156:159], v[120:123]
	v_mfma_f32_16x16x32_bf16 v[108:111], v[44:47], v[164:167], v[108:111]
	v_mfma_f32_16x16x32_bf16 v[104:107], v[60:63], v[164:167], v[104:107]
	v_mfma_f32_16x16x32_bf16 v[92:95], v[44:47], v[178:181], v[92:95]
	v_mfma_f32_16x16x32_bf16 v[88:91], v[60:63], v[178:181], v[88:91]
	s_setprio 0
	s_barrier
	v_add_u32_e32 v190, s65, v208
	s_mov_b32 m0, s66
	ds_read_b128 v[182:185], v190
	ds_read_b128 v[186:189], v190 offset:1024
	ds_read_b128 v[198:201], v190 offset:2048
	ds_read_b128 v[210:213], v190 offset:3072
	v_lshl_add_u64 v[190:191], s[42:43], 0, v[192:193]
	global_load_lds_dwordx4 v[190:191], off
	v_lshl_add_u64 v[206:207], s[42:43], 0, v[172:173]
	s_mov_b32 m0, s64
	s_nop 0
	global_load_lds_dwordx4 v[206:207], off
	s_barrier
	s_waitcnt lgkmcnt(0)
	s_setprio 1
	v_mfma_f32_16x16x32_bf16 v[132:135], v[182:185], v[144:147], v[132:135]
	v_mfma_f32_16x16x32_bf16 v[128:131], v[198:201], v[144:147], v[128:131]
	v_mfma_f32_16x16x32_bf16 v[116:119], v[182:185], v[152:155], v[116:119]
	v_mfma_f32_16x16x32_bf16 v[112:115], v[198:201], v[152:155], v[112:115]
	v_mfma_f32_16x16x32_bf16 v[100:103], v[182:185], v[160:163], v[100:103]
	v_mfma_f32_16x16x32_bf16 v[96:99], v[198:201], v[160:163], v[96:99]
	v_mfma_f32_16x16x32_bf16 v[84:87], v[182:185], v[174:177], v[84:87]
	v_mfma_f32_16x16x32_bf16 v[80:83], v[198:201], v[174:177], v[80:83]
	v_mfma_f32_16x16x32_bf16 v[132:135], v[186:189], v[148:151], v[132:135]
	v_mfma_f32_16x16x32_bf16 v[128:131], v[210:213], v[148:151], v[128:131]
	v_mfma_f32_16x16x32_bf16 v[116:119], v[186:189], v[156:159], v[116:119]
	v_mfma_f32_16x16x32_bf16 v[112:115], v[210:213], v[156:159], v[112:115]
	v_mfma_f32_16x16x32_bf16 v[100:103], v[186:189], v[164:167], v[100:103]
	v_mfma_f32_16x16x32_bf16 v[96:99], v[210:213], v[164:167], v[96:99]
	v_mfma_f32_16x16x32_bf16 v[84:87], v[186:189], v[178:181], v[84:87]
	v_mfma_f32_16x16x32_bf16 v[80:83], v[210:213], v[178:181], v[80:83]
	s_setprio 0
	s_mov_b32 m0, s25
	v_lshl_add_u64 v[214:215], s[40:41], 0, v[168:169]
	s_barrier
	ds_read_b128 v[144:147], v209 offset:16384
	ds_read_b128 v[148:151], v209 offset:17408
	ds_read_b128 v[152:155], v209 offset:18432
	ds_read_b128 v[156:159], v209 offset:19456
	ds_read_b128 v[160:163], v209 offset:20480
	ds_read_b128 v[164:167], v209 offset:21504
	ds_read_b128 v[174:177], v209 offset:22528
	ds_read_b128 v[178:181], v209 offset:23552
	global_load_lds_dwordx4 v[214:215], off
	v_lshl_add_u64 v[216:217], s[40:41], 0, v[170:171]
	s_mov_b32 m0, s52
	s_nop 0
	global_load_lds_dwordx4 v[216:217], off
	s_barrier
	s_waitcnt lgkmcnt(0)
	s_setprio 1
	v_mfma_f32_16x16x32_bf16 v[76:79], v[40:43], v[144:147], v[76:79]
	v_mfma_f32_16x16x32_bf16 v[72:75], v[56:59], v[144:147], v[72:75]
	v_mfma_f32_16x16x32_bf16 v[52:55], v[40:43], v[152:155], v[52:55]
	v_mfma_f32_16x16x32_bf16 v[48:51], v[56:59], v[152:155], v[48:51]
	v_mfma_f32_16x16x32_bf16 v[28:31], v[40:43], v[160:163], v[28:31]
	v_mfma_f32_16x16x32_bf16 v[24:27], v[56:59], v[160:163], v[24:27]
	v_mfma_f32_16x16x32_bf16 v[12:15], v[40:43], v[174:177], v[12:15]
	v_mfma_f32_16x16x32_bf16 v[8:11], v[56:59], v[174:177], v[8:11]
	v_mfma_f32_16x16x32_bf16 v[76:79], v[44:47], v[148:151], v[76:79]
	v_mfma_f32_16x16x32_bf16 v[72:75], v[60:63], v[148:151], v[72:75]
	v_mfma_f32_16x16x32_bf16 v[52:55], v[44:47], v[156:159], v[52:55]
	v_mfma_f32_16x16x32_bf16 v[48:51], v[60:63], v[156:159], v[48:51]
	v_mfma_f32_16x16x32_bf16 v[28:31], v[44:47], v[164:167], v[28:31]
	v_mfma_f32_16x16x32_bf16 v[24:27], v[60:63], v[164:167], v[24:27]
	v_mfma_f32_16x16x32_bf16 v[12:15], v[44:47], v[178:181], v[12:15]
	v_mfma_f32_16x16x32_bf16 v[8:11], v[60:63], v[178:181], v[8:11]
	s_setprio 0
	s_barrier
	s_mov_b32 m0, s61
	v_lshl_add_u64 v[40:41], s[38:39], 0, v[192:193]
	global_load_lds_dwordx4 v[40:41], off
	v_lshl_add_u64 v[40:41], s[38:39], 0, v[172:173]
	s_mov_b32 m0, s60
	s_nop 0
	global_load_lds_dwordx4 v[40:41], off
	s_waitcnt vmcnt(6)
	s_barrier
	s_setprio 1
	v_mfma_f32_16x16x32_bf16 v[36:39], v[182:185], v[152:155], v[36:39]
	v_mfma_f32_16x16x32_bf16 v[32:35], v[198:201], v[152:155], v[32:35]
	v_mfma_f32_16x16x32_bf16 v[20:23], v[182:185], v[160:163], v[20:23]
	v_mfma_f32_16x16x32_bf16 v[16:19], v[198:201], v[160:163], v[16:19]
	v_mfma_f32_16x16x32_bf16 v[4:7], v[182:185], v[174:177], v[4:7]
	v_mfma_f32_16x16x32_bf16 v[0:3], v[198:201], v[174:177], v[0:3]
	v_mfma_f32_16x16x32_bf16 v[40:43], v[182:185], v[144:147], v[68:71]
	v_mfma_f32_16x16x32_bf16 v[44:47], v[198:201], v[144:147], v[64:67]
	v_mfma_f32_16x16x32_bf16 v[36:39], v[186:189], v[156:159], v[36:39]
	v_mfma_f32_16x16x32_bf16 v[32:35], v[210:213], v[156:159], v[32:35]
	v_mfma_f32_16x16x32_bf16 v[20:23], v[186:189], v[164:167], v[20:23]
	v_mfma_f32_16x16x32_bf16 v[16:19], v[210:213], v[164:167], v[16:19]
	v_mfma_f32_16x16x32_bf16 v[4:7], v[186:189], v[178:181], v[4:7]
	v_mfma_f32_16x16x32_bf16 v[0:3], v[210:213], v[178:181], v[0:3]
	v_mfma_f32_16x16x32_bf16 v[40:43], v[186:189], v[148:151], v[40:43]
	v_mfma_f32_16x16x32_bf16 v[44:47], v[210:213], v[148:151], v[44:47]
	s_setprio 0
	v_add_u32_e32 v68, s59, v208
	s_barrier
	ds_read_b128 v[56:59], v68
	ds_read_b128 v[60:63], v68 offset:1024
	ds_read_b128 v[64:67], v68 offset:2048
	ds_read_b128 v[68:71], v68 offset:3072
	s_mov_b32 m0, s53
	v_lshl_add_u64 v[182:183], s[36:37], 0, v[168:169]
	ds_read_b128 v[144:147], v209 offset:32768
	ds_read_b128 v[148:151], v209 offset:33792
	ds_read_b128 v[152:155], v209 offset:34816
	ds_read_b128 v[156:159], v209 offset:35840
	ds_read_b128 v[160:163], v209 offset:36864
	ds_read_b128 v[164:167], v209 offset:37888
	ds_read_b128 v[174:177], v209 offset:38912
	ds_read_b128 v[178:181], v209 offset:39936
	global_load_lds_dwordx4 v[182:183], off
	v_lshl_add_u64 v[182:183], s[36:37], 0, v[170:171]
	s_mov_b32 m0, s54
	s_nop 0
	global_load_lds_dwordx4 v[182:183], off
	s_waitcnt lgkmcnt(8)
	s_barrier
	s_waitcnt lgkmcnt(0)
	s_setprio 1
	v_mfma_f32_16x16x32_bf16 v[140:143], v[56:59], v[144:147], v[140:143]
	v_mfma_f32_16x16x32_bf16 v[136:139], v[64:67], v[144:147], v[136:139]
	v_mfma_f32_16x16x32_bf16 v[124:127], v[56:59], v[152:155], v[124:127]
	v_mfma_f32_16x16x32_bf16 v[120:123], v[64:67], v[152:155], v[120:123]
	v_mfma_f32_16x16x32_bf16 v[108:111], v[56:59], v[160:163], v[108:111]
	v_mfma_f32_16x16x32_bf16 v[104:107], v[64:67], v[160:163], v[104:107]
	v_mfma_f32_16x16x32_bf16 v[92:95], v[56:59], v[174:177], v[92:95]
	v_mfma_f32_16x16x32_bf16 v[88:91], v[64:67], v[174:177], v[88:91]
	v_mfma_f32_16x16x32_bf16 v[140:143], v[60:63], v[148:151], v[140:143]
	v_mfma_f32_16x16x32_bf16 v[136:139], v[68:71], v[148:151], v[136:139]
	v_mfma_f32_16x16x32_bf16 v[124:127], v[60:63], v[156:159], v[124:127]
	v_mfma_f32_16x16x32_bf16 v[120:123], v[68:71], v[156:159], v[120:123]
	v_mfma_f32_16x16x32_bf16 v[108:111], v[60:63], v[164:167], v[108:111]
	v_mfma_f32_16x16x32_bf16 v[104:107], v[68:71], v[164:167], v[104:107]
	v_mfma_f32_16x16x32_bf16 v[92:95], v[60:63], v[178:181], v[92:95]
	v_mfma_f32_16x16x32_bf16 v[88:91], v[68:71], v[178:181], v[88:91]
	s_setprio 0
	s_barrier
	s_mov_b32 m0, s58
	v_add_u32_e32 v196, s33, v208
	v_lshl_add_u64 v[190:191], v[190:191], 0, s[80:81]
	ds_read_b128 v[182:185], v196
	ds_read_b128 v[186:189], v196 offset:1024
	ds_read_b128 v[198:201], v196 offset:2048
	ds_read_b128 v[210:213], v196 offset:3072
	global_load_lds_dwordx4 v[190:191], off
	v_lshl_add_u64 v[190:191], v[206:207], 0, s[80:81]
	s_mov_b32 m0, s23
	s_nop 0
	global_load_lds_dwordx4 v[190:191], off
	s_barrier
	s_waitcnt lgkmcnt(0)
	s_setprio 1
	v_mfma_f32_16x16x32_bf16 v[132:135], v[182:185], v[144:147], v[132:135]
	v_mfma_f32_16x16x32_bf16 v[128:131], v[198:201], v[144:147], v[128:131]
	v_mfma_f32_16x16x32_bf16 v[116:119], v[182:185], v[152:155], v[116:119]
	v_mfma_f32_16x16x32_bf16 v[112:115], v[198:201], v[152:155], v[112:115]
	v_mfma_f32_16x16x32_bf16 v[100:103], v[182:185], v[160:163], v[100:103]
	v_mfma_f32_16x16x32_bf16 v[96:99], v[198:201], v[160:163], v[96:99]
	v_mfma_f32_16x16x32_bf16 v[84:87], v[182:185], v[174:177], v[84:87]
	v_mfma_f32_16x16x32_bf16 v[80:83], v[198:201], v[174:177], v[80:83]
	v_mfma_f32_16x16x32_bf16 v[132:135], v[186:189], v[148:151], v[132:135]
	v_mfma_f32_16x16x32_bf16 v[128:131], v[210:213], v[148:151], v[128:131]
	v_mfma_f32_16x16x32_bf16 v[116:119], v[186:189], v[156:159], v[116:119]
	v_mfma_f32_16x16x32_bf16 v[112:115], v[210:213], v[156:159], v[112:115]
	v_mfma_f32_16x16x32_bf16 v[100:103], v[186:189], v[164:167], v[100:103]
	v_mfma_f32_16x16x32_bf16 v[96:99], v[210:213], v[164:167], v[96:99]
	v_mfma_f32_16x16x32_bf16 v[84:87], v[186:189], v[178:181], v[84:87]
	v_mfma_f32_16x16x32_bf16 v[80:83], v[210:213], v[178:181], v[80:83]
	s_setprio 0
	s_mov_b32 m0, s55
	v_lshl_add_u64 v[190:191], v[214:215], 0, s[80:81]
	s_barrier
	ds_read_b128 v[144:147], v209 offset:49152
	ds_read_b128 v[148:151], v209 offset:50176
	ds_read_b128 v[152:155], v209 offset:51200
	ds_read_b128 v[156:159], v209 offset:52224
	ds_read_b128 v[160:163], v209 offset:53248
	ds_read_b128 v[164:167], v209 offset:54272
	ds_read_b128 v[174:177], v209 offset:55296
	ds_read_b128 v[178:181], v209 offset:56320
	global_load_lds_dwordx4 v[190:191], off
	v_lshl_add_u64 v[190:191], v[216:217], 0, s[80:81]
	s_mov_b32 m0, s56
	s_nop 0
	global_load_lds_dwordx4 v[190:191], off
	s_barrier
	s_waitcnt lgkmcnt(0)
	s_setprio 1
	v_mfma_f32_16x16x32_bf16 v[76:79], v[56:59], v[144:147], v[76:79]
	v_mfma_f32_16x16x32_bf16 v[72:75], v[64:67], v[144:147], v[72:75]
	v_mfma_f32_16x16x32_bf16 v[52:55], v[56:59], v[152:155], v[52:55]
	v_mfma_f32_16x16x32_bf16 v[48:51], v[64:67], v[152:155], v[48:51]
	v_mfma_f32_16x16x32_bf16 v[28:31], v[56:59], v[160:163], v[28:31]
	v_mfma_f32_16x16x32_bf16 v[24:27], v[64:67], v[160:163], v[24:27]
	v_mfma_f32_16x16x32_bf16 v[12:15], v[56:59], v[174:177], v[12:15]
	v_mfma_f32_16x16x32_bf16 v[8:11], v[64:67], v[174:177], v[8:11]
	v_mfma_f32_16x16x32_bf16 v[76:79], v[60:63], v[148:151], v[76:79]
	v_mfma_f32_16x16x32_bf16 v[72:75], v[68:71], v[148:151], v[72:75]
	v_mfma_f32_16x16x32_bf16 v[52:55], v[60:63], v[156:159], v[52:55]
	v_mfma_f32_16x16x32_bf16 v[48:51], v[68:71], v[156:159], v[48:51]
	v_mfma_f32_16x16x32_bf16 v[28:31], v[60:63], v[164:167], v[28:31]
	v_mfma_f32_16x16x32_bf16 v[24:27], v[68:71], v[164:167], v[24:27]
	v_mfma_f32_16x16x32_bf16 v[12:15], v[60:63], v[178:181], v[12:15]
	v_mfma_f32_16x16x32_bf16 v[8:11], v[68:71], v[178:181], v[8:11]
	s_setprio 0
	s_barrier
	s_mov_b32 m0, s63
	v_lshl_add_u64 v[56:57], s[34:35], 0, v[192:193]
	global_load_lds_dwordx4 v[56:57], off
	v_lshl_add_u64 v[56:57], s[34:35], 0, v[172:173]
	s_mov_b32 m0, s62
	s_nop 0
	global_load_lds_dwordx4 v[56:57], off
	s_waitcnt vmcnt(6)
	s_barrier
	s_setprio 1
	v_mfma_f32_16x16x32_bf16 v[40:43], v[182:185], v[144:147], v[40:43]
	v_mfma_f32_16x16x32_bf16 v[68:71], v[186:189], v[148:151], v[40:43]
	v_mfma_f32_16x16x32_bf16 v[40:43], v[198:201], v[144:147], v[44:47]
	v_mfma_f32_16x16x32_bf16 v[36:39], v[182:185], v[152:155], v[36:39]
	v_mfma_f32_16x16x32_bf16 v[32:35], v[198:201], v[152:155], v[32:35]
	v_mfma_f32_16x16x32_bf16 v[20:23], v[182:185], v[160:163], v[20:23]
	v_mfma_f32_16x16x32_bf16 v[16:19], v[198:201], v[160:163], v[16:19]
	v_mfma_f32_16x16x32_bf16 v[4:7], v[182:185], v[174:177], v[4:7]
	v_mfma_f32_16x16x32_bf16 v[0:3], v[198:201], v[174:177], v[0:3]
	v_mfma_f32_16x16x32_bf16 v[64:67], v[210:213], v[148:151], v[40:43]
	v_mfma_f32_16x16x32_bf16 v[36:39], v[186:189], v[156:159], v[36:39]
	v_mfma_f32_16x16x32_bf16 v[32:35], v[210:213], v[156:159], v[32:35]
	v_mfma_f32_16x16x32_bf16 v[20:23], v[186:189], v[164:167], v[20:23]
	v_mfma_f32_16x16x32_bf16 v[16:19], v[210:213], v[164:167], v[16:19]
	v_mfma_f32_16x16x32_bf16 v[4:7], v[186:189], v[178:181], v[4:7]
	v_mfma_f32_16x16x32_bf16 v[0:3], v[210:213], v[178:181], v[0:3]
	s_setprio 0
	s_andn2_b64 vcc, exec, s[30:31]
	s_mov_b64 s[34:35], -1
	s_mov_b64 s[30:31], 0
	s_mov_b64 s[36:37], 0x100
	s_barrier
	s_cbranch_vccz .LBB0_2698
	v_mov_b32_e32 v144, v252
	s_lshl_b32 s1, s24, 8
	v_readfirstlane_b32 s0, v144
	s_ashr_i32 s15, s0, 2
	s_andn2_b32 s15, s15, 63
	s_add_i32 s15, s15, s1
	v_and_b32_e32 v145, 64, v195
	v_lshrrev_b32_e32 v40, 1, v144
	v_and_or_b32 v178, v144, 15, s15
	v_xor_b32_e32 v144, 16, v195
	v_add_u32_e32 v145, 64, v145
	v_cmp_lt_i32_e32 vcc, v144, v145
	s_lshr_b32 s0, s0, 1
	s_lshl_b32 s1, s22, 8
	v_cndmask_b32_e32 v144, v195, v144, vcc
	s_and_b32 s0, s0, 0x60
	v_lshlrev_b32_e32 v198, 2, v144
	v_xor_b32_e32 v144, 32, v195
	s_or_b32 s0, s0, s1
	v_cmp_lt_i32_e32 vcc, v144, v145
	v_and_or_b32 v176, v40, 24, s0
	v_ashrrev_i32_e32 v179, 31, v178
	v_cndmask_b32_e32 v144, v195, v144, vcc
	v_ashrrev_i32_e32 v177, 31, v176
	v_lshlrev_b32_e32 v196, 2, v144
	v_lshlrev_b64 v[144:145], 10, v[178:179]
	v_lshl_add_u64 v[146:147], v[144:145], 0, v[176:177]
	v_lshlrev_b64 v[146:147], 1, v[146:147]
	v_lshl_add_u64 v[44:45], v[176:177], 2, s[10:11]
	v_lshl_add_u64 v[188:189], s[6:7], 0, v[146:147]
	v_lshl_add_u64 v[206:207], s[8:9], 0, v[146:147]
	global_load_dwordx4 v[56:59], v[44:45], off offset:16
	global_load_dwordx4 v[60:63], v[44:45], off
	global_load_dwordx4 v[40:43], v[44:45], off offset:528
	s_nop 0
	global_load_dwordx4 v[44:47], v[44:45], off offset:512
	v_or_b32_e32 v174, 0x80, v176
	global_load_dwordx4 v[210:213], v[188:189], off
	global_load_dwordx4 v[164:167], v[188:189], off offset:256
	global_load_dwordx4 v[214:217], v[206:207], off
	v_ashrrev_i32_e32 v175, 31, v174
	v_or_b32_e32 v184, 16, v178
	v_lshl_add_u64 v[144:145], v[144:145], 0, v[174:175]
	v_ashrrev_i32_e32 v185, 31, v184
	v_lshl_add_u64 v[190:191], v[144:145], 1, s[8:9]
	v_lshlrev_b64 v[144:145], 10, v[184:185]
	v_lshl_add_u64 v[146:147], v[144:145], 0, v[176:177]
	v_lshlrev_b64 v[146:147], 1, v[146:147]
	v_lshl_add_u64 v[148:149], v[144:145], 0, v[174:175]
	v_lshl_add_u64 v[180:181], s[6:7], 0, v[146:147]
	v_lshl_add_u64 v[186:187], s[8:9], 0, v[146:147]
	v_lshl_add_u64 v[182:183], v[148:149], 1, s[8:9]
	global_load_dwordx4 v[160:163], v[190:191], off
	global_load_dwordx4 v[156:159], v[180:181], off
	global_load_dwordx4 v[144:147], v[180:181], off offset:256
	global_load_dwordx4 v[152:155], v[186:187], off
	global_load_dwordx4 v[148:151], v[182:183], off
	v_cmp_gt_u32_e32 vcc, 16, v195
	s_waitcnt vmcnt(0)
	v_lshlrev_b32_e32 v200, 16, v210
	v_and_b32_e32 v201, 0xffff0000, v210
	v_lshlrev_b32_e32 v218, 16, v214
	v_and_b32_e32 v219, 0xffff0000, v214
	v_lshlrev_b32_e32 v210, 16, v211
	v_and_b32_e32 v211, 0xffff0000, v211
	v_lshlrev_b32_e32 v214, 16, v215
	v_and_b32_e32 v215, 0xffff0000, v215
	v_pk_add_f32 v[200:201], v[200:201], v[218:219]
	v_pk_add_f32 v[210:211], v[210:211], v[214:215]
	v_pk_fma_f32 v[200:201], v[140:141], v[60:61], v[200:201]
	v_pk_fma_f32 v[210:211], v[142:143], v[62:63], v[210:211]
	v_lshlrev_b32_e32 v140, 16, v212
	v_and_b32_e32 v141, 0xffff0000, v212
	v_lshlrev_b32_e32 v142, 16, v216
	v_and_b32_e32 v143, 0xffff0000, v216
	v_pk_add_f32 v[140:141], v[140:141], v[142:143]
	v_lshlrev_b32_e32 v142, 16, v213
	v_and_b32_e32 v143, 0xffff0000, v213
	v_lshlrev_b32_e32 v212, 16, v217
	v_and_b32_e32 v213, 0xffff0000, v217
	v_pk_add_f32 v[142:143], v[142:143], v[212:213]
	v_pk_fma_f32 v[214:215], v[136:137], v[56:57], v[140:141]
	v_cvt_pk_bf16_f32 v136, v200, v201
	v_pk_fma_f32 v[212:213], v[138:139], v[58:59], v[142:143]
	v_and_b32_e32 v139, 0xffff0000, v136
	v_lshlrev_b32_e32 v138, 16, v136
	v_pk_add_f32 v[138:139], v[200:201], v[138:139] neg_lo:[0,1] neg_hi:[0,1]
	v_cvt_pk_bf16_f32 v137, v210, v211
	v_cvt_pk_bf16_f32 v140, v138, v139
	v_and_b32_e32 v139, 0xffff0000, v137
	v_lshlrev_b32_e32 v138, 16, v137
	v_pk_add_f32 v[138:139], v[210:211], v[138:139] neg_lo:[0,1] neg_hi:[0,1]
	s_nop 0
	v_cvt_pk_bf16_f32 v141, v138, v139
	v_cvt_pk_bf16_f32 v138, v214, v215
	v_cvt_pk_bf16_f32 v139, v212, v213
	v_and_b32_e32 v143, 0xffff0000, v138
	v_lshlrev_b32_e32 v142, 16, v138
	v_and_b32_e32 v217, 0xffff0000, v139
	v_lshlrev_b32_e32 v216, 16, v139
	v_pk_add_f32 v[142:143], v[214:215], v[142:143] neg_lo:[0,1] neg_hi:[0,1]
	v_pk_add_f32 v[216:217], v[212:213], v[216:217] neg_lo:[0,1] neg_hi:[0,1]
	v_cvt_pk_bf16_f32 v142, v142, v143
	v_cvt_pk_bf16_f32 v143, v216, v217
	global_store_dwordx4 v[188:189], v[136:139], off
	global_store_dwordx4 v[206:207], v[140:143], off
	s_nop 0
	v_pk_mul_f32 v[138:139], v[214:215], v[214:215]
	v_pk_mul_f32 v[136:137], v[212:213], v[212:213]
	v_pk_fma_f32 v[138:139], v[200:201], v[200:201], v[138:139]
	v_pk_fma_f32 v[136:137], v[210:211], v[210:211], v[136:137]
	v_add_f32_e32 v138, v138, v139
	v_add_f32_e32 v136, v136, v138
	v_add_f32_e32 v136, v137, v136
	ds_bpermute_b32 v137, v198, v136
	s_waitcnt lgkmcnt(0)
	v_add_f32_e32 v138, v136, v137
	ds_bpermute_b32 v139, v196, v138
	v_lshl_add_u64 v[136:137], v[178:179], 2, s[12:13]
	s_and_saveexec_b64 s[22:23], vcc
	s_cbranch_execz .LBB0_2701
	s_waitcnt lgkmcnt(0)
	v_add_f32_e32 v138, v138, v139
	global_atomic_add_f32 v[136:137], v138, off

.LBB0_2803:
	v_mov_b64_e32 v[0:1], 0x580
	s_ashr_i32 s9, s8, 31
	v_cmp_lt_i64_e32 vcc, s[12:13], v[0:1]
	s_lshl_b64 s[12:13], s[8:9], 19
	s_add_u32 s12, s82, s12
	s_addc_u32 s13, s83, s13
	s_and_b64 s[14:15], vcc, exec
	s_cselect_b32 s9, s13, s21
	s_cselect_b32 s33, s12, s20
	s_ashr_i32 s11, s10, 31
	s_lshl_b64 s[14:15], s[10:11], 19
	s_add_u32 s14, s26, s14
	s_addc_u32 s15, s27, s15
	s_and_b64 s[22:23], vcc, exec
	s_cselect_b32 s11, s15, s19
	s_cselect_b32 s38, s14, s18
	s_add_u32 s39, s18, 0x100
	s_addc_u32 s40, s19, 0
	s_add_u32 s18, s20, 0x40080
	v_mov_b32_e32 v0, 0
	s_addc_u32 s19, s21, 0
	s_mov_b32 s41, -2
	v_mov_b32_e32 v1, 0
	v_pk_mov_b32 v[2:3], v[0:1], v[0:1]
	v_pk_mov_b32 v[4:5], v[0:1], v[0:1]
	v_pk_mov_b32 v[6:7], v[0:1], v[0:1]
	v_pk_mov_b32 v[8:9], v[0:1], v[0:1]
	v_pk_mov_b32 v[10:11], v[0:1], v[0:1]
	v_pk_mov_b32 v[12:13], v[0:1], v[0:1]
	v_pk_mov_b32 v[14:15], v[0:1], v[0:1]
	v_pk_mov_b32 v[16:17], v[0:1], v[0:1]
	v_pk_mov_b32 v[18:19], v[0:1], v[0:1]
	v_pk_mov_b32 v[20:21], v[0:1], v[0:1]
	v_pk_mov_b32 v[22:23], v[0:1], v[0:1]
	v_pk_mov_b32 v[24:25], v[0:1], v[0:1]
	v_pk_mov_b32 v[26:27], v[0:1], v[0:1]
	v_pk_mov_b32 v[28:29], v[0:1], v[0:1]
	v_pk_mov_b32 v[30:31], v[0:1], v[0:1]
	v_pk_mov_b32 v[32:33], v[0:1], v[0:1]
	v_pk_mov_b32 v[34:35], v[0:1], v[0:1]
	v_pk_mov_b32 v[36:37], v[0:1], v[0:1]
	v_pk_mov_b32 v[38:39], v[0:1], v[0:1]
	v_pk_mov_b32 v[40:41], v[0:1], v[0:1]
	v_pk_mov_b32 v[42:43], v[0:1], v[0:1]
	v_pk_mov_b32 v[44:45], v[0:1], v[0:1]
	v_pk_mov_b32 v[46:47], v[0:1], v[0:1]
	v_pk_mov_b32 v[48:49], v[0:1], v[0:1]
	v_pk_mov_b32 v[50:51], v[0:1], v[0:1]
	v_pk_mov_b32 v[52:53], v[0:1], v[0:1]
	v_pk_mov_b32 v[54:55], v[0:1], v[0:1]
	v_pk_mov_b32 v[56:57], v[0:1], v[0:1]
	v_pk_mov_b32 v[58:59], v[0:1], v[0:1]
	v_pk_mov_b32 v[60:61], v[0:1], v[0:1]
	v_pk_mov_b32 v[62:63], v[0:1], v[0:1]
	v_pk_mov_b32 v[64:65], v[0:1], v[0:1]
	v_pk_mov_b32 v[66:67], v[0:1], v[0:1]
	v_pk_mov_b32 v[68:69], v[0:1], v[0:1]
	v_pk_mov_b32 v[70:71], v[0:1], v[0:1]
	v_pk_mov_b32 v[72:73], v[0:1], v[0:1]
	v_pk_mov_b32 v[74:75], v[0:1], v[0:1]
	v_pk_mov_b32 v[76:77], v[0:1], v[0:1]
	v_pk_mov_b32 v[78:79], v[0:1], v[0:1]
	v_pk_mov_b32 v[80:81], v[0:1], v[0:1]
	v_pk_mov_b32 v[82:83], v[0:1], v[0:1]
	v_pk_mov_b32 v[84:85], v[0:1], v[0:1]
	v_pk_mov_b32 v[86:87], v[0:1], v[0:1]
	v_pk_mov_b32 v[88:89], v[0:1], v[0:1]
	v_pk_mov_b32 v[90:91], v[0:1], v[0:1]
	v_pk_mov_b32 v[92:93], v[0:1], v[0:1]
	v_pk_mov_b32 v[94:95], v[0:1], v[0:1]
	v_pk_mov_b32 v[96:97], v[0:1], v[0:1]
	v_pk_mov_b32 v[98:99], v[0:1], v[0:1]
	v_pk_mov_b32 v[100:101], v[0:1], v[0:1]
	v_pk_mov_b32 v[102:103], v[0:1], v[0:1]
	v_pk_mov_b32 v[104:105], v[0:1], v[0:1]
	v_pk_mov_b32 v[106:107], v[0:1], v[0:1]
	v_pk_mov_b32 v[108:109], v[0:1], v[0:1]
	v_pk_mov_b32 v[110:111], v[0:1], v[0:1]
	v_pk_mov_b32 v[112:113], v[0:1], v[0:1]
	v_pk_mov_b32 v[114:115], v[0:1], v[0:1]
	v_pk_mov_b32 v[116:117], v[0:1], v[0:1]
	v_pk_mov_b32 v[118:119], v[0:1], v[0:1]
	v_pk_mov_b32 v[120:121], v[0:1], v[0:1]
	v_pk_mov_b32 v[122:123], v[0:1], v[0:1]
	v_pk_mov_b32 v[124:125], v[0:1], v[0:1]
	v_pk_mov_b32 v[126:127], v[0:1], v[0:1]
	s_waitcnt vmcnt(0)
	v_add_u32_e32 v202, 0x10000, v151
	v_add_u32_e32 v203, 0x14000, v151
	v_add_u32_e32 v204, 0x18000, v151
	v_add_u32_e32 v205, 0x1c000, v151
.LBB0_2804:
	s_add_u32 s20, s18, 0xfffc0080
	s_addc_u32 s21, s19, -1
	s_add_i32 s42, 0, 0x10000
	ds_read_b128 v[138:141], v202
	ds_read_b128 v[142:145], v202 offset:1024
	ds_read_b128 v[146:149], v202 offset:2048
	ds_read_b128 v[154:157], v202 offset:3072
	s_cmp_eq_u32 s41, 12
	s_cselect_b32 s23, s9, s21
	s_cselect_b32 s22, s33, s20
	s_cselect_b32 s21, s11, s40
	s_cselect_b32 s20, s38, s39
	s_add_i32 m0, s17, 0xc000
	ds_read_b128 v[158:161], v152
	ds_read_b128 v[162:165], v152 offset:1024
	ds_read_b128 v[166:169], v152 offset:2048
	ds_read_b128 v[170:173], v152 offset:3072
	ds_read_b128 v[174:177], v152 offset:4096
	ds_read_b128 v[178:181], v152 offset:5120
	ds_read_b128 v[182:185], v152 offset:6144
	ds_read_b128 v[186:189], v152 offset:7168
	global_load_lds_dwordx4 v136, s[18:19]
	s_add_i32 m0, s17, 0xe000
	s_nop 0
	global_load_lds_dwordx4 v134, s[18:19]
	s_waitcnt lgkmcnt(8)
	s_barrier
	s_waitcnt lgkmcnt(0)
	s_setprio 1
	v_mfma_f32_16x16x32_bf16 v[124:127], v[138:141], v[158:161], v[124:127]
	v_mfma_f32_16x16x32_bf16 v[116:119], v[146:149], v[158:161], v[116:119]
	v_mfma_f32_16x16x32_bf16 v[108:111], v[138:141], v[166:169], v[108:111]
	v_mfma_f32_16x16x32_bf16 v[100:103], v[146:149], v[166:169], v[100:103]
	v_mfma_f32_16x16x32_bf16 v[92:95], v[138:141], v[174:177], v[92:95]
	v_mfma_f32_16x16x32_bf16 v[84:87], v[146:149], v[174:177], v[84:87]
	v_mfma_f32_16x16x32_bf16 v[76:79], v[138:141], v[182:185], v[76:79]
	v_mfma_f32_16x16x32_bf16 v[68:71], v[146:149], v[182:185], v[68:71]
	v_mfma_f32_16x16x32_bf16 v[124:127], v[142:145], v[162:165], v[124:127]
	v_mfma_f32_16x16x32_bf16 v[116:119], v[154:157], v[162:165], v[116:119]
	v_mfma_f32_16x16x32_bf16 v[108:111], v[142:145], v[170:173], v[108:111]
	v_mfma_f32_16x16x32_bf16 v[100:103], v[154:157], v[170:173], v[100:103]
	v_mfma_f32_16x16x32_bf16 v[92:95], v[142:145], v[178:181], v[92:95]
	v_mfma_f32_16x16x32_bf16 v[84:87], v[154:157], v[178:181], v[84:87]
	v_mfma_f32_16x16x32_bf16 v[76:79], v[142:145], v[186:189], v[76:79]
	v_mfma_f32_16x16x32_bf16 v[68:71], v[154:157], v[186:189], v[68:71]
	s_setprio 0
	s_barrier
	s_add_i32 s44, 0, 0x14000
	s_add_i32 s42, s42, s28
	s_mov_b32 m0, s42
	ds_read_b128 v[198:201], v203
	ds_read_b128 v[206:209], v203 offset:1024
	ds_read_b128 v[210:213], v203 offset:2048
	ds_read_b128 v[214:217], v203 offset:3072
	global_load_lds_dwordx4 v192, s[20:21]
	s_add_i32 m0, s42, 0x2000
	s_nop 0
	global_load_lds_dwordx4 v128, s[20:21]
	s_barrier
	s_waitcnt lgkmcnt(0)
	s_setprio 1
	v_mfma_f32_16x16x32_bf16 v[120:123], v[198:201], v[158:161], v[120:123]
	v_mfma_f32_16x16x32_bf16 v[112:115], v[210:213], v[158:161], v[112:115]
	v_mfma_f32_16x16x32_bf16 v[104:107], v[198:201], v[166:169], v[104:107]
	v_mfma_f32_16x16x32_bf16 v[96:99], v[210:213], v[166:169], v[96:99]
	v_mfma_f32_16x16x32_bf16 v[88:91], v[198:201], v[174:177], v[88:91]
	v_mfma_f32_16x16x32_bf16 v[80:83], v[210:213], v[174:177], v[80:83]
	v_mfma_f32_16x16x32_bf16 v[72:75], v[198:201], v[182:185], v[72:75]
	v_mfma_f32_16x16x32_bf16 v[64:67], v[210:213], v[182:185], v[64:67]
	v_mfma_f32_16x16x32_bf16 v[120:123], v[206:209], v[162:165], v[120:123]
	v_mfma_f32_16x16x32_bf16 v[112:115], v[214:217], v[162:165], v[112:115]
	v_mfma_f32_16x16x32_bf16 v[104:107], v[206:209], v[170:173], v[104:107]
	v_mfma_f32_16x16x32_bf16 v[96:99], v[214:217], v[170:173], v[96:99]
	v_mfma_f32_16x16x32_bf16 v[88:91], v[206:209], v[178:181], v[88:91]
	v_mfma_f32_16x16x32_bf16 v[80:83], v[214:217], v[178:181], v[80:83]
	v_mfma_f32_16x16x32_bf16 v[72:75], v[206:209], v[186:189], v[72:75]
	v_mfma_f32_16x16x32_bf16 v[64:67], v[214:217], v[186:189], v[64:67]
	s_setprio 0
	s_mov_b32 m0, s17
	s_add_u32 vcc_lo, s22, 0x80
	s_addc_u32 vcc_hi, s23, 0
	s_barrier
	ds_read_b128 v[158:161], v152 offset:16384
	ds_read_b128 v[162:165], v152 offset:17408
	ds_read_b128 v[166:169], v152 offset:18432
	ds_read_b128 v[170:173], v152 offset:19456
	ds_read_b128 v[174:177], v152 offset:20480
	ds_read_b128 v[178:181], v152 offset:21504
	ds_read_b128 v[182:185], v152 offset:22528
	ds_read_b128 v[186:189], v152 offset:23552
	global_load_lds_dwordx4 v132, s[22:23]
	s_mov_b32 m0, s29
	s_nop 0
	global_load_lds_dwordx4 v130, s[22:23]
	s_barrier
	s_waitcnt lgkmcnt(0)
	s_setprio 1
	v_mfma_f32_16x16x32_bf16 v[60:63], v[138:141], v[158:161], v[60:63]
	v_mfma_f32_16x16x32_bf16 v[52:55], v[146:149], v[158:161], v[52:55]
	v_mfma_f32_16x16x32_bf16 v[44:47], v[138:141], v[166:169], v[44:47]
	v_mfma_f32_16x16x32_bf16 v[36:39], v[146:149], v[166:169], v[36:39]
	v_mfma_f32_16x16x32_bf16 v[28:31], v[138:141], v[174:177], v[28:31]
	v_mfma_f32_16x16x32_bf16 v[20:23], v[146:149], v[174:177], v[20:23]
	v_mfma_f32_16x16x32_bf16 v[12:15], v[138:141], v[182:185], v[12:15]
	v_mfma_f32_16x16x32_bf16 v[4:7], v[146:149], v[182:185], v[4:7]
	v_mfma_f32_16x16x32_bf16 v[60:63], v[142:145], v[162:165], v[60:63]
	v_mfma_f32_16x16x32_bf16 v[52:55], v[154:157], v[162:165], v[52:55]
	v_mfma_f32_16x16x32_bf16 v[44:47], v[142:145], v[170:173], v[44:47]
	v_mfma_f32_16x16x32_bf16 v[36:39], v[154:157], v[170:173], v[36:39]
	v_mfma_f32_16x16x32_bf16 v[28:31], v[142:145], v[178:181], v[28:31]
	v_mfma_f32_16x16x32_bf16 v[20:23], v[154:157], v[178:181], v[20:23]
	v_mfma_f32_16x16x32_bf16 v[12:15], v[142:145], v[186:189], v[12:15]
	v_mfma_f32_16x16x32_bf16 v[4:7], v[154:157], v[186:189], v[4:7]
	s_setprio 0
	s_barrier
	s_add_u32 s42, s20, 0x40000
	s_addc_u32 s43, s21, 0
	s_add_i32 s44, s44, s28
	s_mov_b32 m0, s44
	s_nop 0
	global_load_lds_dwordx4 v192, s[42:43]
	s_add_i32 m0, s44, 0x2000
	s_nop 0
	global_load_lds_dwordx4 v128, s[42:43]
	s_waitcnt vmcnt(6)
	s_barrier
	s_setprio 1
	v_mfma_f32_16x16x32_bf16 v[56:59], v[198:201], v[158:161], v[56:59]
	v_mfma_f32_16x16x32_bf16 v[48:51], v[210:213], v[158:161], v[48:51]
	v_mfma_f32_16x16x32_bf16 v[40:43], v[198:201], v[166:169], v[40:43]
	v_mfma_f32_16x16x32_bf16 v[32:35], v[210:213], v[166:169], v[32:35]
	v_mfma_f32_16x16x32_bf16 v[24:27], v[198:201], v[174:177], v[24:27]
	v_mfma_f32_16x16x32_bf16 v[16:19], v[210:213], v[174:177], v[16:19]
	v_mfma_f32_16x16x32_bf16 v[8:11], v[198:201], v[182:185], v[8:11]
	v_mfma_f32_16x16x32_bf16 v[0:3], v[210:213], v[182:185], v[0:3]
	v_mfma_f32_16x16x32_bf16 v[56:59], v[206:209], v[162:165], v[56:59]
	v_mfma_f32_16x16x32_bf16 v[48:51], v[214:217], v[162:165], v[48:51]
	v_mfma_f32_16x16x32_bf16 v[40:43], v[206:209], v[170:173], v[40:43]
	v_mfma_f32_16x16x32_bf16 v[32:35], v[214:217], v[170:173], v[32:35]
	v_mfma_f32_16x16x32_bf16 v[24:27], v[206:209], v[178:181], v[24:27]
	v_mfma_f32_16x16x32_bf16 v[16:19], v[214:217], v[178:181], v[16:19]
	v_mfma_f32_16x16x32_bf16 v[8:11], v[206:209], v[186:189], v[8:11]
	v_mfma_f32_16x16x32_bf16 v[0:3], v[214:217], v[186:189], v[0:3]
	s_setprio 0
	s_add_i32 s42, 0, 0x18000
	s_barrier
	ds_read_b128 v[138:141], v204
	ds_read_b128 v[142:145], v204 offset:1024
	ds_read_b128 v[146:149], v204 offset:2048
	ds_read_b128 v[154:157], v204 offset:3072
	s_add_u32 s22, s22, 0x40000
	s_addc_u32 s23, s23, 0
	s_mov_b32 m0, s30
	ds_read_b128 v[158:161], v152 offset:32768
	ds_read_b128 v[162:165], v152 offset:33792
	ds_read_b128 v[166:169], v152 offset:34816
	ds_read_b128 v[170:173], v152 offset:35840
	ds_read_b128 v[174:177], v152 offset:36864
	ds_read_b128 v[178:181], v152 offset:37888
	ds_read_b128 v[182:185], v152 offset:38912
	ds_read_b128 v[186:189], v152 offset:39936
	global_load_lds_dwordx4 v132, s[22:23]
	s_mov_b32 m0, s31
	s_nop 0
	global_load_lds_dwordx4 v130, s[22:23]
	s_waitcnt lgkmcnt(8)
	s_barrier
	s_waitcnt lgkmcnt(0)
	s_setprio 1
	v_mfma_f32_16x16x32_bf16 v[124:127], v[138:141], v[158:161], v[124:127]
	v_mfma_f32_16x16x32_bf16 v[116:119], v[146:149], v[158:161], v[116:119]
	v_mfma_f32_16x16x32_bf16 v[108:111], v[138:141], v[166:169], v[108:111]
	v_mfma_f32_16x16x32_bf16 v[100:103], v[146:149], v[166:169], v[100:103]
	v_mfma_f32_16x16x32_bf16 v[92:95], v[138:141], v[174:177], v[92:95]
	v_mfma_f32_16x16x32_bf16 v[84:87], v[146:149], v[174:177], v[84:87]
	v_mfma_f32_16x16x32_bf16 v[76:79], v[138:141], v[182:185], v[76:79]
	v_mfma_f32_16x16x32_bf16 v[68:71], v[146:149], v[182:185], v[68:71]
	v_mfma_f32_16x16x32_bf16 v[124:127], v[142:145], v[162:165], v[124:127]
	v_mfma_f32_16x16x32_bf16 v[116:119], v[154:157], v[162:165], v[116:119]
	v_mfma_f32_16x16x32_bf16 v[108:111], v[142:145], v[170:173], v[108:111]
	v_mfma_f32_16x16x32_bf16 v[100:103], v[154:157], v[170:173], v[100:103]
	v_mfma_f32_16x16x32_bf16 v[92:95], v[142:145], v[178:181], v[92:95]
	v_mfma_f32_16x16x32_bf16 v[84:87], v[154:157], v[178:181], v[84:87]
	v_mfma_f32_16x16x32_bf16 v[76:79], v[142:145], v[186:189], v[76:79]
	v_mfma_f32_16x16x32_bf16 v[68:71], v[154:157], v[186:189], v[68:71]
	s_setprio 0
	s_barrier
	s_add_i32 s22, 0, 0x1c000
	s_add_i32 s23, s42, s28
	s_add_u32 s100, s20, 0x80
	s_addc_u32 s101, s21, 0
	s_mov_b32 m0, s23
	ds_read_b128 v[198:201], v205
	ds_read_b128 v[206:209], v205 offset:1024
	ds_read_b128 v[210:213], v205 offset:2048
	ds_read_b128 v[214:217], v205 offset:3072
	global_load_lds_dwordx4 v192, s[100:101]
	s_add_i32 m0, s23, 0x2000
	s_nop 0
	global_load_lds_dwordx4 v128, s[100:101]
	s_barrier
	s_waitcnt lgkmcnt(0)
	s_setprio 1
	v_mfma_f32_16x16x32_bf16 v[120:123], v[198:201], v[158:161], v[120:123]
	v_mfma_f32_16x16x32_bf16 v[112:115], v[210:213], v[158:161], v[112:115]
	v_mfma_f32_16x16x32_bf16 v[104:107], v[198:201], v[166:169], v[104:107]
	v_mfma_f32_16x16x32_bf16 v[96:99], v[210:213], v[166:169], v[96:99]
	v_mfma_f32_16x16x32_bf16 v[88:91], v[198:201], v[174:177], v[88:91]
	v_mfma_f32_16x16x32_bf16 v[80:83], v[210:213], v[174:177], v[80:83]
	v_mfma_f32_16x16x32_bf16 v[72:75], v[198:201], v[182:185], v[72:75]
	v_mfma_f32_16x16x32_bf16 v[64:67], v[210:213], v[182:185], v[64:67]
	v_mfma_f32_16x16x32_bf16 v[120:123], v[206:209], v[162:165], v[120:123]
	v_mfma_f32_16x16x32_bf16 v[112:115], v[214:217], v[162:165], v[112:115]
	v_mfma_f32_16x16x32_bf16 v[104:107], v[206:209], v[170:173], v[104:107]
	v_mfma_f32_16x16x32_bf16 v[96:99], v[214:217], v[170:173], v[96:99]
	v_mfma_f32_16x16x32_bf16 v[88:91], v[206:209], v[178:181], v[88:91]
	v_mfma_f32_16x16x32_bf16 v[80:83], v[214:217], v[178:181], v[80:83]
	v_mfma_f32_16x16x32_bf16 v[72:75], v[206:209], v[186:189], v[72:75]
	v_mfma_f32_16x16x32_bf16 v[64:67], v[214:217], v[186:189], v[64:67]
	s_setprio 0
	s_mov_b32 m0, s34
	s_barrier
	ds_read_b128 v[158:161], v152 offset:49152
	ds_read_b128 v[162:165], v152 offset:50176
	ds_read_b128 v[166:169], v152 offset:51200
	ds_read_b128 v[170:173], v152 offset:52224
	ds_read_b128 v[174:177], v152 offset:53248
	ds_read_b128 v[178:181], v152 offset:54272
	ds_read_b128 v[182:185], v152 offset:55296
	ds_read_b128 v[186:189], v152 offset:56320
	global_load_lds_dwordx4 v132, vcc
	s_mov_b32 m0, s35
	s_nop 0
	global_load_lds_dwordx4 v130, vcc
	s_barrier
	s_waitcnt lgkmcnt(0)
	s_setprio 1
	v_mfma_f32_16x16x32_bf16 v[60:63], v[138:141], v[158:161], v[60:63]
	v_mfma_f32_16x16x32_bf16 v[52:55], v[146:149], v[158:161], v[52:55]
	v_mfma_f32_16x16x32_bf16 v[44:47], v[138:141], v[166:169], v[44:47]
	v_mfma_f32_16x16x32_bf16 v[36:39], v[146:149], v[166:169], v[36:39]
	v_mfma_f32_16x16x32_bf16 v[28:31], v[138:141], v[174:177], v[28:31]
	v_mfma_f32_16x16x32_bf16 v[20:23], v[146:149], v[174:177], v[20:23]
	v_mfma_f32_16x16x32_bf16 v[12:15], v[138:141], v[182:185], v[12:15]
	v_mfma_f32_16x16x32_bf16 v[4:7], v[146:149], v[182:185], v[4:7]
	v_mfma_f32_16x16x32_bf16 v[60:63], v[142:145], v[162:165], v[60:63]
	v_mfma_f32_16x16x32_bf16 v[52:55], v[154:157], v[162:165], v[52:55]
	v_mfma_f32_16x16x32_bf16 v[44:47], v[142:145], v[170:173], v[44:47]
	v_mfma_f32_16x16x32_bf16 v[36:39], v[154:157], v[170:173], v[36:39]
	v_mfma_f32_16x16x32_bf16 v[28:31], v[142:145], v[178:181], v[28:31]
	v_mfma_f32_16x16x32_bf16 v[20:23], v[154:157], v[178:181], v[20:23]
	v_mfma_f32_16x16x32_bf16 v[12:15], v[142:145], v[186:189], v[12:15]
	v_mfma_f32_16x16x32_bf16 v[4:7], v[154:157], v[186:189], v[4:7]
	s_setprio 0
	s_barrier
	s_add_u32 s20, s20, 0x40080
	s_addc_u32 s21, s21, 0
	s_add_i32 s22, s22, s28
	s_mov_b32 m0, s22
	s_nop 0
	global_load_lds_dwordx4 v192, s[20:21]
	s_add_i32 m0, s22, 0x2000
	s_nop 0
	global_load_lds_dwordx4 v128, s[20:21]
	s_waitcnt vmcnt(6)
	s_barrier
	s_setprio 1
	v_mfma_f32_16x16x32_bf16 v[56:59], v[198:201], v[158:161], v[56:59]
	v_mfma_f32_16x16x32_bf16 v[48:51], v[210:213], v[158:161], v[48:51]
	v_mfma_f32_16x16x32_bf16 v[40:43], v[198:201], v[166:169], v[40:43]
	v_mfma_f32_16x16x32_bf16 v[32:35], v[210:213], v[166:169], v[32:35]
	v_mfma_f32_16x16x32_bf16 v[24:27], v[198:201], v[174:177], v[24:27]
	v_mfma_f32_16x16x32_bf16 v[16:19], v[210:213], v[174:177], v[16:19]
	v_mfma_f32_16x16x32_bf16 v[8:11], v[198:201], v[182:185], v[8:11]
	v_mfma_f32_16x16x32_bf16 v[0:3], v[210:213], v[182:185], v[0:3]
	v_mfma_f32_16x16x32_bf16 v[56:59], v[206:209], v[162:165], v[56:59]
	v_mfma_f32_16x16x32_bf16 v[48:51], v[214:217], v[162:165], v[48:51]
	v_mfma_f32_16x16x32_bf16 v[40:43], v[206:209], v[170:173], v[40:43]
	v_mfma_f32_16x16x32_bf16 v[32:35], v[214:217], v[170:173], v[32:35]
	v_mfma_f32_16x16x32_bf16 v[24:27], v[206:209], v[178:181], v[24:27]
	v_mfma_f32_16x16x32_bf16 v[16:19], v[214:217], v[178:181], v[16:19]
	v_mfma_f32_16x16x32_bf16 v[8:11], v[206:209], v[186:189], v[8:11]
	v_mfma_f32_16x16x32_bf16 v[0:3], v[214:217], v[186:189], v[0:3]
	s_setprio 0
	s_add_i32 s41, s41, 2
	s_add_u32 s39, s39, 0x100
	s_addc_u32 s40, s40, 0
	s_add_u32 s18, s18, 0x100
	s_addc_u32 s19, s19, 0
	s_cmp_gt_u32 s41, 13
	s_barrier
	s_cbranch_scc0 .LBB0_2804
	v_mov_b32_e32 v139, v252
	s_lshl_b32 s11, s16, 8
	v_readfirstlane_b32 s9, v139
	s_ashr_i32 s16, s9, 2
	s_andn2_b32 s16, s16, 63
	s_lshr_b32 s9, s9, 1
	s_add_i32 s16, s16, s11
	s_lshl_b32 s11, s37, 7
	s_and_b32 s9, s9, 0x60
	v_and_or_b32 v138, v139, 15, s16
	s_or_b32 s9, s9, s11
	v_lshrrev_b32_e32 v139, 1, v139
	v_and_or_b32 v148, v139, 24, s9
	v_ashrrev_i32_e32 v139, 31, v138
	v_lshl_add_u64 v[140:141], v[138:139], 2, s[6:7]
	v_or_b32_e32 v146, 16, v138
	v_ashrrev_i32_e32 v147, 31, v146
	v_lshl_add_u64 v[142:143], v[146:147], 2, s[6:7]
	v_or_b32_e32 v144, 32, v138
	v_ashrrev_i32_e32 v145, 31, v144
	v_lshl_add_u64 v[142:143], v[144:145], 2, s[6:7]
	v_or_b32_e32 v142, 48, v138
	v_ashrrev_i32_e32 v143, 31, v142
	v_lshl_add_u64 v[154:155], v[142:143], 2, s[6:7]
	v_pk_mul_f32 v[120:121], v[124:125], v[120:121]
	v_pk_mul_f32 v[122:123], v[126:127], v[122:123]
	v_pk_mul_f32 v[112:113], v[116:117], v[112:113]
	v_pk_mul_f32 v[114:115], v[118:119], v[114:115]
	v_ashrrev_i32_e32 v149, 31, v148
	s_movk_i32 s9, 0x1600
	v_pk_mul_f32 v[104:105], v[108:109], v[104:105]
	v_pk_mul_f32 v[106:107], v[110:111], v[106:107]
	v_pk_mul_f32 v[96:97], v[100:101], v[96:97]
	v_pk_mul_f32 v[98:99], v[102:103], v[98:99]
	v_pk_mul_f32 v[88:89], v[92:93], v[88:89]
	v_pk_mul_f32 v[90:91], v[94:95], v[90:91]
	v_pk_mul_f32 v[80:81], v[84:85], v[80:81]
	v_pk_mul_f32 v[82:83], v[86:87], v[82:83]
	v_pk_mul_f32 v[72:73], v[76:77], v[72:73]
	v_pk_mul_f32 v[74:75], v[78:79], v[74:75]
	v_pk_mul_f32 v[64:65], v[68:69], v[64:65]
	v_pk_mul_f32 v[66:67], v[70:71], v[66:67]
	v_pk_mul_f32 v[56:57], v[60:61], v[56:57]
	v_pk_mul_f32 v[58:59], v[62:63], v[58:59]
	v_pk_mul_f32 v[48:49], v[52:53], v[48:49]
	v_pk_mul_f32 v[50:51], v[54:55], v[50:51]
	v_pk_mul_f32 v[40:41], v[44:45], v[40:41]
	v_pk_mul_f32 v[42:43], v[46:47], v[42:43]
	v_pk_mul_f32 v[32:33], v[36:37], v[32:33]
	v_pk_mul_f32 v[34:35], v[38:39], v[34:35]
	v_pk_mul_f32 v[24:25], v[28:29], v[24:25]
	v_pk_mul_f32 v[26:27], v[30:31], v[26:27]
	v_pk_mul_f32 v[16:17], v[20:21], v[16:17]
	v_pk_mul_f32 v[18:19], v[22:23], v[18:19]
	v_pk_mul_f32 v[8:9], v[12:13], v[8:9]
	v_pk_mul_f32 v[10:11], v[14:15], v[10:11]
	v_pk_mul_f32 v[0:1], v[4:5], v[0:1]
	v_pk_mul_f32 v[2:3], v[6:7], v[2:3]
	s_mov_b32 s37, s10
	s_mov_b32 s16, s8
	s_mov_b64 s[20:21], s[12:13]
	v_fmamk_f32 v143, v231, 0x3a800000, v194
	s_nop 0
	v_rsq_f32_e32 v143, v143
	s_nop 0
	v_mul_f32_e32 v154, 0xbfb8aa3b, v143
	v_pk_mul_f32 v[158:159], v[124:125], v[154:155] op_sel_hi:[1,0]
	v_mul_f32_e32 v150, v143, v143
	v_exp_f32_e32 v143, v158
	v_pk_mul_f32 v[156:157], v[126:127], v[154:155] op_sel_hi:[1,0]
	v_add_f32_e32 v143, 1.0, v143
	v_rcp_f32_e32 v158, v143
	v_exp_f32_e32 v143, v159
	s_nop 0
	v_add_f32_e32 v143, 1.0, v143
	v_rcp_f32_e32 v159, v143
	v_exp_f32_e32 v143, v156
	v_pk_mul_f32 v[124:125], v[150:151], v[158:159] op_sel_hi:[0,1]
	v_add_f32_e32 v143, 1.0, v143
	v_rcp_f32_e32 v156, v143
	v_exp_f32_e32 v143, v157
	v_pk_mul_f32 v[120:121], v[120:121], v[124:125]
	v_add_f32_e32 v143, 1.0, v143
	v_rcp_f32_e32 v157, v143
	v_cvt_pk_bf16_f32 v124, v121, s0
	v_cvt_pk_bf16_f32 v120, v120, s0
	v_pk_mul_f32 v[126:127], v[150:151], v[156:157] op_sel_hi:[0,1]
	v_pk_mul_f32 v[122:123], v[122:123], v[126:127]
	s_nop 0
	v_cvt_pk_bf16_f32 v121, v122, v123
	v_lshlrev_b32_e32 v122, 16, v124
	v_pk_mul_f32 v[124:125], v[116:117], v[154:155] op_sel_hi:[1,0]
	v_or_b32_sdwa v120, v122, v120 dst_sel:DWORD dst_unused:UNUSED_PAD src0_sel:DWORD src1_sel:WORD_0
	v_pk_mul_f32 v[122:123], v[118:119], v[154:155] op_sel_hi:[1,0]
	v_exp_f32_e32 v124, v124
	v_exp_f32_e32 v125, v125
	v_exp_f32_e32 v122, v122
	v_exp_f32_e32 v123, v123
	v_add_f32_e32 v124, 1.0, v124
	v_add_f32_e32 v125, 1.0, v125
	v_rcp_f32_e32 v124, v124
	v_rcp_f32_e32 v125, v125
	v_add_f32_e32 v122, 1.0, v122
	v_add_f32_e32 v123, 1.0, v123
	v_rcp_f32_e32 v122, v122
	v_rcp_f32_e32 v123, v123
	v_pk_mul_f32 v[116:117], v[150:151], v[124:125] op_sel_hi:[0,1]
	v_pk_mul_f32 v[112:113], v[112:113], v[116:117]
	v_pk_mul_f32 v[118:119], v[150:151], v[122:123] op_sel_hi:[0,1]
	v_pk_mul_f32 v[114:115], v[114:115], v[118:119]
	v_cvt_pk_bf16_f32 v122, v112, v113
	v_mov_b64_e32 v[112:113], s[4:5]
	v_cvt_pk_bf16_f32 v123, v114, v115
	v_mad_i64_i32 v[116:117], s[18:19], v138, s9, v[112:113]
	v_lshlrev_b64 v[114:115], 1, v[148:149]
	v_lshl_add_u64 v[116:117], v[116:117], 0, v[114:115]
	global_store_dwordx4 v[116:117], v[120:123], off
	v_fmamk_f32 v116, v232, 0x3a800000, v194
	s_nop 0
	v_rsq_f32_e32 v116, v116
	s_nop 0
	v_mul_f32_e32 v118, 0xbfb8aa3b, v116
	v_pk_mul_f32 v[122:123], v[108:109], v[118:119] op_sel_hi:[1,0]
	v_pk_mul_f32 v[120:121], v[110:111], v[118:119] op_sel_hi:[1,0]
	v_exp_f32_e32 v117, v122
	v_mul_f32_e32 v116, v116, v116
	v_add_f32_e32 v117, 1.0, v117
	v_rcp_f32_e32 v122, v117
	v_exp_f32_e32 v117, v123
	s_nop 0
	v_add_f32_e32 v117, 1.0, v117
	v_rcp_f32_e32 v123, v117
	v_exp_f32_e32 v117, v120
	s_nop 0
	v_add_f32_e32 v117, 1.0, v117
	v_rcp_f32_e32 v120, v117
	v_exp_f32_e32 v117, v121
	s_nop 0
	v_add_f32_e32 v117, 1.0, v117
	v_rcp_f32_e32 v121, v117
	v_pk_mul_f32 v[108:109], v[116:117], v[122:123] op_sel_hi:[0,1]
	v_pk_mul_f32 v[104:105], v[104:105], v[108:109]
	v_pk_mul_f32 v[110:111], v[116:117], v[120:121] op_sel_hi:[0,1]
	v_pk_mul_f32 v[106:107], v[106:107], v[110:111]
	v_cvt_pk_bf16_f32 v108, v105, s0
	v_cvt_pk_bf16_f32 v104, v104, s0
	v_cvt_pk_bf16_f32 v105, v106, v107
	v_lshlrev_b32_e32 v106, 16, v108
	v_pk_mul_f32 v[108:109], v[100:101], v[118:119] op_sel_hi:[1,0]
	v_or_b32_sdwa v104, v106, v104 dst_sel:DWORD dst_unused:UNUSED_PAD src0_sel:DWORD src1_sel:WORD_0
	v_pk_mul_f32 v[106:107], v[102:103], v[118:119] op_sel_hi:[1,0]
	v_exp_f32_e32 v108, v108
	v_exp_f32_e32 v109, v109
	v_exp_f32_e32 v106, v106
	v_exp_f32_e32 v107, v107
	v_add_f32_e32 v108, 1.0, v108
	v_add_f32_e32 v109, 1.0, v109
	v_rcp_f32_e32 v108, v108
	v_rcp_f32_e32 v109, v109
	v_add_f32_e32 v106, 1.0, v106
	v_add_f32_e32 v107, 1.0, v107
	v_rcp_f32_e32 v106, v106
	v_rcp_f32_e32 v107, v107
	v_pk_mul_f32 v[100:101], v[116:117], v[108:109] op_sel_hi:[0,1]
	v_pk_mul_f32 v[96:97], v[96:97], v[100:101]
	v_pk_mul_f32 v[102:103], v[116:117], v[106:107] op_sel_hi:[0,1]
	v_pk_mul_f32 v[98:99], v[98:99], v[102:103]
	v_cvt_pk_bf16_f32 v106, v96, v97
	v_mad_i64_i32 v[96:97], s[18:19], v146, s9, v[112:113]
	v_cvt_pk_bf16_f32 v107, v98, v99
	v_lshl_add_u64 v[96:97], v[96:97], 0, v[114:115]
	global_store_dwordx4 v[96:97], v[104:107], off
	v_fmamk_f32 v96, v233, 0x3a800000, v194
	s_nop 0
	v_rsq_f32_e32 v96, v96
	s_nop 0
	v_mov_b32_e32 v97, v96
	v_mul_f32_e32 v96, 0xbfb8aa3b, v97
	v_pk_mul_f32 v[102:103], v[92:93], v[96:97] op_sel_hi:[1,0]
	v_mul_f32_e32 v98, v97, v97
	v_pk_mul_f32 v[100:101], v[94:95], v[96:97] op_sel_hi:[1,0]
	v_exp_f32_e32 v97, v102
	s_nop 0
	v_add_f32_e32 v97, 1.0, v97
	v_rcp_f32_e32 v102, v97
	v_exp_f32_e32 v97, v103
	s_nop 0
	v_add_f32_e32 v97, 1.0, v97
	v_rcp_f32_e32 v103, v97
	v_exp_f32_e32 v97, v100
	v_pk_mul_f32 v[92:93], v[98:99], v[102:103] op_sel_hi:[0,1]
	v_add_f32_e32 v97, 1.0, v97
	v_rcp_f32_e32 v100, v97
	v_exp_f32_e32 v97, v101
	v_pk_mul_f32 v[88:89], v[88:89], v[92:93]
	v_add_f32_e32 v97, 1.0, v97
	v_rcp_f32_e32 v101, v97
	v_cvt_pk_bf16_f32 v92, v89, s0
	v_cvt_pk_bf16_f32 v88, v88, s0
	v_pk_mul_f32 v[94:95], v[98:99], v[100:101] op_sel_hi:[0,1]
	v_pk_mul_f32 v[90:91], v[90:91], v[94:95]
	s_nop 0
	v_cvt_pk_bf16_f32 v89, v90, v91
	v_lshlrev_b32_e32 v90, 16, v92
	v_pk_mul_f32 v[92:93], v[84:85], v[96:97] op_sel_hi:[1,0]
	v_or_b32_sdwa v88, v90, v88 dst_sel:DWORD dst_unused:UNUSED_PAD src0_sel:DWORD src1_sel:WORD_0
	v_pk_mul_f32 v[90:91], v[86:87], v[96:97] op_sel_hi:[1,0]
	v_exp_f32_e32 v92, v92
	v_exp_f32_e32 v93, v93
	v_exp_f32_e32 v90, v90
	v_exp_f32_e32 v91, v91
	v_add_f32_e32 v92, 1.0, v92
	v_add_f32_e32 v93, 1.0, v93
	v_rcp_f32_e32 v92, v92
	v_rcp_f32_e32 v93, v93
	v_add_f32_e32 v90, 1.0, v90
	v_add_f32_e32 v91, 1.0, v91
	v_rcp_f32_e32 v90, v90
	v_rcp_f32_e32 v91, v91
	v_pk_mul_f32 v[84:85], v[98:99], v[92:93] op_sel_hi:[0,1]
	v_pk_mul_f32 v[80:81], v[80:81], v[84:85]
	v_pk_mul_f32 v[86:87], v[98:99], v[90:91] op_sel_hi:[0,1]
	v_pk_mul_f32 v[82:83], v[82:83], v[86:87]
	v_cvt_pk_bf16_f32 v90, v80, v81
	v_mad_i64_i32 v[80:81], s[18:19], v144, s9, v[112:113]
	v_cvt_pk_bf16_f32 v91, v82, v83
	v_lshl_add_u64 v[80:81], v[80:81], 0, v[114:115]
	global_store_dwordx4 v[80:81], v[88:91], off
	v_fmamk_f32 v80, v234, 0x3a800000, v194
	s_nop 0
	v_rsq_f32_e32 v80, v80
	s_nop 0
	v_mov_b32_e32 v81, v80
	v_mul_f32_e32 v80, 0xbfb8aa3b, v81
	v_pk_mul_f32 v[86:87], v[76:77], v[80:81] op_sel_hi:[1,0]
	v_mul_f32_e32 v82, v81, v81
	v_pk_mul_f32 v[84:85], v[78:79], v[80:81] op_sel_hi:[1,0]
	v_exp_f32_e32 v81, v86
	s_nop 0
	v_add_f32_e32 v81, 1.0, v81
	v_rcp_f32_e32 v86, v81
	v_exp_f32_e32 v81, v87
	s_nop 0
	v_add_f32_e32 v81, 1.0, v81
	v_rcp_f32_e32 v87, v81
	v_exp_f32_e32 v81, v84
	v_pk_mul_f32 v[76:77], v[82:83], v[86:87] op_sel_hi:[0,1]
	v_add_f32_e32 v81, 1.0, v81
	v_rcp_f32_e32 v84, v81
	v_exp_f32_e32 v81, v85
	v_pk_mul_f32 v[72:73], v[72:73], v[76:77]
	v_add_f32_e32 v81, 1.0, v81
	v_rcp_f32_e32 v85, v81
	v_cvt_pk_bf16_f32 v76, v73, s0
	v_cvt_pk_bf16_f32 v72, v72, s0
	v_pk_mul_f32 v[78:79], v[82:83], v[84:85] op_sel_hi:[0,1]
	v_pk_mul_f32 v[74:75], v[74:75], v[78:79]
	s_nop 0
	v_cvt_pk_bf16_f32 v73, v74, v75
	v_lshlrev_b32_e32 v74, 16, v76
	v_pk_mul_f32 v[76:77], v[68:69], v[80:81] op_sel_hi:[1,0]
	v_or_b32_sdwa v72, v74, v72 dst_sel:DWORD dst_unused:UNUSED_PAD src0_sel:DWORD src1_sel:WORD_0
	v_pk_mul_f32 v[74:75], v[70:71], v[80:81] op_sel_hi:[1,0]
	v_exp_f32_e32 v76, v76
	v_exp_f32_e32 v77, v77
	v_exp_f32_e32 v74, v74
	v_exp_f32_e32 v75, v75
	v_add_f32_e32 v76, 1.0, v76
	v_add_f32_e32 v77, 1.0, v77
	v_rcp_f32_e32 v76, v76
	v_rcp_f32_e32 v77, v77
	v_add_f32_e32 v74, 1.0, v74
	v_add_f32_e32 v75, 1.0, v75
	v_rcp_f32_e32 v74, v74
	v_rcp_f32_e32 v75, v75
	v_pk_mul_f32 v[68:69], v[82:83], v[76:77] op_sel_hi:[0,1]
	v_pk_mul_f32 v[64:65], v[64:65], v[68:69]
	v_add_u32_e32 v69, 0x90, v138
	v_pk_mul_f32 v[70:71], v[82:83], v[74:75] op_sel_hi:[0,1]
	v_pk_mul_f32 v[66:67], v[66:67], v[70:71]
	v_cvt_pk_bf16_f32 v74, v64, v65
	v_mad_i64_i32 v[64:65], s[18:19], v142, s9, v[112:113]
	v_cvt_pk_bf16_f32 v75, v66, v67
	v_lshl_add_u64 v[64:65], v[64:65], 0, v[114:115]
	global_store_dwordx4 v[64:65], v[72:75], off
	v_add_u32_e32 v67, 0x80, v138
	v_add_u32_e32 v66, 0xa0, v138
	v_add_u32_e32 v64, 0xb0, v138
	v_fmamk_f32 v68, v235, 0x3a800000, v194
	s_nop 0
	v_rsq_f32_e32 v68, v68
	s_nop 0
	v_mov_b32_e32 v70, v68
	v_mul_f32_e32 v68, 0xbfb8aa3b, v70
	v_pk_mul_f32 v[74:75], v[60:61], v[68:69] op_sel_hi:[1,0]
	v_pk_mul_f32 v[72:73], v[62:63], v[68:69] op_sel_hi:[1,0]
	v_exp_f32_e32 v74, v74
	v_exp_f32_e32 v75, v75
	v_exp_f32_e32 v72, v72
	v_exp_f32_e32 v73, v73
	v_add_f32_e32 v74, 1.0, v74
	v_add_f32_e32 v75, 1.0, v75
	v_rcp_f32_e32 v74, v74
	v_rcp_f32_e32 v75, v75
	v_add_f32_e32 v72, 1.0, v72
	v_add_f32_e32 v73, 1.0, v73
	v_rcp_f32_e32 v72, v72
	v_rcp_f32_e32 v73, v73
	v_mul_f32_e32 v70, v70, v70
	v_pk_mul_f32 v[60:61], v[70:71], v[74:75] op_sel_hi:[0,1]
	v_pk_mul_f32 v[56:57], v[56:57], v[60:61]
	v_pk_mul_f32 v[62:63], v[70:71], v[72:73] op_sel_hi:[0,1]
	v_pk_mul_f32 v[58:59], v[58:59], v[62:63]
	v_cvt_pk_bf16_f32 v60, v57, s0
	v_cvt_pk_bf16_f32 v56, v56, s0
	v_cvt_pk_bf16_f32 v57, v58, v59
	v_lshlrev_b32_e32 v58, 16, v60
	v_pk_mul_f32 v[60:61], v[52:53], v[68:69] op_sel_hi:[1,0]
	v_or_b32_sdwa v56, v58, v56 dst_sel:DWORD dst_unused:UNUSED_PAD src0_sel:DWORD src1_sel:WORD_0
	v_pk_mul_f32 v[58:59], v[54:55], v[68:69] op_sel_hi:[1,0]
	v_exp_f32_e32 v60, v60
	v_exp_f32_e32 v61, v61
	v_exp_f32_e32 v58, v58
	v_exp_f32_e32 v59, v59
	v_add_f32_e32 v60, 1.0, v60
	v_add_f32_e32 v61, 1.0, v61
	v_rcp_f32_e32 v60, v60
	v_rcp_f32_e32 v61, v61
	v_add_f32_e32 v58, 1.0, v58
	v_add_f32_e32 v59, 1.0, v59
	v_rcp_f32_e32 v58, v58
	v_rcp_f32_e32 v59, v59
	v_pk_mul_f32 v[52:53], v[70:71], v[60:61] op_sel_hi:[0,1]
	v_pk_mul_f32 v[48:49], v[48:49], v[52:53]
	v_pk_mul_f32 v[54:55], v[70:71], v[58:59] op_sel_hi:[0,1]
	v_pk_mul_f32 v[50:51], v[50:51], v[54:55]
	v_cvt_pk_bf16_f32 v58, v48, v49
	v_mad_i64_i32 v[48:49], s[18:19], v67, s9, v[112:113]
	v_cvt_pk_bf16_f32 v59, v50, v51
	v_lshl_add_u64 v[48:49], v[48:49], 0, v[114:115]
	global_store_dwordx4 v[48:49], v[56:59], off
	v_fmamk_f32 v48, v236, 0x3a800000, v194
	s_nop 0
	v_rsq_f32_e32 v48, v48
	s_nop 0
	v_mov_b32_e32 v49, v48
	v_mul_f32_e32 v48, 0xbfb8aa3b, v49
	v_pk_mul_f32 v[54:55], v[44:45], v[48:49] op_sel_hi:[1,0]
	v_mul_f32_e32 v50, v49, v49
	v_pk_mul_f32 v[52:53], v[46:47], v[48:49] op_sel_hi:[1,0]
	v_exp_f32_e32 v49, v54
	s_nop 0
	v_add_f32_e32 v49, 1.0, v49
	v_rcp_f32_e32 v54, v49
	v_exp_f32_e32 v49, v55
	s_nop 0
	v_add_f32_e32 v49, 1.0, v49
	v_rcp_f32_e32 v55, v49
	v_exp_f32_e32 v49, v52
	v_pk_mul_f32 v[44:45], v[50:51], v[54:55] op_sel_hi:[0,1]
	v_add_f32_e32 v49, 1.0, v49
	v_rcp_f32_e32 v52, v49
	v_exp_f32_e32 v49, v53
	v_pk_mul_f32 v[40:41], v[40:41], v[44:45]
	v_add_f32_e32 v49, 1.0, v49
	v_rcp_f32_e32 v53, v49
	v_cvt_pk_bf16_f32 v44, v41, s0
	v_cvt_pk_bf16_f32 v40, v40, s0
	v_pk_mul_f32 v[46:47], v[50:51], v[52:53] op_sel_hi:[0,1]
	v_pk_mul_f32 v[42:43], v[42:43], v[46:47]
	s_nop 0
	v_cvt_pk_bf16_f32 v41, v42, v43
	v_lshlrev_b32_e32 v42, 16, v44
	v_pk_mul_f32 v[44:45], v[36:37], v[48:49] op_sel_hi:[1,0]
	v_or_b32_sdwa v40, v42, v40 dst_sel:DWORD dst_unused:UNUSED_PAD src0_sel:DWORD src1_sel:WORD_0
	v_pk_mul_f32 v[42:43], v[38:39], v[48:49] op_sel_hi:[1,0]
	v_exp_f32_e32 v44, v44
	v_exp_f32_e32 v45, v45
	v_exp_f32_e32 v42, v42
	v_exp_f32_e32 v43, v43
	v_add_f32_e32 v44, 1.0, v44
	v_add_f32_e32 v45, 1.0, v45
	v_rcp_f32_e32 v44, v44
	v_rcp_f32_e32 v45, v45
	v_add_f32_e32 v42, 1.0, v42
	v_add_f32_e32 v43, 1.0, v43
	v_rcp_f32_e32 v42, v42
	v_rcp_f32_e32 v43, v43
	v_pk_mul_f32 v[36:37], v[50:51], v[44:45] op_sel_hi:[0,1]
	v_pk_mul_f32 v[32:33], v[32:33], v[36:37]
	v_pk_mul_f32 v[38:39], v[50:51], v[42:43] op_sel_hi:[0,1]
	v_pk_mul_f32 v[34:35], v[34:35], v[38:39]
	v_cvt_pk_bf16_f32 v42, v32, v33
	v_mad_i64_i32 v[32:33], s[18:19], v69, s9, v[112:113]
	v_cvt_pk_bf16_f32 v43, v34, v35
	v_lshl_add_u64 v[32:33], v[32:33], 0, v[114:115]
	global_store_dwordx4 v[32:33], v[40:43], off
	v_fmamk_f32 v32, v237, 0x3a800000, v194
	s_nop 0
	v_rsq_f32_e32 v32, v32
	s_nop 0
	v_mov_b32_e32 v33, v32
	v_mul_f32_e32 v32, 0xbfb8aa3b, v33
	v_pk_mul_f32 v[38:39], v[28:29], v[32:33] op_sel_hi:[1,0]
	v_mul_f32_e32 v34, v33, v33
	v_pk_mul_f32 v[36:37], v[30:31], v[32:33] op_sel_hi:[1,0]
	v_exp_f32_e32 v33, v38
	s_nop 0
	v_add_f32_e32 v33, 1.0, v33
	v_rcp_f32_e32 v38, v33
	v_exp_f32_e32 v33, v39
	s_nop 0
	v_add_f32_e32 v33, 1.0, v33
	v_rcp_f32_e32 v39, v33
	v_exp_f32_e32 v33, v36
	v_pk_mul_f32 v[28:29], v[34:35], v[38:39] op_sel_hi:[0,1]
	v_add_f32_e32 v33, 1.0, v33
	v_rcp_f32_e32 v36, v33
	v_exp_f32_e32 v33, v37
	v_pk_mul_f32 v[24:25], v[24:25], v[28:29]
	v_add_f32_e32 v33, 1.0, v33
	v_rcp_f32_e32 v37, v33
	v_cvt_pk_bf16_f32 v28, v25, s0
	v_cvt_pk_bf16_f32 v24, v24, s0
	v_pk_mul_f32 v[30:31], v[34:35], v[36:37] op_sel_hi:[0,1]
	v_pk_mul_f32 v[26:27], v[26:27], v[30:31]
	s_nop 0
	v_cvt_pk_bf16_f32 v25, v26, v27
	v_lshlrev_b32_e32 v26, 16, v28
	v_pk_mul_f32 v[28:29], v[20:21], v[32:33] op_sel_hi:[1,0]
	v_or_b32_sdwa v24, v26, v24 dst_sel:DWORD dst_unused:UNUSED_PAD src0_sel:DWORD src1_sel:WORD_0
	v_pk_mul_f32 v[26:27], v[22:23], v[32:33] op_sel_hi:[1,0]
	v_exp_f32_e32 v28, v28
	v_exp_f32_e32 v29, v29
	v_exp_f32_e32 v26, v26
	v_exp_f32_e32 v27, v27
	v_add_f32_e32 v28, 1.0, v28
	v_add_f32_e32 v29, 1.0, v29
	v_rcp_f32_e32 v28, v28
	v_rcp_f32_e32 v29, v29
	v_add_f32_e32 v26, 1.0, v26
	v_add_f32_e32 v27, 1.0, v27
	v_rcp_f32_e32 v26, v26
	v_rcp_f32_e32 v27, v27
	v_pk_mul_f32 v[20:21], v[34:35], v[28:29] op_sel_hi:[0,1]
	v_pk_mul_f32 v[16:17], v[16:17], v[20:21]
	v_pk_mul_f32 v[22:23], v[34:35], v[26:27] op_sel_hi:[0,1]
	v_pk_mul_f32 v[18:19], v[18:19], v[22:23]
	v_cvt_pk_bf16_f32 v26, v16, v17
	v_mad_i64_i32 v[16:17], s[18:19], v66, s9, v[112:113]
	v_cvt_pk_bf16_f32 v27, v18, v19
	v_lshl_add_u64 v[16:17], v[16:17], 0, v[114:115]
	global_store_dwordx4 v[16:17], v[24:27], off
	v_fmamk_f32 v16, v238, 0x3a800000, v194
	s_nop 0
	v_rsq_f32_e32 v16, v16
	s_nop 0
	v_mov_b32_e32 v17, v16
	v_mul_f32_e32 v16, 0xbfb8aa3b, v17
	v_pk_mul_f32 v[22:23], v[12:13], v[16:17] op_sel_hi:[1,0]
	v_mul_f32_e32 v18, v17, v17
	v_pk_mul_f32 v[20:21], v[14:15], v[16:17] op_sel_hi:[1,0]
	v_exp_f32_e32 v17, v22
	s_and_b64 vcc, exec, s[0:1]
	v_add_f32_e32 v17, 1.0, v17
	v_rcp_f32_e32 v22, v17
	v_exp_f32_e32 v17, v23
	s_nop 0
	v_add_f32_e32 v17, 1.0, v17
	v_rcp_f32_e32 v23, v17
	v_exp_f32_e32 v17, v20
	v_pk_mul_f32 v[12:13], v[18:19], v[22:23] op_sel_hi:[0,1]
	v_add_f32_e32 v17, 1.0, v17
	v_rcp_f32_e32 v20, v17
	v_exp_f32_e32 v17, v21
	v_pk_mul_f32 v[8:9], v[8:9], v[12:13]
	v_add_f32_e32 v17, 1.0, v17
	v_rcp_f32_e32 v21, v17
	v_cvt_pk_bf16_f32 v12, v9, s0
	v_cvt_pk_bf16_f32 v8, v8, s0
	v_pk_mul_f32 v[14:15], v[18:19], v[20:21] op_sel_hi:[0,1]
	v_pk_mul_f32 v[10:11], v[10:11], v[14:15]
	s_nop 0
	v_cvt_pk_bf16_f32 v9, v10, v11
	v_lshlrev_b32_e32 v10, 16, v12
	v_pk_mul_f32 v[12:13], v[4:5], v[16:17] op_sel_hi:[1,0]
	v_or_b32_sdwa v8, v10, v8 dst_sel:DWORD dst_unused:UNUSED_PAD src0_sel:DWORD src1_sel:WORD_0
	v_pk_mul_f32 v[10:11], v[6:7], v[16:17] op_sel_hi:[1,0]
	v_exp_f32_e32 v12, v12
	v_exp_f32_e32 v13, v13
	v_exp_f32_e32 v10, v10
	v_exp_f32_e32 v11, v11
	v_add_f32_e32 v12, 1.0, v12
	v_add_f32_e32 v13, 1.0, v13
	v_rcp_f32_e32 v12, v12
	v_rcp_f32_e32 v13, v13
	v_add_f32_e32 v10, 1.0, v10
	v_add_f32_e32 v11, 1.0, v11
	v_rcp_f32_e32 v10, v10
	v_rcp_f32_e32 v11, v11
	v_pk_mul_f32 v[4:5], v[18:19], v[12:13] op_sel_hi:[0,1]
	v_pk_mul_f32 v[0:1], v[0:1], v[4:5]
	v_pk_mul_f32 v[6:7], v[18:19], v[10:11] op_sel_hi:[0,1]
	v_pk_mul_f32 v[2:3], v[2:3], v[6:7]
	v_cvt_pk_bf16_f32 v10, v0, v1
	v_mad_i64_i32 v[0:1], s[18:19], v64, s9, v[112:113]
	v_cvt_pk_bf16_f32 v11, v2, v3
	v_lshl_add_u64 v[0:1], v[0:1], 0, v[114:115]
	s_mov_b64 s[18:19], s[14:15]
	global_store_dwordx4 v[0:1], v[8:11], off
	s_cbranch_vccz .LBB0_2801
	s_waitcnt vmcnt(0)
	s_cmpk_gt_u32 s25, 0xff
	s_cbranch_scc1 .LBB0_2808
	s_barrier

.LBB0_3618:
	s_add_u32 s20, s18, 0x100
	s_addc_u32 s21, s19, 0
	s_add_i32 s45, 0, 0x10000
	ds_read_b128 v[128:131], v202
	ds_read_b128 v[132:135], v202 offset:1024
	ds_read_b128 v[136:139], v202 offset:2048
	ds_read_b128 v[140:143], v202 offset:3072
	s_cmp_eq_u32 s44, 40
	s_cselect_b32 s25, s5, s21
	s_cselect_b32 s24, s4, s20
	s_cselect_b32 s23, s7, s43
	s_cselect_b32 s22, s6, s33
	s_add_i32 m0, s30, 0xc000
	ds_read_b128 v[144:147], v198
	ds_read_b128 v[148:151], v198 offset:1024
	ds_read_b128 v[152:155], v198 offset:2048
	ds_read_b128 v[156:159], v198 offset:3072
	ds_read_b128 v[160:163], v198 offset:4096
	ds_read_b128 v[164:167], v198 offset:5120
	ds_read_b128 v[168:171], v198 offset:6144
	ds_read_b128 v[172:175], v198 offset:7168
	global_load_lds_dwordx4 v214, s[18:19]
	s_add_i32 m0, s30, 0xe000
	s_nop 0
	global_load_lds_dwordx4 v212, s[18:19]
	s_waitcnt lgkmcnt(8)
	s_barrier
	s_waitcnt lgkmcnt(0)
	s_setprio 1
	v_mfma_f32_16x16x32_bf16 v[124:127], v[128:131], v[144:147], v[124:127]
	v_mfma_f32_16x16x32_bf16 v[120:123], v[136:139], v[144:147], v[120:123]
	v_mfma_f32_16x16x32_bf16 v[108:111], v[128:131], v[152:155], v[108:111]
	v_mfma_f32_16x16x32_bf16 v[104:107], v[136:139], v[152:155], v[104:107]
	v_mfma_f32_16x16x32_bf16 v[92:95], v[128:131], v[160:163], v[92:95]
	v_mfma_f32_16x16x32_bf16 v[88:91], v[136:139], v[160:163], v[88:91]
	v_mfma_f32_16x16x32_bf16 v[76:79], v[128:131], v[168:171], v[76:79]
	v_mfma_f32_16x16x32_bf16 v[72:75], v[136:139], v[168:171], v[72:75]
	v_mfma_f32_16x16x32_bf16 v[124:127], v[132:135], v[148:151], v[124:127]
	v_mfma_f32_16x16x32_bf16 v[120:123], v[140:143], v[148:151], v[120:123]
	v_mfma_f32_16x16x32_bf16 v[108:111], v[132:135], v[156:159], v[108:111]
	v_mfma_f32_16x16x32_bf16 v[104:107], v[140:143], v[156:159], v[104:107]
	v_mfma_f32_16x16x32_bf16 v[92:95], v[132:135], v[164:167], v[92:95]
	v_mfma_f32_16x16x32_bf16 v[88:91], v[140:143], v[164:167], v[88:91]
	v_mfma_f32_16x16x32_bf16 v[76:79], v[132:135], v[172:175], v[76:79]
	v_mfma_f32_16x16x32_bf16 v[72:75], v[140:143], v[172:175], v[72:75]
	s_setprio 0
	s_barrier
	s_add_i32 s46, 0, 0x14000
	s_add_i32 s18, s45, s29
	s_mov_b32 m0, s18
	ds_read_b128 v[176:179], v203
	ds_read_b128 v[180:183], v203 offset:1024
	ds_read_b128 v[184:187], v203 offset:2048
	ds_read_b128 v[188:191], v203 offset:3072
	global_load_lds_dwordx4 v192, s[22:23]
	s_add_i32 m0, s18, 0x2000
	s_nop 0
	global_load_lds_dwordx4 v210, s[22:23]
	s_barrier
	s_waitcnt lgkmcnt(0)
	s_setprio 1
	v_mfma_f32_16x16x32_bf16 v[116:119], v[176:179], v[144:147], v[116:119]
	v_mfma_f32_16x16x32_bf16 v[112:115], v[184:187], v[144:147], v[112:115]
	v_mfma_f32_16x16x32_bf16 v[100:103], v[176:179], v[152:155], v[100:103]
	v_mfma_f32_16x16x32_bf16 v[96:99], v[184:187], v[152:155], v[96:99]
	v_mfma_f32_16x16x32_bf16 v[84:87], v[176:179], v[160:163], v[84:87]
	v_mfma_f32_16x16x32_bf16 v[80:83], v[184:187], v[160:163], v[80:83]
	v_mfma_f32_16x16x32_bf16 v[68:71], v[176:179], v[168:171], v[68:71]
	v_mfma_f32_16x16x32_bf16 v[64:67], v[184:187], v[168:171], v[64:67]
	v_mfma_f32_16x16x32_bf16 v[116:119], v[180:183], v[148:151], v[116:119]
	v_mfma_f32_16x16x32_bf16 v[112:115], v[188:191], v[148:151], v[112:115]
	v_mfma_f32_16x16x32_bf16 v[100:103], v[180:183], v[156:159], v[100:103]
	v_mfma_f32_16x16x32_bf16 v[96:99], v[188:191], v[156:159], v[96:99]
	v_mfma_f32_16x16x32_bf16 v[84:87], v[180:183], v[164:167], v[84:87]
	v_mfma_f32_16x16x32_bf16 v[80:83], v[188:191], v[164:167], v[80:83]
	v_mfma_f32_16x16x32_bf16 v[68:71], v[180:183], v[172:175], v[68:71]
	v_mfma_f32_16x16x32_bf16 v[64:67], v[188:191], v[172:175], v[64:67]
	s_setprio 0
	s_mov_b32 m0, s30
	s_add_u32 vcc_lo, s24, 0x80
	s_addc_u32 vcc_hi, s25, 0
	s_barrier
	ds_read_b128 v[144:147], v198 offset:16384
	ds_read_b128 v[148:151], v198 offset:17408
	ds_read_b128 v[152:155], v198 offset:18432
	ds_read_b128 v[156:159], v198 offset:19456
	ds_read_b128 v[160:163], v198 offset:20480
	ds_read_b128 v[164:167], v198 offset:21504
	ds_read_b128 v[168:171], v198 offset:22528
	ds_read_b128 v[172:175], v198 offset:23552
	global_load_lds_dwordx4 v206, s[24:25]
	s_mov_b32 m0, s31
	s_nop 0
	global_load_lds_dwordx4 v208, s[24:25]
	s_barrier
	s_waitcnt lgkmcnt(0)
	s_setprio 1
	v_mfma_f32_16x16x32_bf16 v[60:63], v[128:131], v[144:147], v[60:63]
	v_mfma_f32_16x16x32_bf16 v[56:59], v[136:139], v[144:147], v[56:59]
	v_mfma_f32_16x16x32_bf16 v[44:47], v[128:131], v[152:155], v[44:47]
	v_mfma_f32_16x16x32_bf16 v[40:43], v[136:139], v[152:155], v[40:43]
	v_mfma_f32_16x16x32_bf16 v[28:31], v[128:131], v[160:163], v[28:31]
	v_mfma_f32_16x16x32_bf16 v[24:27], v[136:139], v[160:163], v[24:27]
	v_mfma_f32_16x16x32_bf16 v[12:15], v[128:131], v[168:171], v[12:15]
	v_mfma_f32_16x16x32_bf16 v[8:11], v[136:139], v[168:171], v[8:11]
	v_mfma_f32_16x16x32_bf16 v[60:63], v[132:135], v[148:151], v[60:63]
	v_mfma_f32_16x16x32_bf16 v[56:59], v[140:143], v[148:151], v[56:59]
	v_mfma_f32_16x16x32_bf16 v[44:47], v[132:135], v[156:159], v[44:47]
	v_mfma_f32_16x16x32_bf16 v[40:43], v[140:143], v[156:159], v[40:43]
	v_mfma_f32_16x16x32_bf16 v[28:31], v[132:135], v[164:167], v[28:31]
	v_mfma_f32_16x16x32_bf16 v[24:27], v[140:143], v[164:167], v[24:27]
	v_mfma_f32_16x16x32_bf16 v[12:15], v[132:135], v[172:175], v[12:15]
	v_mfma_f32_16x16x32_bf16 v[8:11], v[140:143], v[172:175], v[8:11]
	s_setprio 0
	s_barrier
	s_add_u32 s18, s22, 0xb0000
	s_addc_u32 s19, s23, 0
	s_add_i32 s45, s46, s29
	s_mov_b32 m0, s45
	s_nop 0
	global_load_lds_dwordx4 v192, s[18:19]
	s_add_i32 m0, s45, 0x2000
	s_nop 0
	global_load_lds_dwordx4 v210, s[18:19]
	s_waitcnt vmcnt(6)
	s_barrier
	s_setprio 1
	v_mfma_f32_16x16x32_bf16 v[52:55], v[176:179], v[144:147], v[52:55]
	v_mfma_f32_16x16x32_bf16 v[48:51], v[184:187], v[144:147], v[48:51]
	v_mfma_f32_16x16x32_bf16 v[36:39], v[176:179], v[152:155], v[36:39]
	v_mfma_f32_16x16x32_bf16 v[32:35], v[184:187], v[152:155], v[32:35]
	v_mfma_f32_16x16x32_bf16 v[20:23], v[176:179], v[160:163], v[20:23]
	v_mfma_f32_16x16x32_bf16 v[16:19], v[184:187], v[160:163], v[16:19]
	v_mfma_f32_16x16x32_bf16 v[4:7], v[176:179], v[168:171], v[4:7]
	v_mfma_f32_16x16x32_bf16 v[0:3], v[184:187], v[168:171], v[0:3]
	v_mfma_f32_16x16x32_bf16 v[52:55], v[180:183], v[148:151], v[52:55]
	v_mfma_f32_16x16x32_bf16 v[48:51], v[188:191], v[148:151], v[48:51]
	v_mfma_f32_16x16x32_bf16 v[36:39], v[180:183], v[156:159], v[36:39]
	v_mfma_f32_16x16x32_bf16 v[32:35], v[188:191], v[156:159], v[32:35]
	v_mfma_f32_16x16x32_bf16 v[20:23], v[180:183], v[164:167], v[20:23]
	v_mfma_f32_16x16x32_bf16 v[16:19], v[188:191], v[164:167], v[16:19]
	v_mfma_f32_16x16x32_bf16 v[4:7], v[180:183], v[172:175], v[4:7]
	v_mfma_f32_16x16x32_bf16 v[0:3], v[188:191], v[172:175], v[0:3]
	s_setprio 0
	s_add_i32 s45, 0, 0x18000
	s_barrier
	ds_read_b128 v[128:131], v204
	ds_read_b128 v[132:135], v204 offset:1024
	ds_read_b128 v[136:139], v204 offset:2048
	ds_read_b128 v[140:143], v204 offset:3072
	s_add_u32 s18, s24, 0xb0000
	s_addc_u32 s19, s25, 0
	s_mov_b32 m0, s34
	ds_read_b128 v[144:147], v198 offset:32768
	ds_read_b128 v[148:151], v198 offset:33792
	ds_read_b128 v[152:155], v198 offset:34816
	ds_read_b128 v[156:159], v198 offset:35840
	ds_read_b128 v[160:163], v198 offset:36864
	ds_read_b128 v[164:167], v198 offset:37888
	ds_read_b128 v[168:171], v198 offset:38912
	ds_read_b128 v[172:175], v198 offset:39936
	global_load_lds_dwordx4 v206, s[18:19]
	s_mov_b32 m0, s35
	s_nop 0
	global_load_lds_dwordx4 v208, s[18:19]
	s_waitcnt lgkmcnt(8)
	s_barrier
	s_waitcnt lgkmcnt(0)
	s_setprio 1
	v_mfma_f32_16x16x32_bf16 v[124:127], v[128:131], v[144:147], v[124:127]
	v_mfma_f32_16x16x32_bf16 v[120:123], v[136:139], v[144:147], v[120:123]
	v_mfma_f32_16x16x32_bf16 v[108:111], v[128:131], v[152:155], v[108:111]
	v_mfma_f32_16x16x32_bf16 v[104:107], v[136:139], v[152:155], v[104:107]
	v_mfma_f32_16x16x32_bf16 v[92:95], v[128:131], v[160:163], v[92:95]
	v_mfma_f32_16x16x32_bf16 v[88:91], v[136:139], v[160:163], v[88:91]
	v_mfma_f32_16x16x32_bf16 v[76:79], v[128:131], v[168:171], v[76:79]
	v_mfma_f32_16x16x32_bf16 v[72:75], v[136:139], v[168:171], v[72:75]
	v_mfma_f32_16x16x32_bf16 v[124:127], v[132:135], v[148:151], v[124:127]
	v_mfma_f32_16x16x32_bf16 v[120:123], v[140:143], v[148:151], v[120:123]
	v_mfma_f32_16x16x32_bf16 v[108:111], v[132:135], v[156:159], v[108:111]
	v_mfma_f32_16x16x32_bf16 v[104:107], v[140:143], v[156:159], v[104:107]
	v_mfma_f32_16x16x32_bf16 v[92:95], v[132:135], v[164:167], v[92:95]
	v_mfma_f32_16x16x32_bf16 v[88:91], v[140:143], v[164:167], v[88:91]
	v_mfma_f32_16x16x32_bf16 v[76:79], v[132:135], v[172:175], v[76:79]
	v_mfma_f32_16x16x32_bf16 v[72:75], v[140:143], v[172:175], v[72:75]
	s_setprio 0
	s_barrier
	s_add_i32 s24, 0, 0x1c000
	s_add_i32 s18, s45, s29
	s_add_u32 s100, s22, 0x80
	s_addc_u32 s101, s23, 0
	s_mov_b32 m0, s18
	ds_read_b128 v[176:179], v205
	ds_read_b128 v[180:183], v205 offset:1024
	ds_read_b128 v[184:187], v205 offset:2048
	ds_read_b128 v[188:191], v205 offset:3072
	global_load_lds_dwordx4 v192, s[100:101]
	s_add_i32 m0, s18, 0x2000
	s_nop 0
	global_load_lds_dwordx4 v210, s[100:101]
	s_barrier
	s_waitcnt lgkmcnt(0)
	s_setprio 1
	v_mfma_f32_16x16x32_bf16 v[116:119], v[176:179], v[144:147], v[116:119]
	v_mfma_f32_16x16x32_bf16 v[112:115], v[184:187], v[144:147], v[112:115]
	v_mfma_f32_16x16x32_bf16 v[100:103], v[176:179], v[152:155], v[100:103]
	v_mfma_f32_16x16x32_bf16 v[96:99], v[184:187], v[152:155], v[96:99]
	v_mfma_f32_16x16x32_bf16 v[84:87], v[176:179], v[160:163], v[84:87]
	v_mfma_f32_16x16x32_bf16 v[80:83], v[184:187], v[160:163], v[80:83]
	v_mfma_f32_16x16x32_bf16 v[68:71], v[176:179], v[168:171], v[68:71]
	v_mfma_f32_16x16x32_bf16 v[64:67], v[184:187], v[168:171], v[64:67]
	v_mfma_f32_16x16x32_bf16 v[116:119], v[180:183], v[148:151], v[116:119]
	v_mfma_f32_16x16x32_bf16 v[112:115], v[188:191], v[148:151], v[112:115]
	v_mfma_f32_16x16x32_bf16 v[100:103], v[180:183], v[156:159], v[100:103]
	v_mfma_f32_16x16x32_bf16 v[96:99], v[188:191], v[156:159], v[96:99]
	v_mfma_f32_16x16x32_bf16 v[84:87], v[180:183], v[164:167], v[84:87]
	v_mfma_f32_16x16x32_bf16 v[80:83], v[188:191], v[164:167], v[80:83]
	v_mfma_f32_16x16x32_bf16 v[68:71], v[180:183], v[172:175], v[68:71]
	v_mfma_f32_16x16x32_bf16 v[64:67], v[188:191], v[172:175], v[64:67]
	s_setprio 0
	s_mov_b32 m0, s36
	s_barrier
	ds_read_b128 v[144:147], v198 offset:49152
	ds_read_b128 v[148:151], v198 offset:50176
	ds_read_b128 v[152:155], v198 offset:51200
	ds_read_b128 v[156:159], v198 offset:52224
	ds_read_b128 v[160:163], v198 offset:53248
	ds_read_b128 v[164:167], v198 offset:54272
	ds_read_b128 v[168:171], v198 offset:55296
	ds_read_b128 v[172:175], v198 offset:56320
	global_load_lds_dwordx4 v206, vcc
	s_mov_b32 m0, s37
	s_nop 0
	global_load_lds_dwordx4 v208, vcc
	s_barrier
	s_waitcnt lgkmcnt(0)
	s_setprio 1
	v_mfma_f32_16x16x32_bf16 v[60:63], v[128:131], v[144:147], v[60:63]
	v_mfma_f32_16x16x32_bf16 v[56:59], v[136:139], v[144:147], v[56:59]
	v_mfma_f32_16x16x32_bf16 v[44:47], v[128:131], v[152:155], v[44:47]
	v_mfma_f32_16x16x32_bf16 v[40:43], v[136:139], v[152:155], v[40:43]
	v_mfma_f32_16x16x32_bf16 v[28:31], v[128:131], v[160:163], v[28:31]
	v_mfma_f32_16x16x32_bf16 v[24:27], v[136:139], v[160:163], v[24:27]
	v_mfma_f32_16x16x32_bf16 v[12:15], v[128:131], v[168:171], v[12:15]
	v_mfma_f32_16x16x32_bf16 v[8:11], v[136:139], v[168:171], v[8:11]
	v_mfma_f32_16x16x32_bf16 v[60:63], v[132:135], v[148:151], v[60:63]
	v_mfma_f32_16x16x32_bf16 v[56:59], v[140:143], v[148:151], v[56:59]
	v_mfma_f32_16x16x32_bf16 v[44:47], v[132:135], v[156:159], v[44:47]
	v_mfma_f32_16x16x32_bf16 v[40:43], v[140:143], v[156:159], v[40:43]
	v_mfma_f32_16x16x32_bf16 v[28:31], v[132:135], v[164:167], v[28:31]
	v_mfma_f32_16x16x32_bf16 v[24:27], v[140:143], v[164:167], v[24:27]
	v_mfma_f32_16x16x32_bf16 v[12:15], v[132:135], v[172:175], v[12:15]
	v_mfma_f32_16x16x32_bf16 v[8:11], v[140:143], v[172:175], v[8:11]
	s_setprio 0
	s_barrier
	s_add_u32 s18, s22, 0xb0080
	s_addc_u32 s19, s23, 0
	s_add_i32 s22, s24, s29
	s_mov_b32 m0, s22
	s_nop 0
	global_load_lds_dwordx4 v192, s[18:19]
	s_add_i32 m0, s22, 0x2000
	s_nop 0
	global_load_lds_dwordx4 v210, s[18:19]
	s_waitcnt vmcnt(6)
	s_barrier
	s_setprio 1
	v_mfma_f32_16x16x32_bf16 v[52:55], v[176:179], v[144:147], v[52:55]
	v_mfma_f32_16x16x32_bf16 v[48:51], v[184:187], v[144:147], v[48:51]
	v_mfma_f32_16x16x32_bf16 v[36:39], v[176:179], v[152:155], v[36:39]
	v_mfma_f32_16x16x32_bf16 v[32:35], v[184:187], v[152:155], v[32:35]
	v_mfma_f32_16x16x32_bf16 v[20:23], v[176:179], v[160:163], v[20:23]
	v_mfma_f32_16x16x32_bf16 v[16:19], v[184:187], v[160:163], v[16:19]
	v_mfma_f32_16x16x32_bf16 v[4:7], v[176:179], v[168:171], v[4:7]
	v_mfma_f32_16x16x32_bf16 v[0:3], v[184:187], v[168:171], v[0:3]
	v_mfma_f32_16x16x32_bf16 v[52:55], v[180:183], v[148:151], v[52:55]
	v_mfma_f32_16x16x32_bf16 v[48:51], v[188:191], v[148:151], v[48:51]
	v_mfma_f32_16x16x32_bf16 v[36:39], v[180:183], v[156:159], v[36:39]
	v_mfma_f32_16x16x32_bf16 v[32:35], v[188:191], v[156:159], v[32:35]
	v_mfma_f32_16x16x32_bf16 v[20:23], v[180:183], v[164:167], v[20:23]
	v_mfma_f32_16x16x32_bf16 v[16:19], v[188:191], v[164:167], v[16:19]
	v_mfma_f32_16x16x32_bf16 v[4:7], v[180:183], v[172:175], v[4:7]
	v_mfma_f32_16x16x32_bf16 v[0:3], v[188:191], v[172:175], v[0:3]
	s_setprio 0
	s_add_i32 s44, s44, 2
	s_add_u32 s33, s33, 0x100
	s_addc_u32 s43, s43, 0
	s_cmp_gt_u32 s44, 41
	s_mov_b64 s[18:19], s[20:21]
	s_barrier
	s_cbranch_scc0 .LBB0_3618
	v_mov_b32_e32 v128, v252
	s_lshl_b32 s19, s42, 8
	v_readfirstlane_b32 s18, v128
	s_ashr_i32 s20, s18, 2
	s_andn2_b32 s20, s20, 63
	s_lshr_b32 s18, s18, 1
	s_add_i32 s20, s20, s19
	s_and_b32 s18, s18, 0x60
	s_lshl_b32 s19, s41, 8
	v_and_or_b32 v218, v128, 15, s20
	v_lshrrev_b32_e32 v128, 1, v128
	s_or_b32 s18, s18, s19
	v_and_b32_e32 v129, 64, v195
	v_and_or_b32 v216, v128, 24, s18
	v_xor_b32_e32 v128, 16, v195
	v_add_u32_e32 v129, 64, v129
	v_cmp_lt_i32_e32 vcc, v128, v129
	v_ashrrev_i32_e32 v219, 31, v218
	v_ashrrev_i32_e32 v217, 31, v216
	v_cndmask_b32_e32 v128, v195, v128, vcc
	v_lshlrev_b32_e32 v200, 2, v128
	v_xor_b32_e32 v128, 32, v195
	v_cmp_lt_i32_e32 vcc, v128, v129
	v_or_b32_e32 v220, 0x80, v216
	v_ashrrev_i32_e32 v221, 31, v220
	v_cndmask_b32_e32 v128, v195, v128, vcc
	v_lshlrev_b32_e32 v199, 2, v128
	v_lshlrev_b64 v[128:129], 10, v[218:219]
	v_lshl_add_u64 v[130:131], v[128:129], 0, v[216:217]
	v_lshlrev_b64 v[130:131], 1, v[130:131]
	v_lshl_add_u64 v[246:247], s[10:11], 0, v[130:131]
	v_lshl_add_u64 v[250:251], s[12:13], 0, v[130:131]
	global_load_dwordx4 v[188:191], v[246:247], off
	global_load_dwordx4 v[180:183], v[246:247], off offset:256
	global_load_dwordx4 v[184:187], v[250:251], off
	v_or_b32_e32 v242, 16, v218
	v_lshl_add_u64 v[128:129], v[128:129], 0, v[220:221]
	v_ashrrev_i32_e32 v243, 31, v242
	v_lshl_add_u64 v[248:249], v[128:129], 1, s[12:13]
	v_lshlrev_b64 v[128:129], 10, v[242:243]
	v_or_b32_e32 v234, 32, v218
	v_lshl_add_u64 v[130:131], v[128:129], 0, v[216:217]
	v_lshl_add_u64 v[128:129], v[128:129], 0, v[220:221]
	v_ashrrev_i32_e32 v235, 31, v234
	v_lshlrev_b64 v[130:131], 1, v[130:131]
	v_lshl_add_u64 v[240:241], v[128:129], 1, s[12:13]
	v_lshlrev_b64 v[128:129], 10, v[234:235]
	v_or_b32_e32 v226, 48, v218
	v_lshl_add_u64 v[238:239], s[10:11], 0, v[130:131]
	v_lshl_add_u64 v[244:245], s[12:13], 0, v[130:131]
	v_lshl_add_u64 v[130:131], v[128:129], 0, v[216:217]
	v_lshl_add_u64 v[128:129], v[128:129], 0, v[220:221]
	v_ashrrev_i32_e32 v227, 31, v226
	v_lshlrev_b64 v[130:131], 1, v[130:131]
	v_lshl_add_u64 v[232:233], v[128:129], 1, s[12:13]
	v_lshlrev_b64 v[128:129], 10, v[226:227]
	v_lshl_add_u64 v[228:229], s[10:11], 0, v[130:131]
	v_lshl_add_u64 v[236:237], s[12:13], 0, v[130:131]
	v_lshl_add_u64 v[130:131], v[128:129], 0, v[216:217]
	v_lshlrev_b64 v[130:131], 1, v[130:131]
	v_lshl_add_u64 v[132:133], v[128:129], 0, v[220:221]
	v_lshl_add_u64 v[222:223], s[10:11], 0, v[130:131]
	v_lshl_add_u64 v[230:231], s[12:13], 0, v[130:131]
	v_lshl_add_u64 v[224:225], v[132:133], 1, s[12:13]
	global_load_dwordx4 v[176:179], v[248:249], off
	global_load_dwordx4 v[172:175], v[238:239], off
	global_load_dwordx4 v[164:167], v[238:239], off offset:256
	global_load_dwordx4 v[168:171], v[244:245], off
	global_load_dwordx4 v[160:163], v[240:241], off
	global_load_dwordx4 v[156:159], v[228:229], off
	global_load_dwordx4 v[132:135], v[224:225], off
	global_load_dwordx4 v[152:155], v[236:237], off
	global_load_dwordx4 v[144:147], v[232:233], off
	global_load_dwordx4 v[148:151], v[228:229], off offset:256
	global_load_dwordx4 v[136:139], v[230:231], off
	global_load_dwordx4 v[140:143], v[222:223], off
	global_load_dwordx4 v[128:131], v[222:223], off offset:256
	v_cmp_gt_u32_e32 vcc, 16, v195
	s_waitcnt vmcnt(0)
	v_lshlrev_b32_e32 v202, 16, v188
	v_and_b32_e32 v203, 0xffff0000, v188
	v_lshlrev_b32_e32 v204, 16, v184
	v_and_b32_e32 v205, 0xffff0000, v184
	v_lshlrev_b32_e32 v188, 16, v189
	v_and_b32_e32 v189, 0xffff0000, v189
	v_lshlrev_b32_e32 v184, 16, v185
	v_and_b32_e32 v185, 0xffff0000, v185
	v_pk_add_f32 v[202:203], v[202:203], v[204:205]
	v_pk_add_f32 v[184:185], v[188:189], v[184:185]
	v_pk_fma_f32 v[188:189], v[124:125], 0.5, v[202:203] op_sel_hi:[1,0,1]
	v_pk_fma_f32 v[184:185], v[126:127], 0.5, v[184:185] op_sel_hi:[1,0,1]
	v_lshlrev_b32_e32 v124, 16, v190
	v_and_b32_e32 v125, 0xffff0000, v190
	v_lshlrev_b32_e32 v126, 16, v186
	v_and_b32_e32 v127, 0xffff0000, v186
	v_pk_add_f32 v[124:125], v[124:125], v[126:127]
	v_lshlrev_b32_e32 v126, 16, v191
	v_and_b32_e32 v127, 0xffff0000, v191
	v_lshlrev_b32_e32 v186, 16, v187
	v_and_b32_e32 v187, 0xffff0000, v187
	v_pk_add_f32 v[126:127], v[126:127], v[186:187]
	v_pk_fma_f32 v[190:191], v[120:121], 0.5, v[124:125] op_sel_hi:[1,0,1]
	v_cvt_pk_bf16_f32 v120, v188, v189
	v_pk_fma_f32 v[186:187], v[122:123], 0.5, v[126:127] op_sel_hi:[1,0,1]
	v_and_b32_e32 v123, 0xffff0000, v120
	v_lshlrev_b32_e32 v122, 16, v120
	v_pk_add_f32 v[122:123], v[188:189], v[122:123] neg_lo:[0,1] neg_hi:[0,1]
	v_cvt_pk_bf16_f32 v121, v184, v185
	v_cvt_pk_bf16_f32 v124, v122, v123
	v_and_b32_e32 v123, 0xffff0000, v121
	v_lshlrev_b32_e32 v122, 16, v121
	v_pk_add_f32 v[122:123], v[184:185], v[122:123] neg_lo:[0,1] neg_hi:[0,1]
	s_nop 0
	v_cvt_pk_bf16_f32 v125, v122, v123
	v_cvt_pk_bf16_f32 v122, v190, v191
	v_cvt_pk_bf16_f32 v123, v186, v187
	v_and_b32_e32 v127, 0xffff0000, v122
	v_lshlrev_b32_e32 v126, 16, v122
	v_and_b32_e32 v203, 0xffff0000, v123
	v_lshlrev_b32_e32 v202, 16, v123
	v_pk_add_f32 v[126:127], v[190:191], v[126:127] neg_lo:[0,1] neg_hi:[0,1]
	v_pk_add_f32 v[202:203], v[186:187], v[202:203] neg_lo:[0,1] neg_hi:[0,1]
	v_cvt_pk_bf16_f32 v126, v126, v127
	v_cvt_pk_bf16_f32 v127, v202, v203
	global_store_dwordx4 v[246:247], v[120:123], off
	global_store_dwordx4 v[250:251], v[124:127], off
	s_nop 0
	v_pk_mul_f32 v[122:123], v[190:191], v[190:191]
	v_pk_mul_f32 v[120:121], v[186:187], v[186:187]
	v_pk_fma_f32 v[122:123], v[188:189], v[188:189], v[122:123]
	v_pk_fma_f32 v[120:121], v[184:185], v[184:185], v[120:121]
	v_add_f32_e32 v122, v122, v123
	v_add_f32_e32 v120, v120, v122
	v_add_f32_e32 v120, v121, v120
	ds_bpermute_b32 v121, v200, v120
	s_waitcnt lgkmcnt(0)
	v_add_f32_e32 v122, v120, v121
	ds_bpermute_b32 v123, v199, v122
	v_lshl_add_u64 v[120:121], v[218:219], 2, s[16:17]
	s_and_saveexec_b64 s[18:19], vcc
	s_cbranch_execz .LBB0_3621
	s_waitcnt lgkmcnt(0)
	v_add_f32_e32 v122, v122, v123
	global_atomic_add_f32 v[120:121], v122, off
